# K-loop hand-off: s_setprio 1 moved before the opening barrier, redundant post-barrier lgkmcnt(0) dropped, s_setprio 0 moved after the closing barrier (no SALU between barrier release and first MFMA)
# speedup vs baseline: 1.0040x; 1.0014x over previous
; #define PG8_STAGE(bufoff, gbase, voff) do { _Pragma("unroll") for (int _i = 0; _i < 2; ++_i) \
;         __builtin_amdgcn_global_load_lds((const unsigned*)((const char*)(gbase) + (voff)[_i]), (LAS unsigned*)(lds + (bufoff) + ldsw + _i * 8192), 16, 0, 0); } while (0)
; #define PG8_LDA(dst, b, h) do { _Pragma("unroll") for (int m = 0; m < 4; ++m) _Pragma("unroll") for (int k = 0; k < 2; ++k) dst[m][k] = *(const LAS bf16x8*)(lds + PG8_SA(b, h) + aoff + m * 2048 + k * 1024); } while (0)
; #define PG8_LDB(dst, b, h) do { _Pragma("unroll") for (int n = 0; n < 2; ++n) _Pragma("unroll") for (int k = 0; k < 2; ++k) dst[n][k] = *(const LAS bf16x8*)(lds + PG8_SB(b, h) + boff + n * 2048 + k * 1024); } while (0)
; #define PG8_MMA(ai, bj, At, Bt) do { __builtin_amdgcn_s_setprio(1); _Pragma("unroll") for (int m = 0; m < 4; ++m) _Pragma("unroll") for (int n = 0; n < 2; ++n) _Pragma("unroll") for (int k = 0; k < 2; ++k) \
;         acc[ai][bj][m][n] = __builtin_amdgcn_mfma_f32_16x16x32_bf16(Bt[n][k], At[m][k], acc[ai][bj][m][n], 0, 0, 0); __builtin_amdgcn_s_setprio(0); } while (0)
; #define PG8_WAIT_V(n) asm volatile("s_waitcnt vmcnt(" #n ")" ::: "memory")
; #define PG8_WAIT_L(n) asm volatile("s_waitcnt lgkmcnt(" #n ")" ::: "memory")
; #define PG8_BAR __builtin_amdgcn_s_barrier()
; #define PG8_SCHED __builtin_amdgcn_sched_barrier(0)
; template <class Epi>
; __device__ __forceinline__ void gemm_phase(LAS unsigned char* lds, const int tid, const Gemm g, const StaticOrder& S, const Epi& E) {
;     ...
;         for (int t = 0; t < nt; t += 2) {
;             const bool last = (t == nt - 2);
;             const char* a1 = cA + (size_t)(t + 1) * kstep;
;             const char* a2 = last ? nA : cA + (size_t)(t + 2) * kstep; const char* b2 = last ? nB : cB + (size_t)(t + 2) * kstep;
;             const char* a3 = a2 + kstep; const char* b3 = b2 + kstep;
;             PG8_LDB(B0, 0, 0); PG8_LDB(B1, 0, 1); PG8_SCHED; PG8_LDA(At, 0, 0); PG8_STAGE(PG8_SA(1, 1), a1 + hstepA, voffA);
;             PG8_WAIT_V(8); PG8_WAIT_L(0); PG8_BAR; PG8_MMA(0, 0, At, B0); PG8_MMA(0, 1, At, B1); PG8_BAR; PG8_SCHED;
;             PG8_LDA(At, 0, 1); PG8_STAGE(PG8_SB(0, 0), b2, voffB); PG8_STAGE(PG8_SB(0, 1), b2 + hstepB, voffB); PG8_STAGE(PG8_SA(0, 0), a2, voffA);
;             PG8_WAIT_V(8); PG8_WAIT_L(0); PG8_BAR; PG8_MMA(1, 0, At, B0); PG8_MMA(1, 1, At, B1); PG8_BAR; PG8_SCHED;
.LBB0_414:
	s_add_u32 s10, s68, 0xfffc0080
	s_addc_u32 s11, s69, -1
	s_add_i32 s17, 0, 0x10000
	s_cmp_eq_u32 s16, 12
	s_cselect_b32 s73, s7, s11
	s_cselect_b32 s72, s67, s10
	s_cselect_b32 s71, s5, s76
	s_cselect_b32 s70, vcc_lo, vcc_hi
	s_add_i32 s0, 0, 0x14000
	v_add_u32_e32 v70, s17, v202
	v_add_u32_e32 v160, s0, v202
	ds_read_b128 v[50:53], v70
	ds_read_b128 v[54:57], v70 offset:1024
	ds_read_b128 v[66:69], v70 offset:2048
	ds_read_b128 v[70:73], v70 offset:3072
	ds_read_b128 v[156:159], v160
	ds_read_b128 v[170:173], v160 offset:1024
	ds_read_b128 v[174:177], v160 offset:2048
	ds_read_b128 v[178:181], v160 offset:3072
	v_lshl_add_u64 v[160:161], s[68:69], 0, v[152:153]
	s_add_i32 m0, s83, 0xc000
	s_nop 0
	global_load_lds_dwordx4 v[160:161], off
	v_lshl_add_u64 v[160:161], s[68:69], 0, v[154:155]
	s_add_i32 m0, s83, 0xe000
	s_nop 0
	global_load_lds_dwordx4 v[160:161], off
	ds_read_b128 v[216:219], v215
	ds_read_b128 v[220:223], v215 offset:1024
	ds_read_b128 v[224:227], v215 offset:2048
	ds_read_b128 v[228:231], v215 offset:3072
	ds_read_b128 v[232:235], v215 offset:4096
	ds_read_b128 v[236:239], v215 offset:5120
	ds_read_b128 v[240:243], v215 offset:6144
	ds_read_b128 v[244:247], v215 offset:7168
	s_waitcnt vmcnt(8)
	s_waitcnt lgkmcnt(0)
	s_setprio 1
	s_barrier
	v_mfma_f32_16x16x32_bf16 v[142:145], v[50:53], v[216:219], v[142:145]
	v_mfma_f32_16x16x32_bf16 v[138:141], v[66:69], v[216:219], v[138:141]
	v_mfma_f32_16x16x32_bf16 v[126:129], v[50:53], v[224:227], v[126:129]
	v_mfma_f32_16x16x32_bf16 v[122:125], v[66:69], v[224:227], v[122:125]
	v_mfma_f32_16x16x32_bf16 v[110:113], v[50:53], v[232:235], v[110:113]
	v_mfma_f32_16x16x32_bf16 v[106:109], v[66:69], v[232:235], v[106:109]
	v_mfma_f32_16x16x32_bf16 v[94:97], v[50:53], v[240:243], v[94:97]
	v_mfma_f32_16x16x32_bf16 v[90:93], v[66:69], v[240:243], v[90:93]
	v_mfma_f32_16x16x32_bf16 v[142:145], v[54:57], v[220:223], v[142:145]
	v_mfma_f32_16x16x32_bf16 v[138:141], v[70:73], v[220:223], v[138:141]
	v_mfma_f32_16x16x32_bf16 v[126:129], v[54:57], v[228:231], v[126:129]
	v_mfma_f32_16x16x32_bf16 v[122:125], v[70:73], v[228:231], v[122:125]
	v_mfma_f32_16x16x32_bf16 v[110:113], v[54:57], v[236:239], v[110:113]
	v_mfma_f32_16x16x32_bf16 v[106:109], v[70:73], v[236:239], v[106:109]
	v_mfma_f32_16x16x32_bf16 v[94:97], v[54:57], v[244:247], v[94:97]
	v_mfma_f32_16x16x32_bf16 v[90:93], v[70:73], v[244:247], v[90:93]
	s_setprio 0
	s_setprio 1
	v_mfma_f32_16x16x32_bf16 v[134:137], v[156:159], v[216:219], v[134:137]
	v_mfma_f32_16x16x32_bf16 v[130:133], v[174:177], v[216:219], v[130:133]
	v_mfma_f32_16x16x32_bf16 v[118:121], v[156:159], v[224:227], v[118:121]
	v_mfma_f32_16x16x32_bf16 v[114:117], v[174:177], v[224:227], v[114:117]
	v_mfma_f32_16x16x32_bf16 v[102:105], v[156:159], v[232:235], v[102:105]
	v_mfma_f32_16x16x32_bf16 v[98:101], v[174:177], v[232:235], v[98:101]
	v_mfma_f32_16x16x32_bf16 v[86:89], v[156:159], v[240:243], v[86:89]
	v_mfma_f32_16x16x32_bf16 v[82:85], v[174:177], v[240:243], v[82:85]
	v_mfma_f32_16x16x32_bf16 v[134:137], v[170:173], v[220:223], v[134:137]
	v_mfma_f32_16x16x32_bf16 v[130:133], v[178:181], v[220:223], v[130:133]
	v_mfma_f32_16x16x32_bf16 v[118:121], v[170:173], v[228:231], v[118:121]
	v_mfma_f32_16x16x32_bf16 v[114:117], v[178:181], v[228:231], v[114:117]
	v_mfma_f32_16x16x32_bf16 v[102:105], v[170:173], v[236:239], v[102:105]
	v_mfma_f32_16x16x32_bf16 v[98:101], v[178:181], v[236:239], v[98:101]
	v_mfma_f32_16x16x32_bf16 v[86:89], v[170:173], v[244:247], v[86:89]
	v_mfma_f32_16x16x32_bf16 v[82:85], v[178:181], v[244:247], v[82:85]
	s_barrier
	s_setprio 0
	s_add_i32 s1, s17, s82
	v_lshl_add_u64 v[160:161], s[70:71], 0, v[0:1]
	s_mov_b32 m0, s1
	s_nop 0
	global_load_lds_dwordx4 v[160:161], off
	s_add_i32 m0, s1, 0x2000
	s_add_u32 s10, s70, 0x40000
	v_lshl_add_u64 v[182:183], s[70:71], 0, v[146:147]
	s_addc_u32 s11, s71, 0
	s_add_i32 s0, s0, s82
	global_load_lds_dwordx4 v[182:183], off
	v_lshl_add_u64 v[162:163], s[10:11], 0, v[0:1]
	s_mov_b32 m0, s0
	v_lshl_add_u64 v[164:165], s[72:73], 0, v[150:151]
	global_load_lds_dwordx4 v[162:163], off
	v_lshl_add_u64 v[162:163], s[10:11], 0, v[146:147]
	s_add_i32 m0, s0, 0x2000
	s_nop 0
	global_load_lds_dwordx4 v[162:163], off
	v_lshl_add_u64 v[162:163], s[72:73], 0, v[148:149]
	s_mov_b32 m0, s83
	s_nop 0
	global_load_lds_dwordx4 v[162:163], off
	s_mov_b32 m0, s88
	s_nop 0
	global_load_lds_dwordx4 v[164:165], off
	ds_read_b128 v[216:219], v215 offset:16384
	ds_read_b128 v[220:223], v215 offset:17408
	ds_read_b128 v[224:227], v215 offset:18432
	ds_read_b128 v[228:231], v215 offset:19456
	ds_read_b128 v[232:235], v215 offset:20480
	ds_read_b128 v[236:239], v215 offset:21504
	ds_read_b128 v[240:243], v215 offset:22528
	ds_read_b128 v[244:247], v215 offset:23552
	s_waitcnt vmcnt(8)
	s_waitcnt lgkmcnt(0)
	s_setprio 1
	s_barrier
; #define PG8_STAGE(bufoff, gbase, voff) do { _Pragma("unroll") for (int _i = 0; _i < 2; ++_i) \
;         __builtin_amdgcn_global_load_lds((const unsigned*)((const char*)(gbase) + (voff)[_i]), (LAS unsigned*)(lds + (bufoff) + ldsw + _i * 8192), 16, 0, 0); } while (0)
; #define PG8_LDA(dst, b, h) do { _Pragma("unroll") for (int m = 0; m < 4; ++m) _Pragma("unroll") for (int k = 0; k < 2; ++k) dst[m][k] = *(const LAS bf16x8*)(lds + PG8_SA(b, h) + aoff + m * 2048 + k * 1024); } while (0)
; #define PG8_LDB(dst, b, h) do { _Pragma("unroll") for (int n = 0; n < 2; ++n) _Pragma("unroll") for (int k = 0; k < 2; ++k) dst[n][k] = *(const LAS bf16x8*)(lds + PG8_SB(b, h) + boff + n * 2048 + k * 1024); } while (0)
; #define PG8_MMA(ai, bj, At, Bt) do { __builtin_amdgcn_s_setprio(1); _Pragma("unroll") for (int m = 0; m < 4; ++m) _Pragma("unroll") for (int n = 0; n < 2; ++n) _Pragma("unroll") for (int k = 0; k < 2; ++k) \
;         acc[ai][bj][m][n] = __builtin_amdgcn_mfma_f32_16x16x32_bf16(Bt[n][k], At[m][k], acc[ai][bj][m][n], 0, 0, 0); __builtin_amdgcn_s_setprio(0); } while (0)
; #define PG8_WAIT_V(n) asm volatile("s_waitcnt vmcnt(" #n ")" ::: "memory")
; #define PG8_WAIT_L(n) asm volatile("s_waitcnt lgkmcnt(" #n ")" ::: "memory")
; #define PG8_BAR __builtin_amdgcn_s_barrier()
; #define PG8_SCHED __builtin_amdgcn_sched_barrier(0)
; template <class Epi>
; __device__ __forceinline__ void gemm_phase(LAS unsigned char* lds, const int tid, const Gemm g, const StaticOrder& S, const Epi& E) {
;     ...
;             PG8_WAIT_V(8); PG8_WAIT_L(0); PG8_BAR; PG8_MMA(1, 0, At, B0); PG8_MMA(1, 1, At, B1); PG8_BAR; PG8_SCHED;
;             PG8_LDB(B0, 1, 0); PG8_LDB(B1, 1, 1); PG8_SCHED; PG8_LDA(At, 1, 0); PG8_STAGE(PG8_SA(0, 1), a2 + hstepA, voffA);
;             PG8_WAIT_V(8); PG8_WAIT_L(0); PG8_BAR; PG8_MMA(0, 0, At, B0); PG8_MMA(0, 1, At, B1); PG8_BAR; PG8_SCHED;
	v_mfma_f32_16x16x32_bf16 v[78:81], v[50:53], v[216:219], v[78:81]
	v_mfma_f32_16x16x32_bf16 v[74:77], v[66:69], v[216:219], v[74:77]
	v_mfma_f32_16x16x32_bf16 v[46:49], v[50:53], v[224:227], v[46:49]
	v_mfma_f32_16x16x32_bf16 v[42:45], v[66:69], v[224:227], v[42:45]
	v_mfma_f32_16x16x32_bf16 v[30:33], v[50:53], v[232:235], v[30:33]
	v_mfma_f32_16x16x32_bf16 v[26:29], v[66:69], v[232:235], v[26:29]
	v_mfma_f32_16x16x32_bf16 v[14:17], v[50:53], v[240:243], v[14:17]
	v_mfma_f32_16x16x32_bf16 v[10:13], v[66:69], v[240:243], v[10:13]
	v_mfma_f32_16x16x32_bf16 v[78:81], v[54:57], v[220:223], v[78:81]
	v_mfma_f32_16x16x32_bf16 v[74:77], v[70:73], v[220:223], v[74:77]
	v_mfma_f32_16x16x32_bf16 v[46:49], v[54:57], v[228:231], v[46:49]
	v_mfma_f32_16x16x32_bf16 v[42:45], v[70:73], v[228:231], v[42:45]
	v_mfma_f32_16x16x32_bf16 v[30:33], v[54:57], v[236:239], v[30:33]
	v_mfma_f32_16x16x32_bf16 v[26:29], v[70:73], v[236:239], v[26:29]
	v_mfma_f32_16x16x32_bf16 v[14:17], v[54:57], v[244:247], v[14:17]
	v_mfma_f32_16x16x32_bf16 v[10:13], v[70:73], v[244:247], v[10:13]
	s_setprio 0
	s_setprio 1
	v_mfma_f32_16x16x32_bf16 v[38:41], v[156:159], v[224:227], v[38:41]
	v_mfma_f32_16x16x32_bf16 v[34:37], v[174:177], v[224:227], v[34:37]
	v_mfma_f32_16x16x32_bf16 v[22:25], v[156:159], v[232:235], v[22:25]
	v_mfma_f32_16x16x32_bf16 v[18:21], v[174:177], v[232:235], v[18:21]
	v_mfma_f32_16x16x32_bf16 v[6:9], v[156:159], v[240:243], v[6:9]
	v_mfma_f32_16x16x32_bf16 v[2:5], v[174:177], v[240:243], v[2:5]
	v_mfma_f32_16x16x32_bf16 v[50:53], v[156:159], v[216:219], v[62:65]
	v_mfma_f32_16x16x32_bf16 v[54:57], v[174:177], v[216:219], v[58:61]
	v_mfma_f32_16x16x32_bf16 v[38:41], v[170:173], v[228:231], v[38:41]
	v_mfma_f32_16x16x32_bf16 v[34:37], v[178:181], v[228:231], v[34:37]
	v_mfma_f32_16x16x32_bf16 v[22:25], v[170:173], v[236:239], v[22:25]
	v_mfma_f32_16x16x32_bf16 v[18:21], v[178:181], v[236:239], v[18:21]
	v_mfma_f32_16x16x32_bf16 v[6:9], v[170:173], v[244:247], v[6:9]
	v_mfma_f32_16x16x32_bf16 v[2:5], v[178:181], v[244:247], v[2:5]
	v_mfma_f32_16x16x32_bf16 v[50:53], v[170:173], v[220:223], v[50:53]
	v_mfma_f32_16x16x32_bf16 v[54:57], v[178:181], v[220:223], v[54:57]
	s_barrier
	s_setprio 0
	s_add_i32 s0, 0, 0x18000
	s_add_i32 s1, 0, 0x1c000
	v_add_u32_e32 v70, s0, v202
	v_add_u32_e32 v178, s1, v202
	ds_read_b128 v[58:61], v70
	ds_read_b128 v[62:65], v70 offset:1024
	ds_read_b128 v[66:69], v70 offset:2048
	ds_read_b128 v[70:73], v70 offset:3072
	ds_read_b128 v[156:159], v178
	ds_read_b128 v[170:173], v178 offset:1024
	ds_read_b128 v[174:177], v178 offset:2048
	ds_read_b128 v[178:181], v178 offset:3072
	s_add_u32 s10, s72, 0x40000
	s_addc_u32 s11, s73, 0
	s_mov_b32 m0, s89
	v_lshl_add_u64 v[206:207], s[10:11], 0, v[148:149]
	global_load_lds_dwordx4 v[206:207], off
	v_lshl_add_u64 v[206:207], s[10:11], 0, v[150:151]
	s_mov_b32 m0, s92
	s_nop 0
	global_load_lds_dwordx4 v[206:207], off
	ds_read_b128 v[216:219], v215 offset:32768
	ds_read_b128 v[220:223], v215 offset:33792
	ds_read_b128 v[224:227], v215 offset:34816
	ds_read_b128 v[228:231], v215 offset:35840
	ds_read_b128 v[232:235], v215 offset:36864
	ds_read_b128 v[236:239], v215 offset:37888
	ds_read_b128 v[240:243], v215 offset:38912
	ds_read_b128 v[244:247], v215 offset:39936
	s_waitcnt vmcnt(8)
	s_waitcnt lgkmcnt(0)
	s_setprio 1
	s_barrier
	v_mfma_f32_16x16x32_bf16 v[142:145], v[58:61], v[216:219], v[142:145]
	v_mfma_f32_16x16x32_bf16 v[138:141], v[66:69], v[216:219], v[138:141]
	v_mfma_f32_16x16x32_bf16 v[126:129], v[58:61], v[224:227], v[126:129]
	v_mfma_f32_16x16x32_bf16 v[122:125], v[66:69], v[224:227], v[122:125]
	v_mfma_f32_16x16x32_bf16 v[110:113], v[58:61], v[232:235], v[110:113]
	v_mfma_f32_16x16x32_bf16 v[106:109], v[66:69], v[232:235], v[106:109]
	v_mfma_f32_16x16x32_bf16 v[94:97], v[58:61], v[240:243], v[94:97]
	v_mfma_f32_16x16x32_bf16 v[90:93], v[66:69], v[240:243], v[90:93]
	v_mfma_f32_16x16x32_bf16 v[142:145], v[62:65], v[220:223], v[142:145]
	v_mfma_f32_16x16x32_bf16 v[138:141], v[70:73], v[220:223], v[138:141]
	v_mfma_f32_16x16x32_bf16 v[126:129], v[62:65], v[228:231], v[126:129]
	v_mfma_f32_16x16x32_bf16 v[122:125], v[70:73], v[228:231], v[122:125]
	v_mfma_f32_16x16x32_bf16 v[110:113], v[62:65], v[236:239], v[110:113]
	v_mfma_f32_16x16x32_bf16 v[106:109], v[70:73], v[236:239], v[106:109]
	v_mfma_f32_16x16x32_bf16 v[94:97], v[62:65], v[244:247], v[94:97]
	v_mfma_f32_16x16x32_bf16 v[90:93], v[70:73], v[244:247], v[90:93]
	s_setprio 0
	s_setprio 1
	v_mfma_f32_16x16x32_bf16 v[134:137], v[156:159], v[216:219], v[134:137]
	v_mfma_f32_16x16x32_bf16 v[130:133], v[174:177], v[216:219], v[130:133]
	v_mfma_f32_16x16x32_bf16 v[118:121], v[156:159], v[224:227], v[118:121]
	v_mfma_f32_16x16x32_bf16 v[114:117], v[174:177], v[224:227], v[114:117]
	v_mfma_f32_16x16x32_bf16 v[102:105], v[156:159], v[232:235], v[102:105]
	v_mfma_f32_16x16x32_bf16 v[98:101], v[174:177], v[232:235], v[98:101]
	v_mfma_f32_16x16x32_bf16 v[86:89], v[156:159], v[240:243], v[86:89]
	v_mfma_f32_16x16x32_bf16 v[82:85], v[174:177], v[240:243], v[82:85]
	v_mfma_f32_16x16x32_bf16 v[134:137], v[170:173], v[220:223], v[134:137]
	v_mfma_f32_16x16x32_bf16 v[130:133], v[178:181], v[220:223], v[130:133]
	v_mfma_f32_16x16x32_bf16 v[118:121], v[170:173], v[228:231], v[118:121]
	v_mfma_f32_16x16x32_bf16 v[114:117], v[178:181], v[228:231], v[114:117]
	v_mfma_f32_16x16x32_bf16 v[102:105], v[170:173], v[236:239], v[102:105]
	v_mfma_f32_16x16x32_bf16 v[98:101], v[178:181], v[236:239], v[98:101]
	v_mfma_f32_16x16x32_bf16 v[86:89], v[170:173], v[244:247], v[86:89]
	v_mfma_f32_16x16x32_bf16 v[82:85], v[178:181], v[244:247], v[82:85]
	s_barrier
; #define PG8_STAGE(bufoff, gbase, voff) do { _Pragma("unroll") for (int _i = 0; _i < 2; ++_i) \
;         __builtin_amdgcn_global_load_lds((const unsigned*)((const char*)(gbase) + (voff)[_i]), (LAS unsigned*)(lds + (bufoff) + ldsw + _i * 8192), 16, 0, 0); } while (0)
; #define PG8_LDA(dst, b, h) do { _Pragma("unroll") for (int m = 0; m < 4; ++m) _Pragma("unroll") for (int k = 0; k < 2; ++k) dst[m][k] = *(const LAS bf16x8*)(lds + PG8_SA(b, h) + aoff + m * 2048 + k * 1024); } while (0)
; #define PG8_MMA(ai, bj, At, Bt) do { __builtin_amdgcn_s_setprio(1); _Pragma("unroll") for (int m = 0; m < 4; ++m) _Pragma("unroll") for (int n = 0; n < 2; ++n) _Pragma("unroll") for (int k = 0; k < 2; ++k) \
;         acc[ai][bj][m][n] = __builtin_amdgcn_mfma_f32_16x16x32_bf16(Bt[n][k], At[m][k], acc[ai][bj][m][n], 0, 0, 0); __builtin_amdgcn_s_setprio(0); } while (0)
; #define PG8_WAIT_V(n) asm volatile("s_waitcnt vmcnt(" #n ")" ::: "memory")
; #define PG8_WAIT_L(n) asm volatile("s_waitcnt lgkmcnt(" #n ")" ::: "memory")
; #define PG8_BAR __builtin_amdgcn_s_barrier()
; #define PG8_SCHED __builtin_amdgcn_sched_barrier(0)
; template <class Epi>
; __device__ __forceinline__ void gemm_phase(LAS unsigned char* lds, const int tid, const Gemm g, const StaticOrder& S, const Epi& E) {
;     ...
;             PG8_WAIT_V(8); PG8_WAIT_L(0); PG8_BAR; PG8_MMA(0, 0, At, B0); PG8_MMA(0, 1, At, B1); PG8_BAR; PG8_SCHED;
;             PG8_LDA(At, 1, 1); PG8_STAGE(PG8_SB(1, 0), b3, voffB); PG8_STAGE(PG8_SB(1, 1), b3 + hstepB, voffB); PG8_STAGE(PG8_SA(1, 0), a3, voffA);
;             PG8_WAIT_V(8); PG8_WAIT_L(0); PG8_BAR; PG8_MMA(1, 0, At, B0); PG8_MMA(1, 1, At, B1); PG8_BAR; PG8_SCHED;
;         }
;         if (wr == 0) PG8_BAR;
	s_setprio 0
	s_add_i32 s0, s0, s82
	v_lshl_add_u64 v[160:161], v[160:161], 0, s[36:37]
	s_mov_b32 m0, s0
	s_nop 0
	global_load_lds_dwordx4 v[160:161], off
	s_add_i32 m0, s0, 0x2000
	s_add_u32 s10, s70, 0x40080
	v_lshl_add_u64 v[160:161], v[182:183], 0, s[36:37]
	s_addc_u32 s11, s71, 0
	s_add_i32 s0, s1, s82
	global_load_lds_dwordx4 v[160:161], off
	v_lshl_add_u64 v[160:161], s[10:11], 0, v[0:1]
	s_mov_b32 m0, s0
	s_nop 0
	global_load_lds_dwordx4 v[160:161], off
	v_lshl_add_u64 v[160:161], s[10:11], 0, v[146:147]
	s_add_i32 m0, s0, 0x2000
	s_nop 0
	global_load_lds_dwordx4 v[160:161], off
	v_lshl_add_u64 v[160:161], v[162:163], 0, s[36:37]
	s_mov_b32 m0, s93
	s_nop 0
	global_load_lds_dwordx4 v[160:161], off
	v_lshl_add_u64 v[160:161], v[164:165], 0, s[36:37]
	s_mov_b32 m0, s74
	s_nop 0
	global_load_lds_dwordx4 v[160:161], off
	ds_read_b128 v[216:219], v215 offset:49152
	ds_read_b128 v[220:223], v215 offset:50176
	ds_read_b128 v[224:227], v215 offset:51200
	ds_read_b128 v[228:231], v215 offset:52224
	ds_read_b128 v[232:235], v215 offset:53248
	ds_read_b128 v[236:239], v215 offset:54272
	ds_read_b128 v[240:243], v215 offset:55296
	ds_read_b128 v[244:247], v215 offset:56320
	s_waitcnt vmcnt(8)
	s_waitcnt lgkmcnt(0)
	s_setprio 1
	s_barrier
	v_mfma_f32_16x16x32_bf16 v[78:81], v[58:61], v[216:219], v[78:81]
	v_mfma_f32_16x16x32_bf16 v[74:77], v[66:69], v[216:219], v[74:77]
	v_mfma_f32_16x16x32_bf16 v[46:49], v[58:61], v[224:227], v[46:49]
	v_mfma_f32_16x16x32_bf16 v[42:45], v[66:69], v[224:227], v[42:45]
	v_mfma_f32_16x16x32_bf16 v[30:33], v[58:61], v[232:235], v[30:33]
	v_mfma_f32_16x16x32_bf16 v[26:29], v[66:69], v[232:235], v[26:29]
	v_mfma_f32_16x16x32_bf16 v[14:17], v[58:61], v[240:243], v[14:17]
	v_mfma_f32_16x16x32_bf16 v[10:13], v[66:69], v[240:243], v[10:13]
	v_mfma_f32_16x16x32_bf16 v[78:81], v[62:65], v[220:223], v[78:81]
	v_mfma_f32_16x16x32_bf16 v[74:77], v[70:73], v[220:223], v[74:77]
	v_mfma_f32_16x16x32_bf16 v[46:49], v[62:65], v[228:231], v[46:49]
	v_mfma_f32_16x16x32_bf16 v[42:45], v[70:73], v[228:231], v[42:45]
	v_mfma_f32_16x16x32_bf16 v[30:33], v[62:65], v[236:239], v[30:33]
	v_mfma_f32_16x16x32_bf16 v[26:29], v[70:73], v[236:239], v[26:29]
	v_mfma_f32_16x16x32_bf16 v[14:17], v[62:65], v[244:247], v[14:17]
	v_mfma_f32_16x16x32_bf16 v[10:13], v[70:73], v[244:247], v[10:13]
	s_setprio 0
	s_setprio 1
	v_mfma_f32_16x16x32_bf16 v[50:53], v[156:159], v[216:219], v[50:53]
	v_mfma_f32_16x16x32_bf16 v[62:65], v[170:173], v[220:223], v[50:53]
	v_mfma_f32_16x16x32_bf16 v[50:53], v[174:177], v[216:219], v[54:57]
	v_mfma_f32_16x16x32_bf16 v[38:41], v[156:159], v[224:227], v[38:41]
	v_mfma_f32_16x16x32_bf16 v[34:37], v[174:177], v[224:227], v[34:37]
	v_mfma_f32_16x16x32_bf16 v[22:25], v[156:159], v[232:235], v[22:25]
	v_mfma_f32_16x16x32_bf16 v[18:21], v[174:177], v[232:235], v[18:21]
	v_mfma_f32_16x16x32_bf16 v[6:9], v[156:159], v[240:243], v[6:9]
	v_mfma_f32_16x16x32_bf16 v[2:5], v[174:177], v[240:243], v[2:5]
	v_mfma_f32_16x16x32_bf16 v[58:61], v[178:181], v[220:223], v[50:53]
	v_mfma_f32_16x16x32_bf16 v[38:41], v[170:173], v[228:231], v[38:41]
	v_mfma_f32_16x16x32_bf16 v[34:37], v[178:181], v[228:231], v[34:37]
	v_mfma_f32_16x16x32_bf16 v[22:25], v[170:173], v[236:239], v[22:25]
	v_mfma_f32_16x16x32_bf16 v[18:21], v[178:181], v[236:239], v[18:21]
	v_mfma_f32_16x16x32_bf16 v[6:9], v[170:173], v[244:247], v[6:9]
	v_mfma_f32_16x16x32_bf16 v[2:5], v[178:181], v[244:247], v[2:5]
	s_barrier
	s_setprio 0
	s_add_i32 s16, s16, 2
	s_add_u32 s68, s68, 0x100
	s_addc_u32 s69, s69, 0
	s_add_u32 vcc_hi, vcc_hi, 0x100
	s_addc_u32 s76, s76, 0
	s_cmp_gt_u32 s16, 13
	s_cbranch_scc0 .LBB0_414
	s_and_b64 vcc, exec, s[2:3]
	s_cbranch_vccz .LBB0_417
	s_barrier

; #define PG8_STAGE(bufoff, gbase, voff) do { _Pragma("unroll") for (int _i = 0; _i < 2; ++_i) \
;         __builtin_amdgcn_global_load_lds((const unsigned*)((const char*)(gbase) + (voff)[_i]), (LAS unsigned*)(lds + (bufoff) + ldsw + _i * 8192), 16, 0, 0); } while (0)
; #define PG8_LDA(dst, b, h) do { _Pragma("unroll") for (int m = 0; m < 4; ++m) _Pragma("unroll") for (int k = 0; k < 2; ++k) dst[m][k] = *(const LAS bf16x8*)(lds + PG8_SA(b, h) + aoff + m * 2048 + k * 1024); } while (0)
; #define PG8_LDB(dst, b, h) do { _Pragma("unroll") for (int n = 0; n < 2; ++n) _Pragma("unroll") for (int k = 0; k < 2; ++k) dst[n][k] = *(const LAS bf16x8*)(lds + PG8_SB(b, h) + boff + n * 2048 + k * 1024); } while (0)
; #define PG8_MMA(ai, bj, At, Bt) do { __builtin_amdgcn_s_setprio(1); _Pragma("unroll") for (int m = 0; m < 4; ++m) _Pragma("unroll") for (int n = 0; n < 2; ++n) _Pragma("unroll") for (int k = 0; k < 2; ++k) \
;         acc[ai][bj][m][n] = __builtin_amdgcn_mfma_f32_16x16x32_bf16(Bt[n][k], At[m][k], acc[ai][bj][m][n], 0, 0, 0); __builtin_amdgcn_s_setprio(0); } while (0)
; #define PG8_WAIT_V(n) asm volatile("s_waitcnt vmcnt(" #n ")" ::: "memory")
; #define PG8_WAIT_L(n) asm volatile("s_waitcnt lgkmcnt(" #n ")" ::: "memory")
; #define PG8_BAR __builtin_amdgcn_s_barrier()
; #define PG8_SCHED __builtin_amdgcn_sched_barrier(0)
; template <class Epi>
; __device__ __forceinline__ void gemm_phase(LAS unsigned char* lds, const int tid, const Gemm g, const StaticOrder& S, const Epi& E) {
;     ...
;         for (int t = 0; t < nt; t += 2) {
;             const bool last = (t == nt - 2);
;             const char* a1 = cA + (size_t)(t + 1) * kstep;
;             const char* a2 = last ? nA : cA + (size_t)(t + 2) * kstep; const char* b2 = last ? nB : cB + (size_t)(t + 2) * kstep;
;             const char* a3 = a2 + kstep; const char* b3 = b2 + kstep;
;             PG8_LDB(B0, 0, 0); PG8_LDB(B1, 0, 1); PG8_SCHED; PG8_LDA(At, 0, 0); PG8_STAGE(PG8_SA(1, 1), a1 + hstepA, voffA);
;             PG8_WAIT_V(8); PG8_WAIT_L(0); PG8_BAR; PG8_MMA(0, 0, At, B0); PG8_MMA(0, 1, At, B1); PG8_BAR; PG8_SCHED;
;             PG8_LDA(At, 0, 1); PG8_STAGE(PG8_SB(0, 0), b2, voffB); PG8_STAGE(PG8_SB(0, 1), b2 + hstepB, voffB); PG8_STAGE(PG8_SA(0, 0), a2, voffA);
;             PG8_WAIT_V(8); PG8_WAIT_L(0); PG8_BAR; PG8_MMA(1, 0, At, B0); PG8_MMA(1, 1, At, B1); PG8_BAR; PG8_SCHED;
.LBB0_945:
	s_add_u32 s30, s72, 0xfffc0080
	s_addc_u32 s31, s73, -1
	s_add_i32 s76, 0, 0x10000
	s_cmp_eq_u32 vcc_hi, 12
	s_cselect_b32 s75, s9, s31
	s_cselect_b32 s74, s27, s30
	v_add_u32_e32 v0, s76, v178
	s_cselect_b32 s31, s7, vcc_lo
	s_cselect_b32 s30, s28, s65
	s_add_i32 s0, 0, 0x14000
	ds_read_b128 v[18:21], v0
	ds_read_b128 v[22:25], v0 offset:1024
	ds_read_b128 v[26:29], v0 offset:2048
	ds_read_b128 v[30:33], v0 offset:3072
	v_add_u32_e32 v0, s0, v178
	ds_read_b128 v[170:173], v0
	ds_read_b128 v[174:177], v0 offset:1024
	ds_read_b128 v[190:193], v0 offset:2048
	ds_read_b128 v[194:197], v0 offset:3072
	v_lshl_add_u64 v[162:163], s[72:73], 0, v[158:159]
	s_add_i32 m0, s71, 0xc000
	s_nop 0
	global_load_lds_dwordx4 v[162:163], off
	v_lshl_add_u64 v[162:163], s[72:73], 0, v[160:161]
	s_add_i32 m0, s71, 0xe000
	s_nop 0
	global_load_lds_dwordx4 v[162:163], off
	ds_read_b128 v[198:201], v189
	ds_read_b128 v[210:213], v189 offset:1024
	ds_read_b128 v[214:217], v189 offset:2048
	ds_read_b128 v[218:221], v189 offset:3072
	ds_read_b128 v[222:225], v189 offset:4096
	ds_read_b128 v[226:229], v189 offset:5120
	ds_read_b128 v[230:233], v189 offset:6144
	ds_read_b128 v[234:237], v189 offset:7168
	s_waitcnt vmcnt(8)
	s_waitcnt lgkmcnt(0)
	s_setprio 1
	s_barrier
	v_mfma_f32_16x16x32_bf16 v[142:145], v[18:21], v[198:201], v[142:145]
	v_mfma_f32_16x16x32_bf16 v[138:141], v[26:29], v[198:201], v[138:141]
	v_mfma_f32_16x16x32_bf16 v[126:129], v[18:21], v[214:217], v[126:129]
	v_mfma_f32_16x16x32_bf16 v[122:125], v[26:29], v[214:217], v[122:125]
	v_mfma_f32_16x16x32_bf16 v[110:113], v[18:21], v[222:225], v[110:113]
	v_mfma_f32_16x16x32_bf16 v[106:109], v[26:29], v[222:225], v[106:109]
	v_mfma_f32_16x16x32_bf16 v[94:97], v[18:21], v[230:233], v[94:97]
	v_mfma_f32_16x16x32_bf16 v[90:93], v[26:29], v[230:233], v[90:93]
	v_mfma_f32_16x16x32_bf16 v[142:145], v[22:25], v[210:213], v[142:145]
	v_mfma_f32_16x16x32_bf16 v[138:141], v[30:33], v[210:213], v[138:141]
	v_mfma_f32_16x16x32_bf16 v[126:129], v[22:25], v[218:221], v[126:129]
	v_mfma_f32_16x16x32_bf16 v[122:125], v[30:33], v[218:221], v[122:125]
	v_mfma_f32_16x16x32_bf16 v[110:113], v[22:25], v[226:229], v[110:113]
	v_mfma_f32_16x16x32_bf16 v[106:109], v[30:33], v[226:229], v[106:109]
	v_mfma_f32_16x16x32_bf16 v[94:97], v[22:25], v[234:237], v[94:97]
	v_mfma_f32_16x16x32_bf16 v[90:93], v[30:33], v[234:237], v[90:93]
	s_setprio 0
	s_setprio 1
	v_mfma_f32_16x16x32_bf16 v[134:137], v[170:173], v[198:201], v[134:137]
	v_mfma_f32_16x16x32_bf16 v[130:133], v[190:193], v[198:201], v[130:133]
	v_mfma_f32_16x16x32_bf16 v[118:121], v[170:173], v[214:217], v[118:121]
	v_mfma_f32_16x16x32_bf16 v[114:117], v[190:193], v[214:217], v[114:117]
	v_mfma_f32_16x16x32_bf16 v[102:105], v[170:173], v[222:225], v[102:105]
	v_mfma_f32_16x16x32_bf16 v[98:101], v[190:193], v[222:225], v[98:101]
	v_mfma_f32_16x16x32_bf16 v[86:89], v[170:173], v[230:233], v[86:89]
	v_mfma_f32_16x16x32_bf16 v[82:85], v[190:193], v[230:233], v[82:85]
	v_mfma_f32_16x16x32_bf16 v[134:137], v[174:177], v[210:213], v[134:137]
	v_mfma_f32_16x16x32_bf16 v[130:133], v[194:197], v[210:213], v[130:133]
	v_mfma_f32_16x16x32_bf16 v[118:121], v[174:177], v[218:221], v[118:121]
	v_mfma_f32_16x16x32_bf16 v[114:117], v[194:197], v[218:221], v[114:117]
	v_mfma_f32_16x16x32_bf16 v[102:105], v[174:177], v[226:229], v[102:105]
	v_mfma_f32_16x16x32_bf16 v[98:101], v[194:197], v[226:229], v[98:101]
	v_mfma_f32_16x16x32_bf16 v[86:89], v[174:177], v[234:237], v[86:89]
	v_mfma_f32_16x16x32_bf16 v[82:85], v[194:197], v[234:237], v[82:85]
	s_barrier
	s_setprio 0
	s_add_i32 s1, s76, s93
	v_lshl_add_u64 v[162:163], s[30:31], 0, v[150:151]
	s_mov_b32 m0, s1
	s_nop 0
	global_load_lds_dwordx4 v[162:163], off
	s_add_i32 m0, s1, 0x2000
	s_add_u32 s76, s30, 0x40000
	v_lshl_add_u64 v[164:165], s[30:31], 0, v[154:155]
	s_addc_u32 s77, s31, 0
	s_add_i32 s0, s0, s93
	global_load_lds_dwordx4 v[164:165], off
	v_lshl_add_u64 v[202:203], s[76:77], 0, v[150:151]
	s_mov_b32 m0, s0
	v_lshl_add_u64 v[206:207], s[74:75], 0, v[152:153]
	global_load_lds_dwordx4 v[202:203], off
	v_lshl_add_u64 v[202:203], s[76:77], 0, v[154:155]
	s_add_i32 m0, s0, 0x2000
	s_nop 0
	global_load_lds_dwordx4 v[202:203], off
	v_lshl_add_u64 v[202:203], s[74:75], 0, v[148:149]
	s_mov_b32 m0, s71
	s_nop 0
	global_load_lds_dwordx4 v[202:203], off
	s_mov_b32 m0, s88
	s_nop 0
	global_load_lds_dwordx4 v[206:207], off
	ds_read_b128 v[198:201], v189 offset:16384
	ds_read_b128 v[210:213], v189 offset:17408
	ds_read_b128 v[214:217], v189 offset:18432
	ds_read_b128 v[218:221], v189 offset:19456
	ds_read_b128 v[222:225], v189 offset:20480
	ds_read_b128 v[226:229], v189 offset:21504
	ds_read_b128 v[230:233], v189 offset:22528
	ds_read_b128 v[234:237], v189 offset:23552
	s_waitcnt vmcnt(8)
	s_waitcnt lgkmcnt(0)
	s_setprio 1
	s_barrier
; #define PG8_STAGE(bufoff, gbase, voff) do { _Pragma("unroll") for (int _i = 0; _i < 2; ++_i) \
;         __builtin_amdgcn_global_load_lds((const unsigned*)((const char*)(gbase) + (voff)[_i]), (LAS unsigned*)(lds + (bufoff) + ldsw + _i * 8192), 16, 0, 0); } while (0)
; #define PG8_LDA(dst, b, h) do { _Pragma("unroll") for (int m = 0; m < 4; ++m) _Pragma("unroll") for (int k = 0; k < 2; ++k) dst[m][k] = *(const LAS bf16x8*)(lds + PG8_SA(b, h) + aoff + m * 2048 + k * 1024); } while (0)
; #define PG8_LDB(dst, b, h) do { _Pragma("unroll") for (int n = 0; n < 2; ++n) _Pragma("unroll") for (int k = 0; k < 2; ++k) dst[n][k] = *(const LAS bf16x8*)(lds + PG8_SB(b, h) + boff + n * 2048 + k * 1024); } while (0)
; #define PG8_MMA(ai, bj, At, Bt) do { __builtin_amdgcn_s_setprio(1); _Pragma("unroll") for (int m = 0; m < 4; ++m) _Pragma("unroll") for (int n = 0; n < 2; ++n) _Pragma("unroll") for (int k = 0; k < 2; ++k) \
;         acc[ai][bj][m][n] = __builtin_amdgcn_mfma_f32_16x16x32_bf16(Bt[n][k], At[m][k], acc[ai][bj][m][n], 0, 0, 0); __builtin_amdgcn_s_setprio(0); } while (0)
; #define PG8_WAIT_V(n) asm volatile("s_waitcnt vmcnt(" #n ")" ::: "memory")
; #define PG8_WAIT_L(n) asm volatile("s_waitcnt lgkmcnt(" #n ")" ::: "memory")
; #define PG8_BAR __builtin_amdgcn_s_barrier()
; #define PG8_SCHED __builtin_amdgcn_sched_barrier(0)
; template <class Epi>
; __device__ __forceinline__ void gemm_phase(LAS unsigned char* lds, const int tid, const Gemm g, const StaticOrder& S, const Epi& E) {
;     ...
;             PG8_WAIT_V(8); PG8_WAIT_L(0); PG8_BAR; PG8_MMA(1, 0, At, B0); PG8_MMA(1, 1, At, B1); PG8_BAR; PG8_SCHED;
;             PG8_LDB(B0, 1, 0); PG8_LDB(B1, 1, 1); PG8_SCHED; PG8_LDA(At, 1, 0); PG8_STAGE(PG8_SA(0, 1), a2 + hstepA, voffA);
;             PG8_WAIT_V(8); PG8_WAIT_L(0); PG8_BAR; PG8_MMA(0, 0, At, B0); PG8_MMA(0, 1, At, B1); PG8_BAR; PG8_SCHED;
	v_mfma_f32_16x16x32_bf16 v[78:81], v[18:21], v[198:201], v[78:81]
	v_mfma_f32_16x16x32_bf16 v[74:77], v[26:29], v[198:201], v[74:77]
	v_mfma_f32_16x16x32_bf16 v[62:65], v[18:21], v[214:217], v[62:65]
	v_mfma_f32_16x16x32_bf16 v[58:61], v[26:29], v[214:217], v[58:61]
	v_mfma_f32_16x16x32_bf16 v[46:49], v[18:21], v[222:225], v[46:49]
	v_mfma_f32_16x16x32_bf16 v[42:45], v[26:29], v[222:225], v[42:45]
	v_mfma_f32_16x16x32_bf16 v[14:17], v[18:21], v[230:233], v[14:17]
	v_mfma_f32_16x16x32_bf16 v[10:13], v[26:29], v[230:233], v[10:13]
	v_mfma_f32_16x16x32_bf16 v[78:81], v[22:25], v[210:213], v[78:81]
	v_mfma_f32_16x16x32_bf16 v[74:77], v[30:33], v[210:213], v[74:77]
	v_mfma_f32_16x16x32_bf16 v[62:65], v[22:25], v[218:221], v[62:65]
	v_mfma_f32_16x16x32_bf16 v[58:61], v[30:33], v[218:221], v[58:61]
	v_mfma_f32_16x16x32_bf16 v[46:49], v[22:25], v[226:229], v[46:49]
	v_mfma_f32_16x16x32_bf16 v[42:45], v[30:33], v[226:229], v[42:45]
	v_mfma_f32_16x16x32_bf16 v[14:17], v[22:25], v[234:237], v[14:17]
	v_mfma_f32_16x16x32_bf16 v[10:13], v[30:33], v[234:237], v[10:13]
	s_setprio 0
	s_setprio 1
	v_mfma_f32_16x16x32_bf16 v[38:41], v[170:173], v[222:225], v[38:41]
	v_mfma_f32_16x16x32_bf16 v[34:37], v[190:193], v[222:225], v[34:37]
	v_mfma_f32_16x16x32_bf16 v[6:9], v[170:173], v[230:233], v[6:9]
	v_mfma_f32_16x16x32_bf16 v[2:5], v[190:193], v[230:233], v[2:5]
	v_mfma_f32_16x16x32_bf16 v[18:21], v[170:173], v[198:201], v[70:73]
	v_mfma_f32_16x16x32_bf16 v[22:25], v[190:193], v[198:201], v[66:69]
	v_mfma_f32_16x16x32_bf16 v[26:29], v[170:173], v[214:217], v[54:57]
	v_mfma_f32_16x16x32_bf16 v[30:33], v[190:193], v[214:217], v[50:53]
	v_mfma_f32_16x16x32_bf16 v[38:41], v[174:177], v[226:229], v[38:41]
	v_mfma_f32_16x16x32_bf16 v[34:37], v[194:197], v[226:229], v[34:37]
	v_mfma_f32_16x16x32_bf16 v[6:9], v[174:177], v[234:237], v[6:9]
	v_mfma_f32_16x16x32_bf16 v[2:5], v[194:197], v[234:237], v[2:5]
	v_mfma_f32_16x16x32_bf16 v[18:21], v[174:177], v[210:213], v[18:21]
	v_mfma_f32_16x16x32_bf16 v[22:25], v[194:197], v[210:213], v[22:25]
	v_mfma_f32_16x16x32_bf16 v[26:29], v[174:177], v[218:221], v[26:29]
	v_mfma_f32_16x16x32_bf16 v[30:33], v[194:197], v[218:221], v[30:33]
	s_barrier
	s_setprio 0
	s_add_i32 s0, 0, 0x18000
	v_add_u32_e32 v0, s0, v178
	s_add_i32 s1, 0, 0x1c000
	ds_read_b128 v[50:53], v0
	ds_read_b128 v[54:57], v0 offset:1024
	ds_read_b128 v[66:69], v0 offset:2048
	ds_read_b128 v[70:73], v0 offset:3072
	v_add_u32_e32 v0, s1, v178
	ds_read_b128 v[170:173], v0
	ds_read_b128 v[174:177], v0 offset:1024
	ds_read_b128 v[190:193], v0 offset:2048
	ds_read_b128 v[194:197], v0 offset:3072
	s_add_u32 s74, s74, 0x40000
	s_addc_u32 s75, s75, 0
	s_mov_b32 m0, s83
	v_lshl_add_u64 v[238:239], s[74:75], 0, v[148:149]
	global_load_lds_dwordx4 v[238:239], off
	v_lshl_add_u64 v[238:239], s[74:75], 0, v[152:153]
	s_mov_b32 m0, s16
	s_nop 0
	global_load_lds_dwordx4 v[238:239], off
	ds_read_b128 v[198:201], v189 offset:32768
	ds_read_b128 v[210:213], v189 offset:33792
	ds_read_b128 v[214:217], v189 offset:34816
	ds_read_b128 v[218:221], v189 offset:35840
	ds_read_b128 v[222:225], v189 offset:36864
	ds_read_b128 v[226:229], v189 offset:37888
	ds_read_b128 v[230:233], v189 offset:38912
	ds_read_b128 v[234:237], v189 offset:39936
	s_waitcnt vmcnt(8)
	s_waitcnt lgkmcnt(0)
	s_setprio 1
	s_barrier
	v_mfma_f32_16x16x32_bf16 v[142:145], v[50:53], v[198:201], v[142:145]
	v_mfma_f32_16x16x32_bf16 v[138:141], v[66:69], v[198:201], v[138:141]
	v_mfma_f32_16x16x32_bf16 v[126:129], v[50:53], v[214:217], v[126:129]
	v_mfma_f32_16x16x32_bf16 v[122:125], v[66:69], v[214:217], v[122:125]
	v_mfma_f32_16x16x32_bf16 v[110:113], v[50:53], v[222:225], v[110:113]
	v_mfma_f32_16x16x32_bf16 v[106:109], v[66:69], v[222:225], v[106:109]
	v_mfma_f32_16x16x32_bf16 v[94:97], v[50:53], v[230:233], v[94:97]
	v_mfma_f32_16x16x32_bf16 v[90:93], v[66:69], v[230:233], v[90:93]
	v_mfma_f32_16x16x32_bf16 v[142:145], v[54:57], v[210:213], v[142:145]
	v_mfma_f32_16x16x32_bf16 v[138:141], v[70:73], v[210:213], v[138:141]
	v_mfma_f32_16x16x32_bf16 v[126:129], v[54:57], v[218:221], v[126:129]
	v_mfma_f32_16x16x32_bf16 v[122:125], v[70:73], v[218:221], v[122:125]
	v_mfma_f32_16x16x32_bf16 v[110:113], v[54:57], v[226:229], v[110:113]
	v_mfma_f32_16x16x32_bf16 v[106:109], v[70:73], v[226:229], v[106:109]
	v_mfma_f32_16x16x32_bf16 v[94:97], v[54:57], v[234:237], v[94:97]
	v_mfma_f32_16x16x32_bf16 v[90:93], v[70:73], v[234:237], v[90:93]
	s_setprio 0
	s_setprio 1
	v_mfma_f32_16x16x32_bf16 v[134:137], v[170:173], v[198:201], v[134:137]
	v_mfma_f32_16x16x32_bf16 v[130:133], v[190:193], v[198:201], v[130:133]
	v_mfma_f32_16x16x32_bf16 v[118:121], v[170:173], v[214:217], v[118:121]
	v_mfma_f32_16x16x32_bf16 v[114:117], v[190:193], v[214:217], v[114:117]
	v_mfma_f32_16x16x32_bf16 v[102:105], v[170:173], v[222:225], v[102:105]
	v_mfma_f32_16x16x32_bf16 v[98:101], v[190:193], v[222:225], v[98:101]
	v_mfma_f32_16x16x32_bf16 v[86:89], v[170:173], v[230:233], v[86:89]
	v_mfma_f32_16x16x32_bf16 v[82:85], v[190:193], v[230:233], v[82:85]
	v_mfma_f32_16x16x32_bf16 v[134:137], v[174:177], v[210:213], v[134:137]
	v_mfma_f32_16x16x32_bf16 v[130:133], v[194:197], v[210:213], v[130:133]
	v_mfma_f32_16x16x32_bf16 v[118:121], v[174:177], v[218:221], v[118:121]
	v_mfma_f32_16x16x32_bf16 v[114:117], v[194:197], v[218:221], v[114:117]
	v_mfma_f32_16x16x32_bf16 v[102:105], v[174:177], v[226:229], v[102:105]
	v_mfma_f32_16x16x32_bf16 v[98:101], v[194:197], v[226:229], v[98:101]
	v_mfma_f32_16x16x32_bf16 v[86:89], v[174:177], v[234:237], v[86:89]
	v_mfma_f32_16x16x32_bf16 v[82:85], v[194:197], v[234:237], v[82:85]
	s_barrier
; #define PG8_STAGE(bufoff, gbase, voff) do { _Pragma("unroll") for (int _i = 0; _i < 2; ++_i) \
;         __builtin_amdgcn_global_load_lds((const unsigned*)((const char*)(gbase) + (voff)[_i]), (LAS unsigned*)(lds + (bufoff) + ldsw + _i * 8192), 16, 0, 0); } while (0)
; #define PG8_LDA(dst, b, h) do { _Pragma("unroll") for (int m = 0; m < 4; ++m) _Pragma("unroll") for (int k = 0; k < 2; ++k) dst[m][k] = *(const LAS bf16x8*)(lds + PG8_SA(b, h) + aoff + m * 2048 + k * 1024); } while (0)
; #define PG8_MMA(ai, bj, At, Bt) do { __builtin_amdgcn_s_setprio(1); _Pragma("unroll") for (int m = 0; m < 4; ++m) _Pragma("unroll") for (int n = 0; n < 2; ++n) _Pragma("unroll") for (int k = 0; k < 2; ++k) \
;         acc[ai][bj][m][n] = __builtin_amdgcn_mfma_f32_16x16x32_bf16(Bt[n][k], At[m][k], acc[ai][bj][m][n], 0, 0, 0); __builtin_amdgcn_s_setprio(0); } while (0)
; #define PG8_WAIT_V(n) asm volatile("s_waitcnt vmcnt(" #n ")" ::: "memory")
; #define PG8_WAIT_L(n) asm volatile("s_waitcnt lgkmcnt(" #n ")" ::: "memory")
; #define PG8_BAR __builtin_amdgcn_s_barrier()
; #define PG8_SCHED __builtin_amdgcn_sched_barrier(0)
; template <class Epi>
; __device__ __forceinline__ void gemm_phase(LAS unsigned char* lds, const int tid, const Gemm g, const StaticOrder& S, const Epi& E) {
;     ...
;             PG8_WAIT_V(8); PG8_WAIT_L(0); PG8_BAR; PG8_MMA(0, 0, At, B0); PG8_MMA(0, 1, At, B1); PG8_BAR; PG8_SCHED;
;             PG8_LDA(At, 1, 1); PG8_STAGE(PG8_SB(1, 0), b3, voffB); PG8_STAGE(PG8_SB(1, 1), b3 + hstepB, voffB); PG8_STAGE(PG8_SA(1, 0), a3, voffA);
;             PG8_WAIT_V(8); PG8_WAIT_L(0); PG8_BAR; PG8_MMA(1, 0, At, B0); PG8_MMA(1, 1, At, B1); PG8_BAR; PG8_SCHED;
;         }
;         if (wr == 0) PG8_BAR;
	s_setprio 0
	s_add_i32 s0, s0, s93
	v_lshl_add_u64 v[162:163], v[162:163], 0, s[36:37]
	s_mov_b32 m0, s0
	s_nop 0
	global_load_lds_dwordx4 v[162:163], off
	s_add_i32 m0, s0, 0x2000
	s_add_u32 s30, s30, 0x40080
	v_lshl_add_u64 v[162:163], v[164:165], 0, s[36:37]
	s_addc_u32 s31, s31, 0
	s_add_i32 s0, s1, s93
	global_load_lds_dwordx4 v[162:163], off
	v_lshl_add_u64 v[162:163], s[30:31], 0, v[150:151]
	s_mov_b32 m0, s0
	s_nop 0
	global_load_lds_dwordx4 v[162:163], off
	v_lshl_add_u64 v[162:163], s[30:31], 0, v[154:155]
	s_add_i32 m0, s0, 0x2000
	s_nop 0
	global_load_lds_dwordx4 v[162:163], off
	v_lshl_add_u64 v[162:163], v[202:203], 0, s[36:37]
	s_mov_b32 m0, s92
	s_nop 0
	global_load_lds_dwordx4 v[162:163], off
	v_lshl_add_u64 v[162:163], v[206:207], 0, s[36:37]
	s_mov_b32 m0, s89
	s_nop 0
	global_load_lds_dwordx4 v[162:163], off
	ds_read_b128 v[198:201], v189 offset:49152
	ds_read_b128 v[210:213], v189 offset:50176
	ds_read_b128 v[214:217], v189 offset:51200
	ds_read_b128 v[218:221], v189 offset:52224
	ds_read_b128 v[222:225], v189 offset:53248
	ds_read_b128 v[226:229], v189 offset:54272
	ds_read_b128 v[230:233], v189 offset:55296
	ds_read_b128 v[234:237], v189 offset:56320
	s_waitcnt vmcnt(8)
	s_waitcnt lgkmcnt(0)
	s_setprio 1
	s_barrier
	v_mfma_f32_16x16x32_bf16 v[78:81], v[50:53], v[198:201], v[78:81]
	v_mfma_f32_16x16x32_bf16 v[74:77], v[66:69], v[198:201], v[74:77]
	v_mfma_f32_16x16x32_bf16 v[62:65], v[50:53], v[214:217], v[62:65]
	v_mfma_f32_16x16x32_bf16 v[58:61], v[66:69], v[214:217], v[58:61]
	v_mfma_f32_16x16x32_bf16 v[46:49], v[50:53], v[222:225], v[46:49]
	v_mfma_f32_16x16x32_bf16 v[42:45], v[66:69], v[222:225], v[42:45]
	v_mfma_f32_16x16x32_bf16 v[14:17], v[50:53], v[230:233], v[14:17]
	v_mfma_f32_16x16x32_bf16 v[10:13], v[66:69], v[230:233], v[10:13]
	v_mfma_f32_16x16x32_bf16 v[78:81], v[54:57], v[210:213], v[78:81]
	v_mfma_f32_16x16x32_bf16 v[74:77], v[70:73], v[210:213], v[74:77]
	v_mfma_f32_16x16x32_bf16 v[62:65], v[54:57], v[218:221], v[62:65]
	v_mfma_f32_16x16x32_bf16 v[58:61], v[70:73], v[218:221], v[58:61]
	v_mfma_f32_16x16x32_bf16 v[46:49], v[54:57], v[226:229], v[46:49]
	v_mfma_f32_16x16x32_bf16 v[42:45], v[70:73], v[226:229], v[42:45]
	v_mfma_f32_16x16x32_bf16 v[14:17], v[54:57], v[234:237], v[14:17]
	v_mfma_f32_16x16x32_bf16 v[10:13], v[70:73], v[234:237], v[10:13]
	s_setprio 0
	s_setprio 1
	v_mfma_f32_16x16x32_bf16 v[18:21], v[170:173], v[198:201], v[18:21]
	v_mfma_f32_16x16x32_bf16 v[70:73], v[174:177], v[210:213], v[18:21]
	v_mfma_f32_16x16x32_bf16 v[18:21], v[190:193], v[198:201], v[22:25]
	v_mfma_f32_16x16x32_bf16 v[66:69], v[194:197], v[210:213], v[18:21]
	v_mfma_f32_16x16x32_bf16 v[18:21], v[170:173], v[214:217], v[26:29]
	v_mfma_f32_16x16x32_bf16 v[54:57], v[174:177], v[218:221], v[18:21]
	v_mfma_f32_16x16x32_bf16 v[18:21], v[190:193], v[214:217], v[30:33]
	v_mfma_f32_16x16x32_bf16 v[50:53], v[194:197], v[218:221], v[18:21]
	v_mfma_f32_16x16x32_bf16 v[18:21], v[170:173], v[222:225], v[38:41]
	v_mfma_f32_16x16x32_bf16 v[38:41], v[174:177], v[226:229], v[18:21]
	v_mfma_f32_16x16x32_bf16 v[18:21], v[190:193], v[222:225], v[34:37]
	v_mfma_f32_16x16x32_bf16 v[6:9], v[170:173], v[230:233], v[6:9]
	v_mfma_f32_16x16x32_bf16 v[2:5], v[190:193], v[230:233], v[2:5]
	v_mfma_f32_16x16x32_bf16 v[34:37], v[194:197], v[226:229], v[18:21]
	v_mfma_f32_16x16x32_bf16 v[6:9], v[174:177], v[234:237], v[6:9]
	v_mfma_f32_16x16x32_bf16 v[2:5], v[194:197], v[234:237], v[2:5]
	s_barrier
	s_setprio 0
	s_add_i32 vcc_hi, vcc_hi, 2
	s_add_u32 s72, s72, 0x100
	s_addc_u32 s73, s73, 0
	s_add_u32 s65, s65, 0x100
	s_addc_u32 vcc_lo, vcc_lo, 0
	s_cmp_gt_u32 vcc_hi, 13
	s_cbranch_scc0 .LBB0_945
	s_and_b64 vcc, exec, s[4:5]
	s_cbranch_vccz .LBB0_948
	s_barrier

; #define PG8_STAGE(bufoff, gbase, voff) do { _Pragma("unroll") for (int _i = 0; _i < 2; ++_i) \
;         __builtin_amdgcn_global_load_lds((const unsigned*)((const char*)(gbase) + (voff)[_i]), (LAS unsigned*)(lds + (bufoff) + ldsw + _i * 8192), 16, 0, 0); } while (0)
; #define PG8_LDA(dst, b, h) do { _Pragma("unroll") for (int m = 0; m < 4; ++m) _Pragma("unroll") for (int k = 0; k < 2; ++k) dst[m][k] = *(const LAS bf16x8*)(lds + PG8_SA(b, h) + aoff + m * 2048 + k * 1024); } while (0)
; #define PG8_LDB(dst, b, h) do { _Pragma("unroll") for (int n = 0; n < 2; ++n) _Pragma("unroll") for (int k = 0; k < 2; ++k) dst[n][k] = *(const LAS bf16x8*)(lds + PG8_SB(b, h) + boff + n * 2048 + k * 1024); } while (0)
; #define PG8_MMA(ai, bj, At, Bt) do { __builtin_amdgcn_s_setprio(1); _Pragma("unroll") for (int m = 0; m < 4; ++m) _Pragma("unroll") for (int n = 0; n < 2; ++n) _Pragma("unroll") for (int k = 0; k < 2; ++k) \
;         acc[ai][bj][m][n] = __builtin_amdgcn_mfma_f32_16x16x32_bf16(Bt[n][k], At[m][k], acc[ai][bj][m][n], 0, 0, 0); __builtin_amdgcn_s_setprio(0); } while (0)
; #define PG8_WAIT_V(n) asm volatile("s_waitcnt vmcnt(" #n ")" ::: "memory")
; #define PG8_WAIT_L(n) asm volatile("s_waitcnt lgkmcnt(" #n ")" ::: "memory")
; #define PG8_BAR __builtin_amdgcn_s_barrier()
; #define PG8_SCHED __builtin_amdgcn_sched_barrier(0)
; template <class Epi>
; __device__ __forceinline__ void gemm_phase(LAS unsigned char* lds, const int tid, const Gemm g, const StaticOrder& S, const Epi& E) {
;     ...
;         for (int t = 0; t < nt; t += 2) {
;             const bool last = (t == nt - 2);
;             const char* a1 = cA + (size_t)(t + 1) * kstep;
;             const char* a2 = last ? nA : cA + (size_t)(t + 2) * kstep; const char* b2 = last ? nB : cB + (size_t)(t + 2) * kstep;
;             const char* a3 = a2 + kstep; const char* b3 = b2 + kstep;
;             PG8_LDB(B0, 0, 0); PG8_LDB(B1, 0, 1); PG8_SCHED; PG8_LDA(At, 0, 0); PG8_STAGE(PG8_SA(1, 1), a1 + hstepA, voffA);
;             PG8_WAIT_V(8); PG8_WAIT_L(0); PG8_BAR; PG8_MMA(0, 0, At, B0); PG8_MMA(0, 1, At, B1); PG8_BAR; PG8_SCHED;
;             PG8_LDA(At, 0, 1); PG8_STAGE(PG8_SB(0, 0), b2, voffB); PG8_STAGE(PG8_SB(0, 1), b2 + hstepB, voffB); PG8_STAGE(PG8_SA(0, 0), a2, voffA);
;             PG8_WAIT_V(8); PG8_WAIT_L(0); PG8_BAR; PG8_MMA(1, 0, At, B0); PG8_MMA(1, 1, At, B1); PG8_BAR; PG8_SCHED;
.LBB0_1284:
	s_add_u32 s2, s66, 0xfff80080
	s_addc_u32 s3, s67, -1
	s_add_i32 vcc_hi, 0, 0x10000
	s_cmp_eq_u32 vcc_lo, 12
	s_cselect_b32 s69, s11, s3
	s_cselect_b32 s68, s88, s2
	v_add_u32_e32 v144, vcc_hi, v171
	s_cselect_b32 s31, s9, s93
	s_cselect_b32 s30, s89, s92
	s_add_i32 s0, 0, 0x14000
	ds_read_b128 v[140:143], v144
	ds_read_b128 v[176:179], v144 offset:1024
	ds_read_b128 v[180:183], v144 offset:2048
	ds_read_b128 v[184:187], v144 offset:3072
	v_add_u32_e32 v144, s0, v171
	ds_read_b128 v[188:191], v144
	ds_read_b128 v[192:195], v144 offset:1024
	ds_read_b128 v[196:199], v144 offset:2048
	ds_read_b128 v[200:203], v144 offset:3072
	v_lshl_add_u64 v[144:145], s[66:67], 0, v[136:137]
	s_add_i32 m0, s71, 0xc000
	s_nop 0
	global_load_lds_dwordx4 v[144:145], off
	v_lshl_add_u64 v[144:145], s[66:67], 0, v[138:139]
	s_add_i32 m0, s71, 0xe000
	s_nop 0
	global_load_lds_dwordx4 v[144:145], off
	ds_read_b128 v[210:213], v174
	ds_read_b128 v[214:217], v174 offset:1024
	ds_read_b128 v[218:221], v174 offset:2048
	ds_read_b128 v[222:225], v174 offset:3072
	ds_read_b128 v[226:229], v174 offset:4096
	ds_read_b128 v[230:233], v174 offset:5120
	ds_read_b128 v[234:237], v174 offset:6144
	ds_read_b128 v[238:241], v174 offset:7168
	s_waitcnt vmcnt(8)
	s_waitcnt lgkmcnt(0)
	s_setprio 1
	s_barrier
	v_mfma_f32_16x16x32_bf16 v[126:129], v[140:143], v[210:213], v[126:129]
	v_mfma_f32_16x16x32_bf16 v[122:125], v[180:183], v[210:213], v[122:125]
	v_mfma_f32_16x16x32_bf16 v[118:121], v[140:143], v[218:221], v[118:121]
	v_mfma_f32_16x16x32_bf16 v[110:113], v[180:183], v[218:221], v[110:113]
	v_mfma_f32_16x16x32_bf16 v[94:97], v[140:143], v[226:229], v[94:97]
	v_mfma_f32_16x16x32_bf16 v[90:93], v[180:183], v[226:229], v[90:93]
	v_mfma_f32_16x16x32_bf16 v[86:89], v[140:143], v[234:237], v[86:89]
	v_mfma_f32_16x16x32_bf16 v[78:81], v[180:183], v[234:237], v[78:81]
	v_mfma_f32_16x16x32_bf16 v[126:129], v[176:179], v[214:217], v[126:129]
	v_mfma_f32_16x16x32_bf16 v[122:125], v[184:187], v[214:217], v[122:125]
	v_mfma_f32_16x16x32_bf16 v[118:121], v[176:179], v[222:225], v[118:121]
	v_mfma_f32_16x16x32_bf16 v[110:113], v[184:187], v[222:225], v[110:113]
	v_mfma_f32_16x16x32_bf16 v[94:97], v[176:179], v[230:233], v[94:97]
	v_mfma_f32_16x16x32_bf16 v[90:93], v[184:187], v[230:233], v[90:93]
	v_mfma_f32_16x16x32_bf16 v[86:89], v[176:179], v[238:241], v[86:89]
	v_mfma_f32_16x16x32_bf16 v[78:81], v[184:187], v[238:241], v[78:81]
	s_setprio 0
	s_setprio 1
	v_mfma_f32_16x16x32_bf16 v[114:117], v[188:191], v[210:213], v[114:117]
	v_mfma_f32_16x16x32_bf16 v[106:109], v[196:199], v[210:213], v[106:109]
	v_mfma_f32_16x16x32_bf16 v[102:105], v[188:191], v[218:221], v[102:105]
	v_mfma_f32_16x16x32_bf16 v[98:101], v[196:199], v[218:221], v[98:101]
	v_mfma_f32_16x16x32_bf16 v[82:85], v[188:191], v[226:229], v[82:85]
	v_mfma_f32_16x16x32_bf16 v[74:77], v[196:199], v[226:229], v[74:77]
	v_mfma_f32_16x16x32_bf16 v[70:73], v[188:191], v[234:237], v[70:73]
	v_mfma_f32_16x16x32_bf16 v[66:69], v[196:199], v[234:237], v[66:69]
	v_mfma_f32_16x16x32_bf16 v[114:117], v[192:195], v[214:217], v[114:117]
	v_mfma_f32_16x16x32_bf16 v[106:109], v[200:203], v[214:217], v[106:109]
	v_mfma_f32_16x16x32_bf16 v[102:105], v[192:195], v[222:225], v[102:105]
	v_mfma_f32_16x16x32_bf16 v[98:101], v[200:203], v[222:225], v[98:101]
	v_mfma_f32_16x16x32_bf16 v[82:85], v[192:195], v[230:233], v[82:85]
	v_mfma_f32_16x16x32_bf16 v[74:77], v[200:203], v[230:233], v[74:77]
	v_mfma_f32_16x16x32_bf16 v[70:73], v[192:195], v[238:241], v[70:73]
	v_mfma_f32_16x16x32_bf16 v[66:69], v[200:203], v[238:241], v[66:69]
	s_barrier
	s_setprio 0
	s_add_i32 s1, vcc_hi, s28
	v_lshl_add_u64 v[144:145], s[30:31], 0, v[0:1]
	s_mov_b32 m0, s1
	s_nop 0
	global_load_lds_dwordx4 v[144:145], off
	s_add_i32 m0, s1, 0x2000
	s_add_u32 s2, s30, 0x40000
	v_lshl_add_u64 v[162:163], s[30:31], 0, v[130:131]
	s_addc_u32 s3, s31, 0
	s_add_i32 s0, s0, s28
	global_load_lds_dwordx4 v[162:163], off
	v_lshl_add_u64 v[164:165], s[2:3], 0, v[0:1]
	s_mov_b32 m0, s0
	v_lshl_add_u64 v[206:207], s[68:69], 0, v[132:133]
	global_load_lds_dwordx4 v[164:165], off
	v_lshl_add_u64 v[164:165], s[2:3], 0, v[130:131]
	s_add_i32 m0, s0, 0x2000
	s_nop 0
	global_load_lds_dwordx4 v[164:165], off
	v_lshl_add_u64 v[164:165], s[68:69], 0, v[134:135]
	s_mov_b32 m0, s71
	s_nop 0
	global_load_lds_dwordx4 v[164:165], off
	s_mov_b32 m0, s72
	s_nop 0
	global_load_lds_dwordx4 v[206:207], off
	ds_read_b128 v[210:213], v174 offset:16384
	ds_read_b128 v[214:217], v174 offset:17408
	ds_read_b128 v[218:221], v174 offset:18432
	ds_read_b128 v[222:225], v174 offset:19456
	ds_read_b128 v[226:229], v174 offset:20480
	ds_read_b128 v[230:233], v174 offset:21504
	ds_read_b128 v[234:237], v174 offset:22528
	ds_read_b128 v[238:241], v174 offset:23552
	s_waitcnt vmcnt(8)
	s_waitcnt lgkmcnt(0)
	s_setprio 1
	s_barrier
; #define PG8_STAGE(bufoff, gbase, voff) do { _Pragma("unroll") for (int _i = 0; _i < 2; ++_i) \
;         __builtin_amdgcn_global_load_lds((const unsigned*)((const char*)(gbase) + (voff)[_i]), (LAS unsigned*)(lds + (bufoff) + ldsw + _i * 8192), 16, 0, 0); } while (0)
; #define PG8_LDA(dst, b, h) do { _Pragma("unroll") for (int m = 0; m < 4; ++m) _Pragma("unroll") for (int k = 0; k < 2; ++k) dst[m][k] = *(const LAS bf16x8*)(lds + PG8_SA(b, h) + aoff + m * 2048 + k * 1024); } while (0)
; #define PG8_LDB(dst, b, h) do { _Pragma("unroll") for (int n = 0; n < 2; ++n) _Pragma("unroll") for (int k = 0; k < 2; ++k) dst[n][k] = *(const LAS bf16x8*)(lds + PG8_SB(b, h) + boff + n * 2048 + k * 1024); } while (0)
; #define PG8_MMA(ai, bj, At, Bt) do { __builtin_amdgcn_s_setprio(1); _Pragma("unroll") for (int m = 0; m < 4; ++m) _Pragma("unroll") for (int n = 0; n < 2; ++n) _Pragma("unroll") for (int k = 0; k < 2; ++k) \
;         acc[ai][bj][m][n] = __builtin_amdgcn_mfma_f32_16x16x32_bf16(Bt[n][k], At[m][k], acc[ai][bj][m][n], 0, 0, 0); __builtin_amdgcn_s_setprio(0); } while (0)
; #define PG8_WAIT_V(n) asm volatile("s_waitcnt vmcnt(" #n ")" ::: "memory")
; #define PG8_WAIT_L(n) asm volatile("s_waitcnt lgkmcnt(" #n ")" ::: "memory")
; #define PG8_BAR __builtin_amdgcn_s_barrier()
; #define PG8_SCHED __builtin_amdgcn_sched_barrier(0)
; template <class Epi>
; __device__ __forceinline__ void gemm_phase(LAS unsigned char* lds, const int tid, const Gemm g, const StaticOrder& S, const Epi& E) {
;     ...
;             PG8_WAIT_V(8); PG8_WAIT_L(0); PG8_BAR; PG8_MMA(1, 0, At, B0); PG8_MMA(1, 1, At, B1); PG8_BAR; PG8_SCHED;
;             PG8_LDB(B0, 1, 0); PG8_LDB(B1, 1, 1); PG8_SCHED; PG8_LDA(At, 1, 0); PG8_STAGE(PG8_SA(0, 1), a2 + hstepA, voffA);
;             PG8_WAIT_V(8); PG8_WAIT_L(0); PG8_BAR; PG8_MMA(0, 0, At, B0); PG8_MMA(0, 1, At, B1); PG8_BAR; PG8_SCHED;
	v_mfma_f32_16x16x32_bf16 v[62:65], v[140:143], v[210:213], v[62:65]
	v_mfma_f32_16x16x32_bf16 v[58:61], v[180:183], v[210:213], v[58:61]
	v_mfma_f32_16x16x32_bf16 v[54:57], v[140:143], v[218:221], v[54:57]
	v_mfma_f32_16x16x32_bf16 v[46:49], v[180:183], v[218:221], v[46:49]
	v_mfma_f32_16x16x32_bf16 v[30:33], v[140:143], v[226:229], v[30:33]
	v_mfma_f32_16x16x32_bf16 v[26:29], v[180:183], v[226:229], v[26:29]
	v_mfma_f32_16x16x32_bf16 v[22:25], v[140:143], v[234:237], v[22:25]
	v_mfma_f32_16x16x32_bf16 v[14:17], v[180:183], v[234:237], v[14:17]
	v_mfma_f32_16x16x32_bf16 v[62:65], v[176:179], v[214:217], v[62:65]
	v_mfma_f32_16x16x32_bf16 v[58:61], v[184:187], v[214:217], v[58:61]
	v_mfma_f32_16x16x32_bf16 v[54:57], v[176:179], v[222:225], v[54:57]
	v_mfma_f32_16x16x32_bf16 v[46:49], v[184:187], v[222:225], v[46:49]
	v_mfma_f32_16x16x32_bf16 v[30:33], v[176:179], v[230:233], v[30:33]
	v_mfma_f32_16x16x32_bf16 v[26:29], v[184:187], v[230:233], v[26:29]
	v_mfma_f32_16x16x32_bf16 v[22:25], v[176:179], v[238:241], v[22:25]
	v_mfma_f32_16x16x32_bf16 v[14:17], v[184:187], v[238:241], v[14:17]
	s_setprio 0
	s_setprio 1
	v_mfma_f32_16x16x32_bf16 v[50:53], v[188:191], v[210:213], v[50:53]
	v_mfma_f32_16x16x32_bf16 v[42:45], v[196:199], v[210:213], v[42:45]
	v_mfma_f32_16x16x32_bf16 v[38:41], v[188:191], v[218:221], v[38:41]
	v_mfma_f32_16x16x32_bf16 v[34:37], v[196:199], v[218:221], v[34:37]
	v_mfma_f32_16x16x32_bf16 v[18:21], v[188:191], v[226:229], v[18:21]
	v_mfma_f32_16x16x32_bf16 v[10:13], v[196:199], v[226:229], v[10:13]
	v_mfma_f32_16x16x32_bf16 v[6:9], v[188:191], v[234:237], v[6:9]
	v_mfma_f32_16x16x32_bf16 v[2:5], v[196:199], v[234:237], v[2:5]
	v_mfma_f32_16x16x32_bf16 v[50:53], v[192:195], v[214:217], v[50:53]
	v_mfma_f32_16x16x32_bf16 v[42:45], v[200:203], v[214:217], v[42:45]
	v_mfma_f32_16x16x32_bf16 v[38:41], v[192:195], v[222:225], v[38:41]
	v_mfma_f32_16x16x32_bf16 v[34:37], v[200:203], v[222:225], v[34:37]
	v_mfma_f32_16x16x32_bf16 v[18:21], v[192:195], v[230:233], v[18:21]
	v_mfma_f32_16x16x32_bf16 v[10:13], v[200:203], v[230:233], v[10:13]
	v_mfma_f32_16x16x32_bf16 v[6:9], v[192:195], v[238:241], v[6:9]
	v_mfma_f32_16x16x32_bf16 v[2:5], v[200:203], v[238:241], v[2:5]
	s_barrier
	s_setprio 0
	s_add_i32 s0, 0, 0x18000
	v_add_u32_e32 v175, s0, v171
	s_add_i32 s1, 0, 0x1c000
	ds_read_b128 v[140:143], v175
	ds_read_b128 v[176:179], v175 offset:1024
	ds_read_b128 v[180:183], v175 offset:2048
	ds_read_b128 v[184:187], v175 offset:3072
	v_add_u32_e32 v175, s1, v171
	ds_read_b128 v[188:191], v175
	ds_read_b128 v[192:195], v175 offset:1024
	ds_read_b128 v[196:199], v175 offset:2048
	ds_read_b128 v[200:203], v175 offset:3072
	s_add_u32 s2, s68, 0x80000
	s_addc_u32 s3, s69, 0
	s_mov_b32 m0, s73
	v_lshl_add_u64 v[242:243], s[2:3], 0, v[134:135]
	global_load_lds_dwordx4 v[242:243], off
	v_lshl_add_u64 v[242:243], s[2:3], 0, v[132:133]
	s_mov_b32 m0, s74
	s_nop 0
	global_load_lds_dwordx4 v[242:243], off
	ds_read_b128 v[210:213], v174 offset:32768
	ds_read_b128 v[214:217], v174 offset:33792
	ds_read_b128 v[218:221], v174 offset:34816
	ds_read_b128 v[222:225], v174 offset:35840
	ds_read_b128 v[226:229], v174 offset:36864
	ds_read_b128 v[230:233], v174 offset:37888
	ds_read_b128 v[234:237], v174 offset:38912
	ds_read_b128 v[238:241], v174 offset:39936
	s_waitcnt vmcnt(8)
	s_waitcnt lgkmcnt(0)
	s_setprio 1
	s_barrier
	v_mfma_f32_16x16x32_bf16 v[126:129], v[140:143], v[210:213], v[126:129]
	v_mfma_f32_16x16x32_bf16 v[122:125], v[180:183], v[210:213], v[122:125]
	v_mfma_f32_16x16x32_bf16 v[118:121], v[140:143], v[218:221], v[118:121]
	v_mfma_f32_16x16x32_bf16 v[110:113], v[180:183], v[218:221], v[110:113]
	v_mfma_f32_16x16x32_bf16 v[94:97], v[140:143], v[226:229], v[94:97]
	v_mfma_f32_16x16x32_bf16 v[90:93], v[180:183], v[226:229], v[90:93]
	v_mfma_f32_16x16x32_bf16 v[86:89], v[140:143], v[234:237], v[86:89]
	v_mfma_f32_16x16x32_bf16 v[78:81], v[180:183], v[234:237], v[78:81]
	v_mfma_f32_16x16x32_bf16 v[126:129], v[176:179], v[214:217], v[126:129]
	v_mfma_f32_16x16x32_bf16 v[122:125], v[184:187], v[214:217], v[122:125]
	v_mfma_f32_16x16x32_bf16 v[118:121], v[176:179], v[222:225], v[118:121]
	v_mfma_f32_16x16x32_bf16 v[110:113], v[184:187], v[222:225], v[110:113]
	v_mfma_f32_16x16x32_bf16 v[94:97], v[176:179], v[230:233], v[94:97]
	v_mfma_f32_16x16x32_bf16 v[90:93], v[184:187], v[230:233], v[90:93]
	v_mfma_f32_16x16x32_bf16 v[86:89], v[176:179], v[238:241], v[86:89]
	v_mfma_f32_16x16x32_bf16 v[78:81], v[184:187], v[238:241], v[78:81]
	s_setprio 0
	s_setprio 1
	v_mfma_f32_16x16x32_bf16 v[114:117], v[188:191], v[210:213], v[114:117]
	v_mfma_f32_16x16x32_bf16 v[106:109], v[196:199], v[210:213], v[106:109]
	v_mfma_f32_16x16x32_bf16 v[102:105], v[188:191], v[218:221], v[102:105]
	v_mfma_f32_16x16x32_bf16 v[98:101], v[196:199], v[218:221], v[98:101]
	v_mfma_f32_16x16x32_bf16 v[82:85], v[188:191], v[226:229], v[82:85]
	v_mfma_f32_16x16x32_bf16 v[74:77], v[196:199], v[226:229], v[74:77]
	v_mfma_f32_16x16x32_bf16 v[70:73], v[188:191], v[234:237], v[70:73]
	v_mfma_f32_16x16x32_bf16 v[66:69], v[196:199], v[234:237], v[66:69]
	v_mfma_f32_16x16x32_bf16 v[114:117], v[192:195], v[214:217], v[114:117]
	v_mfma_f32_16x16x32_bf16 v[106:109], v[200:203], v[214:217], v[106:109]
	v_mfma_f32_16x16x32_bf16 v[102:105], v[192:195], v[222:225], v[102:105]
	v_mfma_f32_16x16x32_bf16 v[98:101], v[200:203], v[222:225], v[98:101]
	v_mfma_f32_16x16x32_bf16 v[82:85], v[192:195], v[230:233], v[82:85]
	v_mfma_f32_16x16x32_bf16 v[74:77], v[200:203], v[230:233], v[74:77]
	v_mfma_f32_16x16x32_bf16 v[70:73], v[192:195], v[238:241], v[70:73]
	v_mfma_f32_16x16x32_bf16 v[66:69], v[200:203], v[238:241], v[66:69]
	s_barrier
; #define PG8_STAGE(bufoff, gbase, voff) do { _Pragma("unroll") for (int _i = 0; _i < 2; ++_i) \
;         __builtin_amdgcn_global_load_lds((const unsigned*)((const char*)(gbase) + (voff)[_i]), (LAS unsigned*)(lds + (bufoff) + ldsw + _i * 8192), 16, 0, 0); } while (0)
; #define PG8_LDA(dst, b, h) do { _Pragma("unroll") for (int m = 0; m < 4; ++m) _Pragma("unroll") for (int k = 0; k < 2; ++k) dst[m][k] = *(const LAS bf16x8*)(lds + PG8_SA(b, h) + aoff + m * 2048 + k * 1024); } while (0)
; #define PG8_MMA(ai, bj, At, Bt) do { __builtin_amdgcn_s_setprio(1); _Pragma("unroll") for (int m = 0; m < 4; ++m) _Pragma("unroll") for (int n = 0; n < 2; ++n) _Pragma("unroll") for (int k = 0; k < 2; ++k) \
;         acc[ai][bj][m][n] = __builtin_amdgcn_mfma_f32_16x16x32_bf16(Bt[n][k], At[m][k], acc[ai][bj][m][n], 0, 0, 0); __builtin_amdgcn_s_setprio(0); } while (0)
; #define PG8_WAIT_V(n) asm volatile("s_waitcnt vmcnt(" #n ")" ::: "memory")
; #define PG8_WAIT_L(n) asm volatile("s_waitcnt lgkmcnt(" #n ")" ::: "memory")
; #define PG8_BAR __builtin_amdgcn_s_barrier()
; #define PG8_SCHED __builtin_amdgcn_sched_barrier(0)
; template <class Epi>
; __device__ __forceinline__ void gemm_phase(LAS unsigned char* lds, const int tid, const Gemm g, const StaticOrder& S, const Epi& E) {
;     ...
;             PG8_WAIT_V(8); PG8_WAIT_L(0); PG8_BAR; PG8_MMA(0, 0, At, B0); PG8_MMA(0, 1, At, B1); PG8_BAR; PG8_SCHED;
;             PG8_LDA(At, 1, 1); PG8_STAGE(PG8_SB(1, 0), b3, voffB); PG8_STAGE(PG8_SB(1, 1), b3 + hstepB, voffB); PG8_STAGE(PG8_SA(1, 0), a3, voffA);
;             PG8_WAIT_V(8); PG8_WAIT_L(0); PG8_BAR; PG8_MMA(1, 0, At, B0); PG8_MMA(1, 1, At, B1); PG8_BAR; PG8_SCHED;
;         }
;         if (wr == 0) PG8_BAR;
	s_setprio 0
	s_add_i32 s0, s0, s28
	v_lshl_add_u64 v[144:145], v[144:145], 0, s[36:37]
	s_mov_b32 m0, s0
	s_nop 0
	global_load_lds_dwordx4 v[144:145], off
	s_add_i32 m0, s0, 0x2000
	s_add_u32 s2, s30, 0x40080
	v_lshl_add_u64 v[144:145], v[162:163], 0, s[36:37]
	s_addc_u32 s3, s31, 0
	s_add_i32 s0, s1, s28
	global_load_lds_dwordx4 v[144:145], off
	v_lshl_add_u64 v[144:145], s[2:3], 0, v[0:1]
	s_mov_b32 m0, s0
	s_nop 0
	global_load_lds_dwordx4 v[144:145], off
	v_lshl_add_u64 v[144:145], s[2:3], 0, v[130:131]
	s_add_i32 m0, s0, 0x2000
	s_nop 0
	global_load_lds_dwordx4 v[144:145], off
	v_lshl_add_u64 v[144:145], v[164:165], 0, s[36:37]
	s_mov_b32 m0, s75
	s_nop 0
	global_load_lds_dwordx4 v[144:145], off
	v_lshl_add_u64 v[144:145], v[206:207], 0, s[36:37]
	s_mov_b32 m0, s76
	s_nop 0
	global_load_lds_dwordx4 v[144:145], off
	ds_read_b128 v[210:213], v174 offset:49152
	ds_read_b128 v[214:217], v174 offset:50176
	ds_read_b128 v[218:221], v174 offset:51200
	ds_read_b128 v[222:225], v174 offset:52224
	ds_read_b128 v[226:229], v174 offset:53248
	ds_read_b128 v[230:233], v174 offset:54272
	ds_read_b128 v[234:237], v174 offset:55296
	ds_read_b128 v[238:241], v174 offset:56320
	s_waitcnt vmcnt(8)
	s_waitcnt lgkmcnt(0)
	s_setprio 1
	s_barrier
	v_mfma_f32_16x16x32_bf16 v[62:65], v[140:143], v[210:213], v[62:65]
	v_mfma_f32_16x16x32_bf16 v[58:61], v[180:183], v[210:213], v[58:61]
	v_mfma_f32_16x16x32_bf16 v[54:57], v[140:143], v[218:221], v[54:57]
	v_mfma_f32_16x16x32_bf16 v[46:49], v[180:183], v[218:221], v[46:49]
	v_mfma_f32_16x16x32_bf16 v[30:33], v[140:143], v[226:229], v[30:33]
	v_mfma_f32_16x16x32_bf16 v[26:29], v[180:183], v[226:229], v[26:29]
	v_mfma_f32_16x16x32_bf16 v[22:25], v[140:143], v[234:237], v[22:25]
	v_mfma_f32_16x16x32_bf16 v[14:17], v[180:183], v[234:237], v[14:17]
	v_mfma_f32_16x16x32_bf16 v[62:65], v[176:179], v[214:217], v[62:65]
	v_mfma_f32_16x16x32_bf16 v[58:61], v[184:187], v[214:217], v[58:61]
	v_mfma_f32_16x16x32_bf16 v[54:57], v[176:179], v[222:225], v[54:57]
	v_mfma_f32_16x16x32_bf16 v[46:49], v[184:187], v[222:225], v[46:49]
	v_mfma_f32_16x16x32_bf16 v[30:33], v[176:179], v[230:233], v[30:33]
	v_mfma_f32_16x16x32_bf16 v[26:29], v[184:187], v[230:233], v[26:29]
	v_mfma_f32_16x16x32_bf16 v[22:25], v[176:179], v[238:241], v[22:25]
	v_mfma_f32_16x16x32_bf16 v[14:17], v[184:187], v[238:241], v[14:17]
	s_setprio 0
	s_setprio 1
	v_mfma_f32_16x16x32_bf16 v[50:53], v[188:191], v[210:213], v[50:53]
	v_mfma_f32_16x16x32_bf16 v[42:45], v[196:199], v[210:213], v[42:45]
	v_mfma_f32_16x16x32_bf16 v[38:41], v[188:191], v[218:221], v[38:41]
	v_mfma_f32_16x16x32_bf16 v[34:37], v[196:199], v[218:221], v[34:37]
	v_mfma_f32_16x16x32_bf16 v[18:21], v[188:191], v[226:229], v[18:21]
	v_mfma_f32_16x16x32_bf16 v[10:13], v[196:199], v[226:229], v[10:13]
	v_mfma_f32_16x16x32_bf16 v[6:9], v[188:191], v[234:237], v[6:9]
	v_mfma_f32_16x16x32_bf16 v[2:5], v[196:199], v[234:237], v[2:5]
	v_mfma_f32_16x16x32_bf16 v[50:53], v[192:195], v[214:217], v[50:53]
	v_mfma_f32_16x16x32_bf16 v[42:45], v[200:203], v[214:217], v[42:45]
	v_mfma_f32_16x16x32_bf16 v[38:41], v[192:195], v[222:225], v[38:41]
	v_mfma_f32_16x16x32_bf16 v[34:37], v[200:203], v[222:225], v[34:37]
	v_mfma_f32_16x16x32_bf16 v[18:21], v[192:195], v[230:233], v[18:21]
	v_mfma_f32_16x16x32_bf16 v[10:13], v[200:203], v[230:233], v[10:13]
	v_mfma_f32_16x16x32_bf16 v[6:9], v[192:195], v[238:241], v[6:9]
	v_mfma_f32_16x16x32_bf16 v[2:5], v[200:203], v[238:241], v[2:5]
	s_barrier
	s_setprio 0
	s_add_i32 vcc_lo, vcc_lo, 2
	s_add_u32 s66, s66, 0x100
	s_addc_u32 s67, s67, 0
	s_add_u32 s92, s92, 0x100
	s_addc_u32 s93, s93, 0
	s_cmp_gt_u32 vcc_lo, 13
	s_cbranch_scc0 .LBB0_1284
	s_and_b64 vcc, exec, s[6:7]
	s_mov_b32 s92, 0x2c000
	s_mov_b32 s93, 0x2e000
	s_cbranch_vccz .LBB0_1287
	s_barrier

; #define PG8_STAGE(bufoff, gbase, voff) do { _Pragma("unroll") for (int _i = 0; _i < 2; ++_i) \
;         __builtin_amdgcn_global_load_lds((const unsigned*)((const char*)(gbase) + (voff)[_i]), (LAS unsigned*)(lds + (bufoff) + ldsw + _i * 8192), 16, 0, 0); } while (0)
; #define PG8_LDA(dst, b, h) do { _Pragma("unroll") for (int m = 0; m < 4; ++m) _Pragma("unroll") for (int k = 0; k < 2; ++k) dst[m][k] = *(const LAS bf16x8*)(lds + PG8_SA(b, h) + aoff + m * 2048 + k * 1024); } while (0)
; #define PG8_LDB(dst, b, h) do { _Pragma("unroll") for (int n = 0; n < 2; ++n) _Pragma("unroll") for (int k = 0; k < 2; ++k) dst[n][k] = *(const LAS bf16x8*)(lds + PG8_SB(b, h) + boff + n * 2048 + k * 1024); } while (0)
; #define PG8_MMA(ai, bj, At, Bt) do { __builtin_amdgcn_s_setprio(1); _Pragma("unroll") for (int m = 0; m < 4; ++m) _Pragma("unroll") for (int n = 0; n < 2; ++n) _Pragma("unroll") for (int k = 0; k < 2; ++k) \
;         acc[ai][bj][m][n] = __builtin_amdgcn_mfma_f32_16x16x32_bf16(Bt[n][k], At[m][k], acc[ai][bj][m][n], 0, 0, 0); __builtin_amdgcn_s_setprio(0); } while (0)
; #define PG8_WAIT_V(n) asm volatile("s_waitcnt vmcnt(" #n ")" ::: "memory")
; #define PG8_WAIT_L(n) asm volatile("s_waitcnt lgkmcnt(" #n ")" ::: "memory")
; #define PG8_BAR __builtin_amdgcn_s_barrier()
; #define PG8_SCHED __builtin_amdgcn_sched_barrier(0)
; template <class Epi>
; __device__ __forceinline__ void gemm_phase(LAS unsigned char* lds, const int tid, const Gemm g, const StaticOrder& S, const Epi& E) {
;     ...
;         for (int t = 0; t < nt; t += 2) {
;             const bool last = (t == nt - 2);
;             const char* a1 = cA + (size_t)(t + 1) * kstep;
;             const char* a2 = last ? nA : cA + (size_t)(t + 2) * kstep; const char* b2 = last ? nB : cB + (size_t)(t + 2) * kstep;
;             const char* a3 = a2 + kstep; const char* b3 = b2 + kstep;
;             PG8_LDB(B0, 0, 0); PG8_LDB(B1, 0, 1); PG8_SCHED; PG8_LDA(At, 0, 0); PG8_STAGE(PG8_SA(1, 1), a1 + hstepA, voffA);
;             PG8_WAIT_V(8); PG8_WAIT_L(0); PG8_BAR; PG8_MMA(0, 0, At, B0); PG8_MMA(0, 1, At, B1); PG8_BAR; PG8_SCHED;
;             PG8_LDA(At, 0, 1); PG8_STAGE(PG8_SB(0, 0), b2, voffB); PG8_STAGE(PG8_SB(0, 1), b2 + hstepB, voffB); PG8_STAGE(PG8_SA(0, 0), a2, voffA);
;             PG8_WAIT_V(8); PG8_WAIT_L(0); PG8_BAR; PG8_MMA(1, 0, At, B0); PG8_MMA(1, 1, At, B1); PG8_BAR; PG8_SCHED;
.LBB0_1333:
	s_add_u32 s0, s66, 0xfff80080
	s_addc_u32 s1, s67, -1
	s_add_i32 s2, 0, 0x10000
	s_cmp_eq_u32 vcc_lo, 12
	s_cselect_b32 s69, s11, s1
	s_cselect_b32 s68, s88, s0
	s_cselect_b32 s31, s9, s93
	s_cselect_b32 s30, s89, s92
	s_add_i32 s0, 0, 0x14000
	v_add_u32_e32 v142, s2, v189
	v_add_u32_e32 v162, s0, v189
	ds_read_b128 v[130:133], v142
	ds_read_b128 v[134:137], v142 offset:1024
	ds_read_b128 v[138:141], v142 offset:2048
	ds_read_b128 v[142:145], v142 offset:3072
	ds_read_b128 v[158:161], v162
	ds_read_b128 v[192:195], v162 offset:1024
	ds_read_b128 v[196:199], v162 offset:2048
	ds_read_b128 v[200:203], v162 offset:3072
	v_lshl_add_u64 v[162:163], s[66:67], 0, v[154:155]
	s_add_i32 m0, s71, 0xc000
	s_nop 0
	global_load_lds_dwordx4 v[162:163], off
	v_lshl_add_u64 v[162:163], s[66:67], 0, v[156:157]
	s_add_i32 m0, s71, 0xe000
	s_nop 0
	global_load_lds_dwordx4 v[162:163], off
	ds_read_b128 v[210:213], v191
	ds_read_b128 v[214:217], v191 offset:1024
	ds_read_b128 v[218:221], v191 offset:2048
	ds_read_b128 v[222:225], v191 offset:3072
	ds_read_b128 v[226:229], v191 offset:4096
	ds_read_b128 v[230:233], v191 offset:5120
	ds_read_b128 v[234:237], v191 offset:6144
	ds_read_b128 v[238:241], v191 offset:7168
	s_waitcnt vmcnt(8)
	s_waitcnt lgkmcnt(0)
	s_setprio 1
	s_barrier
	v_mfma_f32_16x16x32_bf16 v[126:129], v[130:133], v[210:213], v[126:129]
	v_mfma_f32_16x16x32_bf16 v[122:125], v[138:141], v[210:213], v[122:125]
	v_mfma_f32_16x16x32_bf16 v[110:113], v[130:133], v[218:221], v[110:113]
	v_mfma_f32_16x16x32_bf16 v[106:109], v[138:141], v[218:221], v[106:109]
	v_mfma_f32_16x16x32_bf16 v[94:97], v[130:133], v[226:229], v[94:97]
	v_mfma_f32_16x16x32_bf16 v[90:93], v[138:141], v[226:229], v[90:93]
	v_mfma_f32_16x16x32_bf16 v[78:81], v[130:133], v[234:237], v[78:81]
	v_mfma_f32_16x16x32_bf16 v[74:77], v[138:141], v[234:237], v[74:77]
	v_mfma_f32_16x16x32_bf16 v[126:129], v[134:137], v[214:217], v[126:129]
	v_mfma_f32_16x16x32_bf16 v[122:125], v[142:145], v[214:217], v[122:125]
	v_mfma_f32_16x16x32_bf16 v[110:113], v[134:137], v[222:225], v[110:113]
	v_mfma_f32_16x16x32_bf16 v[106:109], v[142:145], v[222:225], v[106:109]
	v_mfma_f32_16x16x32_bf16 v[94:97], v[134:137], v[230:233], v[94:97]
	v_mfma_f32_16x16x32_bf16 v[90:93], v[142:145], v[230:233], v[90:93]
	v_mfma_f32_16x16x32_bf16 v[78:81], v[134:137], v[238:241], v[78:81]
	v_mfma_f32_16x16x32_bf16 v[74:77], v[142:145], v[238:241], v[74:77]
	s_setprio 0
	s_setprio 1
	v_mfma_f32_16x16x32_bf16 v[118:121], v[158:161], v[210:213], v[118:121]
	v_mfma_f32_16x16x32_bf16 v[114:117], v[196:199], v[210:213], v[114:117]
	v_mfma_f32_16x16x32_bf16 v[102:105], v[158:161], v[218:221], v[102:105]
	v_mfma_f32_16x16x32_bf16 v[98:101], v[196:199], v[218:221], v[98:101]
	v_mfma_f32_16x16x32_bf16 v[86:89], v[158:161], v[226:229], v[86:89]
	v_mfma_f32_16x16x32_bf16 v[82:85], v[196:199], v[226:229], v[82:85]
	v_mfma_f32_16x16x32_bf16 v[70:73], v[158:161], v[234:237], v[70:73]
	v_mfma_f32_16x16x32_bf16 v[66:69], v[196:199], v[234:237], v[66:69]
	v_mfma_f32_16x16x32_bf16 v[118:121], v[192:195], v[214:217], v[118:121]
	v_mfma_f32_16x16x32_bf16 v[114:117], v[200:203], v[214:217], v[114:117]
	v_mfma_f32_16x16x32_bf16 v[102:105], v[192:195], v[222:225], v[102:105]
	v_mfma_f32_16x16x32_bf16 v[98:101], v[200:203], v[222:225], v[98:101]
	v_mfma_f32_16x16x32_bf16 v[86:89], v[192:195], v[230:233], v[86:89]
	v_mfma_f32_16x16x32_bf16 v[82:85], v[200:203], v[230:233], v[82:85]
	v_mfma_f32_16x16x32_bf16 v[70:73], v[192:195], v[238:241], v[70:73]
	v_mfma_f32_16x16x32_bf16 v[66:69], v[200:203], v[238:241], v[66:69]
	s_barrier
	s_setprio 0
	s_add_i32 s1, s2, s28
	v_lshl_add_u64 v[162:163], s[30:31], 0, v[0:1]
	s_mov_b32 m0, s1
	s_nop 0
	global_load_lds_dwordx4 v[162:163], off
	s_add_i32 m0, s1, 0x2000
	s_add_u32 s2, s30, 0x40000
	v_lshl_add_u64 v[164:165], s[30:31], 0, v[148:149]
	s_addc_u32 s3, s31, 0
	s_add_i32 s0, s0, s28
	global_load_lds_dwordx4 v[164:165], off
	v_lshl_add_u64 v[170:171], s[2:3], 0, v[0:1]
	s_mov_b32 m0, s0
	v_lshl_add_u64 v[206:207], s[68:69], 0, v[150:151]
	global_load_lds_dwordx4 v[170:171], off
	v_lshl_add_u64 v[170:171], s[2:3], 0, v[148:149]
	s_add_i32 m0, s0, 0x2000
	s_nop 0
	global_load_lds_dwordx4 v[170:171], off
	v_lshl_add_u64 v[170:171], s[68:69], 0, v[152:153]
	s_mov_b32 m0, s71
	s_nop 0
	global_load_lds_dwordx4 v[170:171], off
	s_mov_b32 m0, s72
	s_nop 0
	global_load_lds_dwordx4 v[206:207], off
	ds_read_b128 v[210:213], v191 offset:16384
	ds_read_b128 v[214:217], v191 offset:17408
	ds_read_b128 v[218:221], v191 offset:18432
	ds_read_b128 v[222:225], v191 offset:19456
	ds_read_b128 v[226:229], v191 offset:20480
	ds_read_b128 v[230:233], v191 offset:21504
	ds_read_b128 v[234:237], v191 offset:22528
	ds_read_b128 v[238:241], v191 offset:23552
	s_waitcnt vmcnt(8)
	s_waitcnt lgkmcnt(0)
	s_setprio 1
	s_barrier
; #define PG8_STAGE(bufoff, gbase, voff) do { _Pragma("unroll") for (int _i = 0; _i < 2; ++_i) \
;         __builtin_amdgcn_global_load_lds((const unsigned*)((const char*)(gbase) + (voff)[_i]), (LAS unsigned*)(lds + (bufoff) + ldsw + _i * 8192), 16, 0, 0); } while (0)
; #define PG8_LDA(dst, b, h) do { _Pragma("unroll") for (int m = 0; m < 4; ++m) _Pragma("unroll") for (int k = 0; k < 2; ++k) dst[m][k] = *(const LAS bf16x8*)(lds + PG8_SA(b, h) + aoff + m * 2048 + k * 1024); } while (0)
; #define PG8_LDB(dst, b, h) do { _Pragma("unroll") for (int n = 0; n < 2; ++n) _Pragma("unroll") for (int k = 0; k < 2; ++k) dst[n][k] = *(const LAS bf16x8*)(lds + PG8_SB(b, h) + boff + n * 2048 + k * 1024); } while (0)
; #define PG8_MMA(ai, bj, At, Bt) do { __builtin_amdgcn_s_setprio(1); _Pragma("unroll") for (int m = 0; m < 4; ++m) _Pragma("unroll") for (int n = 0; n < 2; ++n) _Pragma("unroll") for (int k = 0; k < 2; ++k) \
;         acc[ai][bj][m][n] = __builtin_amdgcn_mfma_f32_16x16x32_bf16(Bt[n][k], At[m][k], acc[ai][bj][m][n], 0, 0, 0); __builtin_amdgcn_s_setprio(0); } while (0)
; #define PG8_WAIT_V(n) asm volatile("s_waitcnt vmcnt(" #n ")" ::: "memory")
; #define PG8_WAIT_L(n) asm volatile("s_waitcnt lgkmcnt(" #n ")" ::: "memory")
; #define PG8_BAR __builtin_amdgcn_s_barrier()
; #define PG8_SCHED __builtin_amdgcn_sched_barrier(0)
; template <class Epi>
; __device__ __forceinline__ void gemm_phase(LAS unsigned char* lds, const int tid, const Gemm g, const StaticOrder& S, const Epi& E) {
;     ...
;             PG8_WAIT_V(8); PG8_WAIT_L(0); PG8_BAR; PG8_MMA(1, 0, At, B0); PG8_MMA(1, 1, At, B1); PG8_BAR; PG8_SCHED;
;             PG8_LDB(B0, 1, 0); PG8_LDB(B1, 1, 1); PG8_SCHED; PG8_LDA(At, 1, 0); PG8_STAGE(PG8_SA(0, 1), a2 + hstepA, voffA);
;             PG8_WAIT_V(8); PG8_WAIT_L(0); PG8_BAR; PG8_MMA(0, 0, At, B0); PG8_MMA(0, 1, At, B1); PG8_BAR; PG8_SCHED;
	v_mfma_f32_16x16x32_bf16 v[62:65], v[130:133], v[210:213], v[62:65]
	v_mfma_f32_16x16x32_bf16 v[58:61], v[138:141], v[210:213], v[58:61]
	v_mfma_f32_16x16x32_bf16 v[46:49], v[130:133], v[218:221], v[46:49]
	v_mfma_f32_16x16x32_bf16 v[42:45], v[138:141], v[218:221], v[42:45]
	v_mfma_f32_16x16x32_bf16 v[30:33], v[130:133], v[226:229], v[30:33]
	v_mfma_f32_16x16x32_bf16 v[26:29], v[138:141], v[226:229], v[26:29]
	v_mfma_f32_16x16x32_bf16 v[14:17], v[130:133], v[234:237], v[14:17]
	v_mfma_f32_16x16x32_bf16 v[10:13], v[138:141], v[234:237], v[10:13]
	v_mfma_f32_16x16x32_bf16 v[62:65], v[134:137], v[214:217], v[62:65]
	v_mfma_f32_16x16x32_bf16 v[58:61], v[142:145], v[214:217], v[58:61]
	v_mfma_f32_16x16x32_bf16 v[46:49], v[134:137], v[222:225], v[46:49]
	v_mfma_f32_16x16x32_bf16 v[42:45], v[142:145], v[222:225], v[42:45]
	v_mfma_f32_16x16x32_bf16 v[30:33], v[134:137], v[230:233], v[30:33]
	v_mfma_f32_16x16x32_bf16 v[26:29], v[142:145], v[230:233], v[26:29]
	v_mfma_f32_16x16x32_bf16 v[14:17], v[134:137], v[238:241], v[14:17]
	v_mfma_f32_16x16x32_bf16 v[10:13], v[142:145], v[238:241], v[10:13]
	s_setprio 0
	s_setprio 1
	v_mfma_f32_16x16x32_bf16 v[54:57], v[158:161], v[210:213], v[54:57]
	v_mfma_f32_16x16x32_bf16 v[50:53], v[196:199], v[210:213], v[50:53]
	v_mfma_f32_16x16x32_bf16 v[38:41], v[158:161], v[218:221], v[38:41]
	v_mfma_f32_16x16x32_bf16 v[34:37], v[196:199], v[218:221], v[34:37]
	v_mfma_f32_16x16x32_bf16 v[22:25], v[158:161], v[226:229], v[22:25]
	v_mfma_f32_16x16x32_bf16 v[18:21], v[196:199], v[226:229], v[18:21]
	v_mfma_f32_16x16x32_bf16 v[6:9], v[158:161], v[234:237], v[6:9]
	v_mfma_f32_16x16x32_bf16 v[2:5], v[196:199], v[234:237], v[2:5]
	v_mfma_f32_16x16x32_bf16 v[54:57], v[192:195], v[214:217], v[54:57]
	v_mfma_f32_16x16x32_bf16 v[50:53], v[200:203], v[214:217], v[50:53]
	v_mfma_f32_16x16x32_bf16 v[38:41], v[192:195], v[222:225], v[38:41]
	v_mfma_f32_16x16x32_bf16 v[34:37], v[200:203], v[222:225], v[34:37]
	v_mfma_f32_16x16x32_bf16 v[22:25], v[192:195], v[230:233], v[22:25]
	v_mfma_f32_16x16x32_bf16 v[18:21], v[200:203], v[230:233], v[18:21]
	v_mfma_f32_16x16x32_bf16 v[6:9], v[192:195], v[238:241], v[6:9]
	v_mfma_f32_16x16x32_bf16 v[2:5], v[200:203], v[238:241], v[2:5]
	s_barrier
	s_setprio 0
	s_add_i32 s0, 0, 0x18000
	s_add_i32 s1, 0, 0x1c000
	v_add_u32_e32 v142, s0, v189
	v_add_u32_e32 v200, s1, v189
	ds_read_b128 v[130:133], v142
	ds_read_b128 v[134:137], v142 offset:1024
	ds_read_b128 v[138:141], v142 offset:2048
	ds_read_b128 v[142:145], v142 offset:3072
	ds_read_b128 v[158:161], v200
	ds_read_b128 v[192:195], v200 offset:1024
	ds_read_b128 v[196:199], v200 offset:2048
	ds_read_b128 v[200:203], v200 offset:3072
	s_add_u32 s2, s68, 0x80000
	s_addc_u32 s3, s69, 0
	s_mov_b32 m0, s73
	v_lshl_add_u64 v[242:243], s[2:3], 0, v[152:153]
	global_load_lds_dwordx4 v[242:243], off
	v_lshl_add_u64 v[242:243], s[2:3], 0, v[150:151]
	s_mov_b32 m0, s74
	s_nop 0
	global_load_lds_dwordx4 v[242:243], off
	ds_read_b128 v[210:213], v191 offset:32768
	ds_read_b128 v[214:217], v191 offset:33792
	ds_read_b128 v[218:221], v191 offset:34816
	ds_read_b128 v[222:225], v191 offset:35840
	ds_read_b128 v[226:229], v191 offset:36864
	ds_read_b128 v[230:233], v191 offset:37888
	ds_read_b128 v[234:237], v191 offset:38912
	ds_read_b128 v[238:241], v191 offset:39936
	s_waitcnt vmcnt(8)
	s_waitcnt lgkmcnt(0)
	s_setprio 1
	s_barrier
	v_mfma_f32_16x16x32_bf16 v[126:129], v[130:133], v[210:213], v[126:129]
	v_mfma_f32_16x16x32_bf16 v[122:125], v[138:141], v[210:213], v[122:125]
	v_mfma_f32_16x16x32_bf16 v[110:113], v[130:133], v[218:221], v[110:113]
	v_mfma_f32_16x16x32_bf16 v[106:109], v[138:141], v[218:221], v[106:109]
	v_mfma_f32_16x16x32_bf16 v[94:97], v[130:133], v[226:229], v[94:97]
	v_mfma_f32_16x16x32_bf16 v[90:93], v[138:141], v[226:229], v[90:93]
	v_mfma_f32_16x16x32_bf16 v[78:81], v[130:133], v[234:237], v[78:81]
	v_mfma_f32_16x16x32_bf16 v[74:77], v[138:141], v[234:237], v[74:77]
	v_mfma_f32_16x16x32_bf16 v[126:129], v[134:137], v[214:217], v[126:129]
	v_mfma_f32_16x16x32_bf16 v[122:125], v[142:145], v[214:217], v[122:125]
	v_mfma_f32_16x16x32_bf16 v[110:113], v[134:137], v[222:225], v[110:113]
	v_mfma_f32_16x16x32_bf16 v[106:109], v[142:145], v[222:225], v[106:109]
	v_mfma_f32_16x16x32_bf16 v[94:97], v[134:137], v[230:233], v[94:97]
	v_mfma_f32_16x16x32_bf16 v[90:93], v[142:145], v[230:233], v[90:93]
	v_mfma_f32_16x16x32_bf16 v[78:81], v[134:137], v[238:241], v[78:81]
	v_mfma_f32_16x16x32_bf16 v[74:77], v[142:145], v[238:241], v[74:77]
	s_setprio 0
	s_setprio 1
	v_mfma_f32_16x16x32_bf16 v[118:121], v[158:161], v[210:213], v[118:121]
	v_mfma_f32_16x16x32_bf16 v[114:117], v[196:199], v[210:213], v[114:117]
	v_mfma_f32_16x16x32_bf16 v[102:105], v[158:161], v[218:221], v[102:105]
	v_mfma_f32_16x16x32_bf16 v[98:101], v[196:199], v[218:221], v[98:101]
	v_mfma_f32_16x16x32_bf16 v[86:89], v[158:161], v[226:229], v[86:89]
	v_mfma_f32_16x16x32_bf16 v[82:85], v[196:199], v[226:229], v[82:85]
	v_mfma_f32_16x16x32_bf16 v[70:73], v[158:161], v[234:237], v[70:73]
	v_mfma_f32_16x16x32_bf16 v[66:69], v[196:199], v[234:237], v[66:69]
	v_mfma_f32_16x16x32_bf16 v[118:121], v[192:195], v[214:217], v[118:121]
	v_mfma_f32_16x16x32_bf16 v[114:117], v[200:203], v[214:217], v[114:117]
	v_mfma_f32_16x16x32_bf16 v[102:105], v[192:195], v[222:225], v[102:105]
	v_mfma_f32_16x16x32_bf16 v[98:101], v[200:203], v[222:225], v[98:101]
	v_mfma_f32_16x16x32_bf16 v[86:89], v[192:195], v[230:233], v[86:89]
	v_mfma_f32_16x16x32_bf16 v[82:85], v[200:203], v[230:233], v[82:85]
	v_mfma_f32_16x16x32_bf16 v[70:73], v[192:195], v[238:241], v[70:73]
	v_mfma_f32_16x16x32_bf16 v[66:69], v[200:203], v[238:241], v[66:69]
	s_barrier
; #define PG8_STAGE(bufoff, gbase, voff) do { _Pragma("unroll") for (int _i = 0; _i < 2; ++_i) \
;         __builtin_amdgcn_global_load_lds((const unsigned*)((const char*)(gbase) + (voff)[_i]), (LAS unsigned*)(lds + (bufoff) + ldsw + _i * 8192), 16, 0, 0); } while (0)
; #define PG8_LDA(dst, b, h) do { _Pragma("unroll") for (int m = 0; m < 4; ++m) _Pragma("unroll") for (int k = 0; k < 2; ++k) dst[m][k] = *(const LAS bf16x8*)(lds + PG8_SA(b, h) + aoff + m * 2048 + k * 1024); } while (0)
; #define PG8_MMA(ai, bj, At, Bt) do { __builtin_amdgcn_s_setprio(1); _Pragma("unroll") for (int m = 0; m < 4; ++m) _Pragma("unroll") for (int n = 0; n < 2; ++n) _Pragma("unroll") for (int k = 0; k < 2; ++k) \
;         acc[ai][bj][m][n] = __builtin_amdgcn_mfma_f32_16x16x32_bf16(Bt[n][k], At[m][k], acc[ai][bj][m][n], 0, 0, 0); __builtin_amdgcn_s_setprio(0); } while (0)
; #define PG8_WAIT_V(n) asm volatile("s_waitcnt vmcnt(" #n ")" ::: "memory")
; #define PG8_WAIT_L(n) asm volatile("s_waitcnt lgkmcnt(" #n ")" ::: "memory")
; #define PG8_BAR __builtin_amdgcn_s_barrier()
; #define PG8_SCHED __builtin_amdgcn_sched_barrier(0)
; template <class Epi>
; __device__ __forceinline__ void gemm_phase(LAS unsigned char* lds, const int tid, const Gemm g, const StaticOrder& S, const Epi& E) {
;     ...
;             PG8_WAIT_V(8); PG8_WAIT_L(0); PG8_BAR; PG8_MMA(0, 0, At, B0); PG8_MMA(0, 1, At, B1); PG8_BAR; PG8_SCHED;
;             PG8_LDA(At, 1, 1); PG8_STAGE(PG8_SB(1, 0), b3, voffB); PG8_STAGE(PG8_SB(1, 1), b3 + hstepB, voffB); PG8_STAGE(PG8_SA(1, 0), a3, voffA);
;             PG8_WAIT_V(8); PG8_WAIT_L(0); PG8_BAR; PG8_MMA(1, 0, At, B0); PG8_MMA(1, 1, At, B1); PG8_BAR; PG8_SCHED;
;         }
;         if (wr == 0) PG8_BAR;
	s_setprio 0
	s_add_i32 s0, s0, s28
	v_lshl_add_u64 v[162:163], v[162:163], 0, s[36:37]
	s_mov_b32 m0, s0
	s_nop 0
	global_load_lds_dwordx4 v[162:163], off
	s_add_i32 m0, s0, 0x2000
	s_add_u32 s2, s30, 0x40080
	v_lshl_add_u64 v[162:163], v[164:165], 0, s[36:37]
	s_addc_u32 s3, s31, 0
	s_add_i32 s0, s1, s28
	global_load_lds_dwordx4 v[162:163], off
	v_lshl_add_u64 v[162:163], s[2:3], 0, v[0:1]
	s_mov_b32 m0, s0
	s_nop 0
	global_load_lds_dwordx4 v[162:163], off
	v_lshl_add_u64 v[162:163], s[2:3], 0, v[148:149]
	s_add_i32 m0, s0, 0x2000
	s_nop 0
	global_load_lds_dwordx4 v[162:163], off
	v_lshl_add_u64 v[162:163], v[170:171], 0, s[36:37]
	s_mov_b32 m0, s75
	s_nop 0
	global_load_lds_dwordx4 v[162:163], off
	v_lshl_add_u64 v[162:163], v[206:207], 0, s[36:37]
	s_mov_b32 m0, s76
	s_nop 0
	global_load_lds_dwordx4 v[162:163], off
	ds_read_b128 v[210:213], v191 offset:49152
	ds_read_b128 v[214:217], v191 offset:50176
	ds_read_b128 v[218:221], v191 offset:51200
	ds_read_b128 v[222:225], v191 offset:52224
	ds_read_b128 v[226:229], v191 offset:53248
	ds_read_b128 v[230:233], v191 offset:54272
	ds_read_b128 v[234:237], v191 offset:55296
	ds_read_b128 v[238:241], v191 offset:56320
	s_waitcnt vmcnt(8)
	s_waitcnt lgkmcnt(0)
	s_setprio 1
	s_barrier
	v_mfma_f32_16x16x32_bf16 v[62:65], v[130:133], v[210:213], v[62:65]
	v_mfma_f32_16x16x32_bf16 v[58:61], v[138:141], v[210:213], v[58:61]
	v_mfma_f32_16x16x32_bf16 v[46:49], v[130:133], v[218:221], v[46:49]
	v_mfma_f32_16x16x32_bf16 v[42:45], v[138:141], v[218:221], v[42:45]
	v_mfma_f32_16x16x32_bf16 v[30:33], v[130:133], v[226:229], v[30:33]
	v_mfma_f32_16x16x32_bf16 v[26:29], v[138:141], v[226:229], v[26:29]
	v_mfma_f32_16x16x32_bf16 v[14:17], v[130:133], v[234:237], v[14:17]
	v_mfma_f32_16x16x32_bf16 v[10:13], v[138:141], v[234:237], v[10:13]
	v_mfma_f32_16x16x32_bf16 v[62:65], v[134:137], v[214:217], v[62:65]
	v_mfma_f32_16x16x32_bf16 v[58:61], v[142:145], v[214:217], v[58:61]
	v_mfma_f32_16x16x32_bf16 v[46:49], v[134:137], v[222:225], v[46:49]
	v_mfma_f32_16x16x32_bf16 v[42:45], v[142:145], v[222:225], v[42:45]
	v_mfma_f32_16x16x32_bf16 v[30:33], v[134:137], v[230:233], v[30:33]
	v_mfma_f32_16x16x32_bf16 v[26:29], v[142:145], v[230:233], v[26:29]
	v_mfma_f32_16x16x32_bf16 v[14:17], v[134:137], v[238:241], v[14:17]
	v_mfma_f32_16x16x32_bf16 v[10:13], v[142:145], v[238:241], v[10:13]
	s_setprio 0
	s_setprio 1
	v_mfma_f32_16x16x32_bf16 v[54:57], v[158:161], v[210:213], v[54:57]
	v_mfma_f32_16x16x32_bf16 v[50:53], v[196:199], v[210:213], v[50:53]
	v_mfma_f32_16x16x32_bf16 v[38:41], v[158:161], v[218:221], v[38:41]
	v_mfma_f32_16x16x32_bf16 v[34:37], v[196:199], v[218:221], v[34:37]
	v_mfma_f32_16x16x32_bf16 v[22:25], v[158:161], v[226:229], v[22:25]
	v_mfma_f32_16x16x32_bf16 v[18:21], v[196:199], v[226:229], v[18:21]
	v_mfma_f32_16x16x32_bf16 v[6:9], v[158:161], v[234:237], v[6:9]
	v_mfma_f32_16x16x32_bf16 v[2:5], v[196:199], v[234:237], v[2:5]
	v_mfma_f32_16x16x32_bf16 v[54:57], v[192:195], v[214:217], v[54:57]
	v_mfma_f32_16x16x32_bf16 v[50:53], v[200:203], v[214:217], v[50:53]
	v_mfma_f32_16x16x32_bf16 v[38:41], v[192:195], v[222:225], v[38:41]
	v_mfma_f32_16x16x32_bf16 v[34:37], v[200:203], v[222:225], v[34:37]
	v_mfma_f32_16x16x32_bf16 v[22:25], v[192:195], v[230:233], v[22:25]
	v_mfma_f32_16x16x32_bf16 v[18:21], v[200:203], v[230:233], v[18:21]
	v_mfma_f32_16x16x32_bf16 v[6:9], v[192:195], v[238:241], v[6:9]
	v_mfma_f32_16x16x32_bf16 v[2:5], v[200:203], v[238:241], v[2:5]
	s_barrier
	s_setprio 0
	s_add_i32 vcc_lo, vcc_lo, 2
	s_add_u32 s66, s66, 0x100
	s_addc_u32 s67, s67, 0
	s_add_u32 s92, s92, 0x100
	s_addc_u32 s93, s93, 0
	s_cmp_gt_u32 vcc_lo, 13
	s_cbranch_scc0 .LBB0_1333
	s_and_b64 vcc, exec, s[6:7]
	s_cbranch_vccz .LBB0_1336
	s_barrier

; #define PG8_STAGE(bufoff, gbase, voff) do { _Pragma("unroll") for (int _i = 0; _i < 2; ++_i) \
;         __builtin_amdgcn_global_load_lds((const unsigned*)((const char*)(gbase) + (voff)[_i]), (LAS unsigned*)(lds + (bufoff) + ldsw + _i * 8192), 16, 0, 0); } while (0)
; #define PG8_LDA(dst, b, h) do { _Pragma("unroll") for (int m = 0; m < 4; ++m) _Pragma("unroll") for (int k = 0; k < 2; ++k) dst[m][k] = *(const LAS bf16x8*)(lds + PG8_SA(b, h) + aoff + m * 2048 + k * 1024); } while (0)
; #define PG8_LDB(dst, b, h) do { _Pragma("unroll") for (int n = 0; n < 2; ++n) _Pragma("unroll") for (int k = 0; k < 2; ++k) dst[n][k] = *(const LAS bf16x8*)(lds + PG8_SB(b, h) + boff + n * 2048 + k * 1024); } while (0)
; #define PG8_MMA(ai, bj, At, Bt) do { __builtin_amdgcn_s_setprio(1); _Pragma("unroll") for (int m = 0; m < 4; ++m) _Pragma("unroll") for (int n = 0; n < 2; ++n) _Pragma("unroll") for (int k = 0; k < 2; ++k) \
;         acc[ai][bj][m][n] = __builtin_amdgcn_mfma_f32_16x16x32_bf16(Bt[n][k], At[m][k], acc[ai][bj][m][n], 0, 0, 0); __builtin_amdgcn_s_setprio(0); } while (0)
; #define PG8_WAIT_V(n) asm volatile("s_waitcnt vmcnt(" #n ")" ::: "memory")
; #define PG8_WAIT_L(n) asm volatile("s_waitcnt lgkmcnt(" #n ")" ::: "memory")
; #define PG8_BAR __builtin_amdgcn_s_barrier()
; #define PG8_SCHED __builtin_amdgcn_sched_barrier(0)
; template <class Epi>
; __device__ __forceinline__ void gemm_phase(LAS unsigned char* lds, const int tid, const Gemm g, const StaticOrder& S, const Epi& E) {
;     ...
;         for (int t = 0; t < nt; t += 2) {
;             const bool last = (t == nt - 2);
;             const char* a1 = cA + (size_t)(t + 1) * kstep;
;             const char* a2 = last ? nA : cA + (size_t)(t + 2) * kstep; const char* b2 = last ? nB : cB + (size_t)(t + 2) * kstep;
;             const char* a3 = a2 + kstep; const char* b3 = b2 + kstep;
;             PG8_LDB(B0, 0, 0); PG8_LDB(B1, 0, 1); PG8_SCHED; PG8_LDA(At, 0, 0); PG8_STAGE(PG8_SA(1, 1), a1 + hstepA, voffA);
;             PG8_WAIT_V(8); PG8_WAIT_L(0); PG8_BAR; PG8_MMA(0, 0, At, B0); PG8_MMA(0, 1, At, B1); PG8_BAR; PG8_SCHED;
;             PG8_LDA(At, 0, 1); PG8_STAGE(PG8_SB(0, 0), b2, voffB); PG8_STAGE(PG8_SB(0, 1), b2 + hstepB, voffB); PG8_STAGE(PG8_SA(0, 0), a2, voffA);
;             PG8_WAIT_V(8); PG8_WAIT_L(0); PG8_BAR; PG8_MMA(1, 0, At, B0); PG8_MMA(1, 1, At, B1); PG8_BAR; PG8_SCHED;
.LBB0_1487:
	s_add_u32 s27, s68, 0xfffc0080
	s_addc_u32 s30, s69, -1
	s_add_i32 s62, 0, 0x10000
	s_cmp_eq_u32 s26, 12
	s_cselect_b32 vcc_hi, s28, s30
	s_cselect_b32 vcc_lo, s71, s27
	s_cselect_b32 s31, s5, s83
	s_cselect_b32 s30, s73, s75
	s_add_i32 s27, 0, 0x14000
	v_add_u32_e32 v142, s62, v216
	v_add_u32_e32 v158, s27, v216
	ds_read_b128 v[130:133], v142
	ds_read_b128 v[134:137], v142 offset:1024
	ds_read_b128 v[138:141], v142 offset:2048
	ds_read_b128 v[142:145], v142 offset:3072
	ds_read_b128 v[146:149], v158
	ds_read_b128 v[150:153], v158 offset:1024
	ds_read_b128 v[154:157], v158 offset:2048
	ds_read_b128 v[158:161], v158 offset:3072
	v_lshl_add_u64 v[162:163], s[68:69], 0, v[176:177]
	s_add_i32 m0, s1, 0xc000
	s_nop 0
	global_load_lds_dwordx4 v[162:163], off
	v_lshl_add_u64 v[162:163], s[68:69], 0, v[178:179]
	s_add_i32 m0, s1, 0xe000
	s_nop 0
	global_load_lds_dwordx4 v[162:163], off
	ds_read_b128 v[180:183], v218
	ds_read_b128 v[184:187], v218 offset:1024
	ds_read_b128 v[220:223], v218 offset:2048
	ds_read_b128 v[224:227], v218 offset:3072
	ds_read_b128 v[228:231], v218 offset:4096
	ds_read_b128 v[232:235], v218 offset:5120
	ds_read_b128 v[236:239], v218 offset:6144
	ds_read_b128 v[240:243], v218 offset:7168
	s_waitcnt vmcnt(8)
	s_waitcnt lgkmcnt(0)
	s_setprio 1
	s_barrier
	v_mfma_f32_16x16x32_bf16 v[126:129], v[130:133], v[180:183], v[126:129]
	v_mfma_f32_16x16x32_bf16 v[122:125], v[138:141], v[180:183], v[122:125]
	v_mfma_f32_16x16x32_bf16 v[110:113], v[130:133], v[220:223], v[110:113]
	v_mfma_f32_16x16x32_bf16 v[106:109], v[138:141], v[220:223], v[106:109]
	v_mfma_f32_16x16x32_bf16 v[94:97], v[130:133], v[228:231], v[94:97]
	v_mfma_f32_16x16x32_bf16 v[90:93], v[138:141], v[228:231], v[90:93]
	v_mfma_f32_16x16x32_bf16 v[78:81], v[130:133], v[236:239], v[78:81]
	v_mfma_f32_16x16x32_bf16 v[74:77], v[138:141], v[236:239], v[74:77]
	v_mfma_f32_16x16x32_bf16 v[126:129], v[134:137], v[184:187], v[126:129]
	v_mfma_f32_16x16x32_bf16 v[122:125], v[142:145], v[184:187], v[122:125]
	v_mfma_f32_16x16x32_bf16 v[110:113], v[134:137], v[224:227], v[110:113]
	v_mfma_f32_16x16x32_bf16 v[106:109], v[142:145], v[224:227], v[106:109]
	v_mfma_f32_16x16x32_bf16 v[94:97], v[134:137], v[232:235], v[94:97]
	v_mfma_f32_16x16x32_bf16 v[90:93], v[142:145], v[232:235], v[90:93]
	v_mfma_f32_16x16x32_bf16 v[78:81], v[134:137], v[240:243], v[78:81]
	v_mfma_f32_16x16x32_bf16 v[74:77], v[142:145], v[240:243], v[74:77]
	s_setprio 0
	s_setprio 1
	v_mfma_f32_16x16x32_bf16 v[118:121], v[146:149], v[180:183], v[118:121]
	v_mfma_f32_16x16x32_bf16 v[114:117], v[154:157], v[180:183], v[114:117]
	v_mfma_f32_16x16x32_bf16 v[102:105], v[146:149], v[220:223], v[102:105]
	v_mfma_f32_16x16x32_bf16 v[98:101], v[154:157], v[220:223], v[98:101]
	v_mfma_f32_16x16x32_bf16 v[86:89], v[146:149], v[228:231], v[86:89]
	v_mfma_f32_16x16x32_bf16 v[82:85], v[154:157], v[228:231], v[82:85]
	v_mfma_f32_16x16x32_bf16 v[70:73], v[146:149], v[236:239], v[70:73]
	v_mfma_f32_16x16x32_bf16 v[66:69], v[154:157], v[236:239], v[66:69]
	v_mfma_f32_16x16x32_bf16 v[118:121], v[150:153], v[184:187], v[118:121]
	v_mfma_f32_16x16x32_bf16 v[114:117], v[158:161], v[184:187], v[114:117]
	v_mfma_f32_16x16x32_bf16 v[102:105], v[150:153], v[224:227], v[102:105]
	v_mfma_f32_16x16x32_bf16 v[98:101], v[158:161], v[224:227], v[98:101]
	v_mfma_f32_16x16x32_bf16 v[86:89], v[150:153], v[232:235], v[86:89]
	v_mfma_f32_16x16x32_bf16 v[82:85], v[158:161], v[232:235], v[82:85]
	v_mfma_f32_16x16x32_bf16 v[70:73], v[150:153], v[240:243], v[70:73]
	v_mfma_f32_16x16x32_bf16 v[66:69], v[158:161], v[240:243], v[66:69]
	s_barrier
	s_setprio 0
	s_add_i32 s62, s62, s0
	v_lshl_add_u64 v[162:163], s[30:31], 0, v[0:1]
	s_mov_b32 m0, s62
	s_nop 0
	global_load_lds_dwordx4 v[162:163], off
	s_add_i32 m0, s62, 0x2000
	s_add_u32 s62, s30, 0x40000
	v_lshl_add_u64 v[164:165], s[30:31], 0, v[170:171]
	s_addc_u32 s63, s31, 0
	s_add_i32 s27, s27, s0
	global_load_lds_dwordx4 v[164:165], off
	v_lshl_add_u64 v[206:207], s[62:63], 0, v[0:1]
	s_mov_b32 m0, s27
	v_lshl_add_u64 v[244:245], vcc, 0, v[174:175]
	global_load_lds_dwordx4 v[206:207], off
	v_lshl_add_u64 v[206:207], s[62:63], 0, v[170:171]
	s_add_i32 m0, s27, 0x2000
	s_nop 0
	global_load_lds_dwordx4 v[206:207], off
	v_lshl_add_u64 v[206:207], vcc, 0, v[172:173]
	s_mov_b32 m0, s1
	s_nop 0
	global_load_lds_dwordx4 v[206:207], off
	s_mov_b32 m0, s2
	s_nop 0
	global_load_lds_dwordx4 v[244:245], off
	ds_read_b128 v[180:183], v218 offset:16384
	ds_read_b128 v[184:187], v218 offset:17408
	ds_read_b128 v[220:223], v218 offset:18432
	ds_read_b128 v[224:227], v218 offset:19456
	ds_read_b128 v[228:231], v218 offset:20480
	ds_read_b128 v[232:235], v218 offset:21504
	ds_read_b128 v[236:239], v218 offset:22528
	ds_read_b128 v[240:243], v218 offset:23552
	s_waitcnt vmcnt(8)
	s_waitcnt lgkmcnt(0)
	s_setprio 1
	s_barrier
; #define PG8_STAGE(bufoff, gbase, voff) do { _Pragma("unroll") for (int _i = 0; _i < 2; ++_i) \
;         __builtin_amdgcn_global_load_lds((const unsigned*)((const char*)(gbase) + (voff)[_i]), (LAS unsigned*)(lds + (bufoff) + ldsw + _i * 8192), 16, 0, 0); } while (0)
; #define PG8_LDA(dst, b, h) do { _Pragma("unroll") for (int m = 0; m < 4; ++m) _Pragma("unroll") for (int k = 0; k < 2; ++k) dst[m][k] = *(const LAS bf16x8*)(lds + PG8_SA(b, h) + aoff + m * 2048 + k * 1024); } while (0)
; #define PG8_LDB(dst, b, h) do { _Pragma("unroll") for (int n = 0; n < 2; ++n) _Pragma("unroll") for (int k = 0; k < 2; ++k) dst[n][k] = *(const LAS bf16x8*)(lds + PG8_SB(b, h) + boff + n * 2048 + k * 1024); } while (0)
; #define PG8_MMA(ai, bj, At, Bt) do { __builtin_amdgcn_s_setprio(1); _Pragma("unroll") for (int m = 0; m < 4; ++m) _Pragma("unroll") for (int n = 0; n < 2; ++n) _Pragma("unroll") for (int k = 0; k < 2; ++k) \
;         acc[ai][bj][m][n] = __builtin_amdgcn_mfma_f32_16x16x32_bf16(Bt[n][k], At[m][k], acc[ai][bj][m][n], 0, 0, 0); __builtin_amdgcn_s_setprio(0); } while (0)
; #define PG8_WAIT_V(n) asm volatile("s_waitcnt vmcnt(" #n ")" ::: "memory")
; #define PG8_WAIT_L(n) asm volatile("s_waitcnt lgkmcnt(" #n ")" ::: "memory")
; #define PG8_BAR __builtin_amdgcn_s_barrier()
; #define PG8_SCHED __builtin_amdgcn_sched_barrier(0)
; template <class Epi>
; __device__ __forceinline__ void gemm_phase(LAS unsigned char* lds, const int tid, const Gemm g, const StaticOrder& S, const Epi& E) {
;     ...
;             PG8_WAIT_V(8); PG8_WAIT_L(0); PG8_BAR; PG8_MMA(1, 0, At, B0); PG8_MMA(1, 1, At, B1); PG8_BAR; PG8_SCHED;
;             PG8_LDB(B0, 1, 0); PG8_LDB(B1, 1, 1); PG8_SCHED; PG8_LDA(At, 1, 0); PG8_STAGE(PG8_SA(0, 1), a2 + hstepA, voffA);
;             PG8_WAIT_V(8); PG8_WAIT_L(0); PG8_BAR; PG8_MMA(0, 0, At, B0); PG8_MMA(0, 1, At, B1); PG8_BAR; PG8_SCHED;
	v_mfma_f32_16x16x32_bf16 v[62:65], v[130:133], v[180:183], v[62:65]
	v_mfma_f32_16x16x32_bf16 v[58:61], v[138:141], v[180:183], v[58:61]
	v_mfma_f32_16x16x32_bf16 v[46:49], v[130:133], v[220:223], v[46:49]
	v_mfma_f32_16x16x32_bf16 v[42:45], v[138:141], v[220:223], v[42:45]
	v_mfma_f32_16x16x32_bf16 v[30:33], v[130:133], v[228:231], v[30:33]
	v_mfma_f32_16x16x32_bf16 v[26:29], v[138:141], v[228:231], v[26:29]
	v_mfma_f32_16x16x32_bf16 v[14:17], v[130:133], v[236:239], v[14:17]
	v_mfma_f32_16x16x32_bf16 v[10:13], v[138:141], v[236:239], v[10:13]
	v_mfma_f32_16x16x32_bf16 v[62:65], v[134:137], v[184:187], v[62:65]
	v_mfma_f32_16x16x32_bf16 v[58:61], v[142:145], v[184:187], v[58:61]
	v_mfma_f32_16x16x32_bf16 v[46:49], v[134:137], v[224:227], v[46:49]
	v_mfma_f32_16x16x32_bf16 v[42:45], v[142:145], v[224:227], v[42:45]
	v_mfma_f32_16x16x32_bf16 v[30:33], v[134:137], v[232:235], v[30:33]
	v_mfma_f32_16x16x32_bf16 v[26:29], v[142:145], v[232:235], v[26:29]
	v_mfma_f32_16x16x32_bf16 v[14:17], v[134:137], v[240:243], v[14:17]
	v_mfma_f32_16x16x32_bf16 v[10:13], v[142:145], v[240:243], v[10:13]
	s_setprio 0
	s_setprio 1
	v_mfma_f32_16x16x32_bf16 v[54:57], v[146:149], v[180:183], v[54:57]
	v_mfma_f32_16x16x32_bf16 v[50:53], v[154:157], v[180:183], v[50:53]
	v_mfma_f32_16x16x32_bf16 v[38:41], v[146:149], v[220:223], v[38:41]
	v_mfma_f32_16x16x32_bf16 v[34:37], v[154:157], v[220:223], v[34:37]
	v_mfma_f32_16x16x32_bf16 v[22:25], v[146:149], v[228:231], v[22:25]
	v_mfma_f32_16x16x32_bf16 v[18:21], v[154:157], v[228:231], v[18:21]
	v_mfma_f32_16x16x32_bf16 v[6:9], v[146:149], v[236:239], v[6:9]
	v_mfma_f32_16x16x32_bf16 v[2:5], v[154:157], v[236:239], v[2:5]
	v_mfma_f32_16x16x32_bf16 v[54:57], v[150:153], v[184:187], v[54:57]
	v_mfma_f32_16x16x32_bf16 v[50:53], v[158:161], v[184:187], v[50:53]
	v_mfma_f32_16x16x32_bf16 v[38:41], v[150:153], v[224:227], v[38:41]
	v_mfma_f32_16x16x32_bf16 v[34:37], v[158:161], v[224:227], v[34:37]
	v_mfma_f32_16x16x32_bf16 v[22:25], v[150:153], v[232:235], v[22:25]
	v_mfma_f32_16x16x32_bf16 v[18:21], v[158:161], v[232:235], v[18:21]
	v_mfma_f32_16x16x32_bf16 v[6:9], v[150:153], v[240:243], v[6:9]
	v_mfma_f32_16x16x32_bf16 v[2:5], v[158:161], v[240:243], v[2:5]
	s_barrier
	s_setprio 0
	s_add_i32 s27, 0, 0x18000
	s_add_i32 s17, 0, 0x1c000
	v_add_u32_e32 v142, s27, v216
	v_add_u32_e32 v158, s17, v216
	ds_read_b128 v[130:133], v142
	ds_read_b128 v[134:137], v142 offset:1024
	ds_read_b128 v[138:141], v142 offset:2048
	ds_read_b128 v[142:145], v142 offset:3072
	ds_read_b128 v[146:149], v158
	ds_read_b128 v[150:153], v158 offset:1024
	ds_read_b128 v[154:157], v158 offset:2048
	ds_read_b128 v[158:161], v158 offset:3072
	s_add_u32 s62, vcc_lo, 0x40000
	s_addc_u32 s63, vcc_hi, 0
	s_mov_b32 m0, s3
	v_lshl_add_u64 v[246:247], s[62:63], 0, v[172:173]
	global_load_lds_dwordx4 v[246:247], off
	v_lshl_add_u64 v[246:247], s[62:63], 0, v[174:175]
	s_mov_b32 m0, s16
	s_nop 0
	global_load_lds_dwordx4 v[246:247], off
	ds_read_b128 v[180:183], v218 offset:32768
	ds_read_b128 v[184:187], v218 offset:33792
	ds_read_b128 v[220:223], v218 offset:34816
	ds_read_b128 v[224:227], v218 offset:35840
	ds_read_b128 v[228:231], v218 offset:36864
	ds_read_b128 v[232:235], v218 offset:37888
	ds_read_b128 v[236:239], v218 offset:38912
	ds_read_b128 v[240:243], v218 offset:39936
	s_waitcnt vmcnt(8)
	s_waitcnt lgkmcnt(0)
	s_setprio 1
	s_barrier
	v_mfma_f32_16x16x32_bf16 v[126:129], v[130:133], v[180:183], v[126:129]
	v_mfma_f32_16x16x32_bf16 v[122:125], v[138:141], v[180:183], v[122:125]
	v_mfma_f32_16x16x32_bf16 v[110:113], v[130:133], v[220:223], v[110:113]
	v_mfma_f32_16x16x32_bf16 v[106:109], v[138:141], v[220:223], v[106:109]
	v_mfma_f32_16x16x32_bf16 v[94:97], v[130:133], v[228:231], v[94:97]
	v_mfma_f32_16x16x32_bf16 v[90:93], v[138:141], v[228:231], v[90:93]
	v_mfma_f32_16x16x32_bf16 v[78:81], v[130:133], v[236:239], v[78:81]
	v_mfma_f32_16x16x32_bf16 v[74:77], v[138:141], v[236:239], v[74:77]
	v_mfma_f32_16x16x32_bf16 v[126:129], v[134:137], v[184:187], v[126:129]
	v_mfma_f32_16x16x32_bf16 v[122:125], v[142:145], v[184:187], v[122:125]
	v_mfma_f32_16x16x32_bf16 v[110:113], v[134:137], v[224:227], v[110:113]
	v_mfma_f32_16x16x32_bf16 v[106:109], v[142:145], v[224:227], v[106:109]
	v_mfma_f32_16x16x32_bf16 v[94:97], v[134:137], v[232:235], v[94:97]
	v_mfma_f32_16x16x32_bf16 v[90:93], v[142:145], v[232:235], v[90:93]
	v_mfma_f32_16x16x32_bf16 v[78:81], v[134:137], v[240:243], v[78:81]
	v_mfma_f32_16x16x32_bf16 v[74:77], v[142:145], v[240:243], v[74:77]
	s_setprio 0
	s_setprio 1
	v_mfma_f32_16x16x32_bf16 v[118:121], v[146:149], v[180:183], v[118:121]
	v_mfma_f32_16x16x32_bf16 v[114:117], v[154:157], v[180:183], v[114:117]
	v_mfma_f32_16x16x32_bf16 v[102:105], v[146:149], v[220:223], v[102:105]
	v_mfma_f32_16x16x32_bf16 v[98:101], v[154:157], v[220:223], v[98:101]
	v_mfma_f32_16x16x32_bf16 v[86:89], v[146:149], v[228:231], v[86:89]
	v_mfma_f32_16x16x32_bf16 v[82:85], v[154:157], v[228:231], v[82:85]
	v_mfma_f32_16x16x32_bf16 v[70:73], v[146:149], v[236:239], v[70:73]
	v_mfma_f32_16x16x32_bf16 v[66:69], v[154:157], v[236:239], v[66:69]
	v_mfma_f32_16x16x32_bf16 v[118:121], v[150:153], v[184:187], v[118:121]
	v_mfma_f32_16x16x32_bf16 v[114:117], v[158:161], v[184:187], v[114:117]
	v_mfma_f32_16x16x32_bf16 v[102:105], v[150:153], v[224:227], v[102:105]
	v_mfma_f32_16x16x32_bf16 v[98:101], v[158:161], v[224:227], v[98:101]
	v_mfma_f32_16x16x32_bf16 v[86:89], v[150:153], v[232:235], v[86:89]
	v_mfma_f32_16x16x32_bf16 v[82:85], v[158:161], v[232:235], v[82:85]
	v_mfma_f32_16x16x32_bf16 v[70:73], v[150:153], v[240:243], v[70:73]
	v_mfma_f32_16x16x32_bf16 v[66:69], v[158:161], v[240:243], v[66:69]
	s_barrier
; #define PG8_STAGE(bufoff, gbase, voff) do { _Pragma("unroll") for (int _i = 0; _i < 2; ++_i) \
;         __builtin_amdgcn_global_load_lds((const unsigned*)((const char*)(gbase) + (voff)[_i]), (LAS unsigned*)(lds + (bufoff) + ldsw + _i * 8192), 16, 0, 0); } while (0)
; #define PG8_LDA(dst, b, h) do { _Pragma("unroll") for (int m = 0; m < 4; ++m) _Pragma("unroll") for (int k = 0; k < 2; ++k) dst[m][k] = *(const LAS bf16x8*)(lds + PG8_SA(b, h) + aoff + m * 2048 + k * 1024); } while (0)
; #define PG8_MMA(ai, bj, At, Bt) do { __builtin_amdgcn_s_setprio(1); _Pragma("unroll") for (int m = 0; m < 4; ++m) _Pragma("unroll") for (int n = 0; n < 2; ++n) _Pragma("unroll") for (int k = 0; k < 2; ++k) \
;         acc[ai][bj][m][n] = __builtin_amdgcn_mfma_f32_16x16x32_bf16(Bt[n][k], At[m][k], acc[ai][bj][m][n], 0, 0, 0); __builtin_amdgcn_s_setprio(0); } while (0)
; #define PG8_WAIT_V(n) asm volatile("s_waitcnt vmcnt(" #n ")" ::: "memory")
; #define PG8_WAIT_L(n) asm volatile("s_waitcnt lgkmcnt(" #n ")" ::: "memory")
; #define PG8_BAR __builtin_amdgcn_s_barrier()
; #define PG8_SCHED __builtin_amdgcn_sched_barrier(0)
; template <class Epi>
; __device__ __forceinline__ void gemm_phase(LAS unsigned char* lds, const int tid, const Gemm g, const StaticOrder& S, const Epi& E) {
;     ...
;             PG8_WAIT_V(8); PG8_WAIT_L(0); PG8_BAR; PG8_MMA(0, 0, At, B0); PG8_MMA(0, 1, At, B1); PG8_BAR; PG8_SCHED;
;             PG8_LDA(At, 1, 1); PG8_STAGE(PG8_SB(1, 0), b3, voffB); PG8_STAGE(PG8_SB(1, 1), b3 + hstepB, voffB); PG8_STAGE(PG8_SA(1, 0), a3, voffA);
;             PG8_WAIT_V(8); PG8_WAIT_L(0); PG8_BAR; PG8_MMA(1, 0, At, B0); PG8_MMA(1, 1, At, B1); PG8_BAR; PG8_SCHED;
;         }
;         if (wr == 0) PG8_BAR;
	s_setprio 0
	s_add_i32 s27, s27, s0
	v_lshl_add_u64 v[162:163], v[162:163], 0, s[36:37]
	s_mov_b32 m0, s27
	s_nop 0
	global_load_lds_dwordx4 v[162:163], off
	s_add_i32 m0, s27, 0x2000
	s_add_u32 s30, s30, 0x40080
	v_lshl_add_u64 v[162:163], v[164:165], 0, s[36:37]
	s_addc_u32 s31, s31, 0
	s_add_i32 s17, s17, s0
	global_load_lds_dwordx4 v[162:163], off
	v_lshl_add_u64 v[162:163], s[30:31], 0, v[0:1]
	s_mov_b32 m0, s17
	s_nop 0
	global_load_lds_dwordx4 v[162:163], off
	v_lshl_add_u64 v[162:163], s[30:31], 0, v[170:171]
	s_add_i32 m0, s17, 0x2000
	s_nop 0
	global_load_lds_dwordx4 v[162:163], off
	v_lshl_add_u64 v[162:163], v[206:207], 0, s[36:37]
	s_mov_b32 m0, s10
	s_nop 0
	global_load_lds_dwordx4 v[162:163], off
	v_lshl_add_u64 v[162:163], v[244:245], 0, s[36:37]
	s_mov_b32 m0, s11
	s_nop 0
	global_load_lds_dwordx4 v[162:163], off
	ds_read_b128 v[180:183], v218 offset:49152
	ds_read_b128 v[184:187], v218 offset:50176
	ds_read_b128 v[220:223], v218 offset:51200
	ds_read_b128 v[224:227], v218 offset:52224
	ds_read_b128 v[228:231], v218 offset:53248
	ds_read_b128 v[232:235], v218 offset:54272
	ds_read_b128 v[236:239], v218 offset:55296
	ds_read_b128 v[240:243], v218 offset:56320
	s_waitcnt vmcnt(8)
	s_waitcnt lgkmcnt(0)
	s_setprio 1
	s_barrier
	v_mfma_f32_16x16x32_bf16 v[62:65], v[130:133], v[180:183], v[62:65]
	v_mfma_f32_16x16x32_bf16 v[58:61], v[138:141], v[180:183], v[58:61]
	v_mfma_f32_16x16x32_bf16 v[46:49], v[130:133], v[220:223], v[46:49]
	v_mfma_f32_16x16x32_bf16 v[42:45], v[138:141], v[220:223], v[42:45]
	v_mfma_f32_16x16x32_bf16 v[30:33], v[130:133], v[228:231], v[30:33]
	v_mfma_f32_16x16x32_bf16 v[26:29], v[138:141], v[228:231], v[26:29]
	v_mfma_f32_16x16x32_bf16 v[14:17], v[130:133], v[236:239], v[14:17]
	v_mfma_f32_16x16x32_bf16 v[10:13], v[138:141], v[236:239], v[10:13]
	v_mfma_f32_16x16x32_bf16 v[62:65], v[134:137], v[184:187], v[62:65]
	v_mfma_f32_16x16x32_bf16 v[58:61], v[142:145], v[184:187], v[58:61]
	v_mfma_f32_16x16x32_bf16 v[46:49], v[134:137], v[224:227], v[46:49]
	v_mfma_f32_16x16x32_bf16 v[42:45], v[142:145], v[224:227], v[42:45]
	v_mfma_f32_16x16x32_bf16 v[30:33], v[134:137], v[232:235], v[30:33]
	v_mfma_f32_16x16x32_bf16 v[26:29], v[142:145], v[232:235], v[26:29]
	v_mfma_f32_16x16x32_bf16 v[14:17], v[134:137], v[240:243], v[14:17]
	v_mfma_f32_16x16x32_bf16 v[10:13], v[142:145], v[240:243], v[10:13]
	s_setprio 0
	s_setprio 1
	v_mfma_f32_16x16x32_bf16 v[54:57], v[146:149], v[180:183], v[54:57]
	v_mfma_f32_16x16x32_bf16 v[50:53], v[154:157], v[180:183], v[50:53]
	v_mfma_f32_16x16x32_bf16 v[38:41], v[146:149], v[220:223], v[38:41]
	v_mfma_f32_16x16x32_bf16 v[34:37], v[154:157], v[220:223], v[34:37]
	v_mfma_f32_16x16x32_bf16 v[22:25], v[146:149], v[228:231], v[22:25]
	v_mfma_f32_16x16x32_bf16 v[18:21], v[154:157], v[228:231], v[18:21]
	v_mfma_f32_16x16x32_bf16 v[6:9], v[146:149], v[236:239], v[6:9]
	v_mfma_f32_16x16x32_bf16 v[2:5], v[154:157], v[236:239], v[2:5]
	v_mfma_f32_16x16x32_bf16 v[54:57], v[150:153], v[184:187], v[54:57]
	v_mfma_f32_16x16x32_bf16 v[50:53], v[158:161], v[184:187], v[50:53]
	v_mfma_f32_16x16x32_bf16 v[38:41], v[150:153], v[224:227], v[38:41]
	v_mfma_f32_16x16x32_bf16 v[34:37], v[158:161], v[224:227], v[34:37]
	v_mfma_f32_16x16x32_bf16 v[22:25], v[150:153], v[232:235], v[22:25]
	v_mfma_f32_16x16x32_bf16 v[18:21], v[158:161], v[232:235], v[18:21]
	v_mfma_f32_16x16x32_bf16 v[6:9], v[150:153], v[240:243], v[6:9]
	v_mfma_f32_16x16x32_bf16 v[2:5], v[158:161], v[240:243], v[2:5]
	s_barrier
	s_setprio 0
	s_add_i32 s26, s26, 2
	s_add_u32 s68, s68, 0x100
	s_addc_u32 s69, s69, 0
	s_add_u32 s75, s75, 0x100
	s_addc_u32 s83, s83, 0
	s_cmp_gt_u32 s26, 13
	s_cbranch_scc0 .LBB0_1487
	v_readlane_b32 s26, v255, 55
	v_readlane_b32 s27, v255, 56
	s_and_b64 vcc, exec, s[26:27]
	s_cbranch_vccz .LBB0_1490
	s_barrier

; #define PG8_STAGE(bufoff, gbase, voff) do { _Pragma("unroll") for (int _i = 0; _i < 2; ++_i) \
;         __builtin_amdgcn_global_load_lds((const unsigned*)((const char*)(gbase) + (voff)[_i]), (LAS unsigned*)(lds + (bufoff) + ldsw + _i * 8192), 16, 0, 0); } while (0)
; #define PG8_LDA(dst, b, h) do { _Pragma("unroll") for (int m = 0; m < 4; ++m) _Pragma("unroll") for (int k = 0; k < 2; ++k) dst[m][k] = *(const LAS bf16x8*)(lds + PG8_SA(b, h) + aoff + m * 2048 + k * 1024); } while (0)
; #define PG8_LDB(dst, b, h) do { _Pragma("unroll") for (int n = 0; n < 2; ++n) _Pragma("unroll") for (int k = 0; k < 2; ++k) dst[n][k] = *(const LAS bf16x8*)(lds + PG8_SB(b, h) + boff + n * 2048 + k * 1024); } while (0)
; #define PG8_MMA(ai, bj, At, Bt) do { __builtin_amdgcn_s_setprio(1); _Pragma("unroll") for (int m = 0; m < 4; ++m) _Pragma("unroll") for (int n = 0; n < 2; ++n) _Pragma("unroll") for (int k = 0; k < 2; ++k) \
;         acc[ai][bj][m][n] = __builtin_amdgcn_mfma_f32_16x16x32_bf16(Bt[n][k], At[m][k], acc[ai][bj][m][n], 0, 0, 0); __builtin_amdgcn_s_setprio(0); } while (0)
; #define PG8_WAIT_V(n) asm volatile("s_waitcnt vmcnt(" #n ")" ::: "memory")
; #define PG8_WAIT_L(n) asm volatile("s_waitcnt lgkmcnt(" #n ")" ::: "memory")
; #define PG8_BAR __builtin_amdgcn_s_barrier()
; #define PG8_SCHED __builtin_amdgcn_sched_barrier(0)
; template <class Epi>
; __device__ __forceinline__ void gemm_phase(LAS unsigned char* lds, const int tid, const Gemm g, const StaticOrder& S, const Epi& E) {
;     ...
;         for (int t = 0; t < nt; t += 2) {
;             const bool last = (t == nt - 2);
;             const char* a1 = cA + (size_t)(t + 1) * kstep;
;             const char* a2 = last ? nA : cA + (size_t)(t + 2) * kstep; const char* b2 = last ? nB : cB + (size_t)(t + 2) * kstep;
;             const char* a3 = a2 + kstep; const char* b3 = b2 + kstep;
;             PG8_LDB(B0, 0, 0); PG8_LDB(B1, 0, 1); PG8_SCHED; PG8_LDA(At, 0, 0); PG8_STAGE(PG8_SA(1, 1), a1 + hstepA, voffA);
;             PG8_WAIT_V(8); PG8_WAIT_L(0); PG8_BAR; PG8_MMA(0, 0, At, B0); PG8_MMA(0, 1, At, B1); PG8_BAR; PG8_SCHED;
;             PG8_LDA(At, 0, 1); PG8_STAGE(PG8_SB(0, 0), b2, voffB); PG8_STAGE(PG8_SB(0, 1), b2 + hstepB, voffB); PG8_STAGE(PG8_SA(0, 0), a2, voffA);
;             PG8_WAIT_V(8); PG8_WAIT_L(0); PG8_BAR; PG8_MMA(1, 0, At, B0); PG8_MMA(1, 1, At, B1); PG8_BAR; PG8_SCHED;
.LBB0_1912:
	s_add_u32 s30, s82, 0xfffc0080
	s_addc_u32 s31, s83, -1
	s_add_i32 s92, 0, 0x10000
	s_cmp_eq_u32 s17, 12
	s_cselect_b32 s89, s7, s31
	s_cselect_b32 s88, s65, s30
	s_cselect_b32 s31, s5, s27
	s_cselect_b32 s30, vcc_lo, vcc_hi
	s_add_i32 s11, 0, 0x14000
	v_add_u32_e32 v110, s92, v158
	v_add_u32_e32 v162, s11, v158
	ds_read_b128 v[98:101], v110
	ds_read_b128 v[102:105], v110 offset:1024
	ds_read_b128 v[106:109], v110 offset:2048
	ds_read_b128 v[110:113], v110 offset:3072
	ds_read_b128 v[174:177], v162
	ds_read_b128 v[178:181], v162 offset:1024
	ds_read_b128 v[182:185], v162 offset:2048
	ds_read_b128 v[186:189], v162 offset:3072
	v_lshl_add_u64 v[162:163], s[82:83], 0, v[152:153]
	s_add_i32 m0, s66, 0xc000
	s_nop 0
	global_load_lds_dwordx4 v[162:163], off
	v_lshl_add_u64 v[162:163], s[82:83], 0, v[154:155]
	s_add_i32 m0, s66, 0xe000
	s_nop 0
	global_load_lds_dwordx4 v[162:163], off
	ds_read_b128 v[190:193], v172
	ds_read_b128 v[194:197], v172 offset:1024
	ds_read_b128 v[198:201], v172 offset:2048
	ds_read_b128 v[210:213], v172 offset:3072
	ds_read_b128 v[214:217], v172 offset:4096
	ds_read_b128 v[218:221], v172 offset:5120
	ds_read_b128 v[222:225], v172 offset:6144
	ds_read_b128 v[226:229], v172 offset:7168
	s_waitcnt vmcnt(8)
	s_waitcnt lgkmcnt(0)
	s_setprio 1
	s_barrier
	v_mfma_f32_16x16x32_bf16 v[142:145], v[98:101], v[190:193], v[142:145]
	v_mfma_f32_16x16x32_bf16 v[138:141], v[106:109], v[190:193], v[138:141]
	v_mfma_f32_16x16x32_bf16 v[134:137], v[98:101], v[198:201], v[134:137]
	v_mfma_f32_16x16x32_bf16 v[130:133], v[106:109], v[198:201], v[130:133]
	v_mfma_f32_16x16x32_bf16 v[94:97], v[98:101], v[214:217], v[94:97]
	v_mfma_f32_16x16x32_bf16 v[90:93], v[106:109], v[214:217], v[90:93]
	v_mfma_f32_16x16x32_bf16 v[78:81], v[98:101], v[222:225], v[78:81]
	v_mfma_f32_16x16x32_bf16 v[74:77], v[106:109], v[222:225], v[74:77]
	v_mfma_f32_16x16x32_bf16 v[142:145], v[102:105], v[194:197], v[142:145]
	v_mfma_f32_16x16x32_bf16 v[138:141], v[110:113], v[194:197], v[138:141]
	v_mfma_f32_16x16x32_bf16 v[134:137], v[102:105], v[210:213], v[134:137]
	v_mfma_f32_16x16x32_bf16 v[130:133], v[110:113], v[210:213], v[130:133]
	v_mfma_f32_16x16x32_bf16 v[94:97], v[102:105], v[218:221], v[94:97]
	v_mfma_f32_16x16x32_bf16 v[90:93], v[110:113], v[218:221], v[90:93]
	v_mfma_f32_16x16x32_bf16 v[78:81], v[102:105], v[226:229], v[78:81]
	v_mfma_f32_16x16x32_bf16 v[74:77], v[110:113], v[226:229], v[74:77]
	s_setprio 0
	s_setprio 1
	v_mfma_f32_16x16x32_bf16 v[126:129], v[174:177], v[190:193], v[126:129]
	v_mfma_f32_16x16x32_bf16 v[122:125], v[182:185], v[190:193], v[122:125]
	v_mfma_f32_16x16x32_bf16 v[118:121], v[174:177], v[198:201], v[118:121]
	v_mfma_f32_16x16x32_bf16 v[114:117], v[182:185], v[198:201], v[114:117]
	v_mfma_f32_16x16x32_bf16 v[86:89], v[174:177], v[214:217], v[86:89]
	v_mfma_f32_16x16x32_bf16 v[82:85], v[182:185], v[214:217], v[82:85]
	v_mfma_f32_16x16x32_bf16 v[70:73], v[174:177], v[222:225], v[70:73]
	v_mfma_f32_16x16x32_bf16 v[66:69], v[182:185], v[222:225], v[66:69]
	v_mfma_f32_16x16x32_bf16 v[126:129], v[178:181], v[194:197], v[126:129]
	v_mfma_f32_16x16x32_bf16 v[122:125], v[186:189], v[194:197], v[122:125]
	v_mfma_f32_16x16x32_bf16 v[118:121], v[178:181], v[210:213], v[118:121]
	v_mfma_f32_16x16x32_bf16 v[114:117], v[186:189], v[210:213], v[114:117]
	v_mfma_f32_16x16x32_bf16 v[86:89], v[178:181], v[218:221], v[86:89]
	v_mfma_f32_16x16x32_bf16 v[82:85], v[186:189], v[218:221], v[82:85]
	v_mfma_f32_16x16x32_bf16 v[70:73], v[178:181], v[226:229], v[70:73]
	v_mfma_f32_16x16x32_bf16 v[66:69], v[186:189], v[226:229], v[66:69]
	s_barrier
	s_setprio 0
	s_add_i32 s92, s92, s28
	v_lshl_add_u64 v[162:163], s[30:31], 0, v[0:1]
	s_mov_b32 m0, s92
	s_nop 0
	global_load_lds_dwordx4 v[162:163], off
	s_add_i32 m0, s92, 0x2000
	s_add_u32 s92, s30, 0x40000
	v_lshl_add_u64 v[164:165], s[30:31], 0, v[146:147]
	s_addc_u32 s93, s31, 0
	s_add_i32 s11, s11, s28
	global_load_lds_dwordx4 v[164:165], off
	v_lshl_add_u64 v[202:203], s[92:93], 0, v[0:1]
	s_mov_b32 m0, s11
	v_lshl_add_u64 v[206:207], s[88:89], 0, v[148:149]
	global_load_lds_dwordx4 v[202:203], off
	v_lshl_add_u64 v[202:203], s[92:93], 0, v[146:147]
	s_add_i32 m0, s11, 0x2000
	s_nop 0
	global_load_lds_dwordx4 v[202:203], off
	v_lshl_add_u64 v[202:203], s[88:89], 0, v[150:151]
	s_mov_b32 m0, s66
	s_nop 0
	global_load_lds_dwordx4 v[202:203], off
	s_mov_b32 m0, s67
	s_nop 0
	global_load_lds_dwordx4 v[206:207], off
	ds_read_b128 v[190:193], v172 offset:16384
	ds_read_b128 v[194:197], v172 offset:17408
	ds_read_b128 v[198:201], v172 offset:18432
	ds_read_b128 v[210:213], v172 offset:19456
	ds_read_b128 v[214:217], v172 offset:20480
	ds_read_b128 v[218:221], v172 offset:21504
	ds_read_b128 v[222:225], v172 offset:22528
	ds_read_b128 v[226:229], v172 offset:23552
	s_waitcnt vmcnt(8)
	s_waitcnt lgkmcnt(0)
	s_setprio 1
	s_barrier
; #define PG8_STAGE(bufoff, gbase, voff) do { _Pragma("unroll") for (int _i = 0; _i < 2; ++_i) \
;         __builtin_amdgcn_global_load_lds((const unsigned*)((const char*)(gbase) + (voff)[_i]), (LAS unsigned*)(lds + (bufoff) + ldsw + _i * 8192), 16, 0, 0); } while (0)
; #define PG8_LDA(dst, b, h) do { _Pragma("unroll") for (int m = 0; m < 4; ++m) _Pragma("unroll") for (int k = 0; k < 2; ++k) dst[m][k] = *(const LAS bf16x8*)(lds + PG8_SA(b, h) + aoff + m * 2048 + k * 1024); } while (0)
; #define PG8_LDB(dst, b, h) do { _Pragma("unroll") for (int n = 0; n < 2; ++n) _Pragma("unroll") for (int k = 0; k < 2; ++k) dst[n][k] = *(const LAS bf16x8*)(lds + PG8_SB(b, h) + boff + n * 2048 + k * 1024); } while (0)
; #define PG8_MMA(ai, bj, At, Bt) do { __builtin_amdgcn_s_setprio(1); _Pragma("unroll") for (int m = 0; m < 4; ++m) _Pragma("unroll") for (int n = 0; n < 2; ++n) _Pragma("unroll") for (int k = 0; k < 2; ++k) \
;         acc[ai][bj][m][n] = __builtin_amdgcn_mfma_f32_16x16x32_bf16(Bt[n][k], At[m][k], acc[ai][bj][m][n], 0, 0, 0); __builtin_amdgcn_s_setprio(0); } while (0)
; #define PG8_WAIT_V(n) asm volatile("s_waitcnt vmcnt(" #n ")" ::: "memory")
; #define PG8_WAIT_L(n) asm volatile("s_waitcnt lgkmcnt(" #n ")" ::: "memory")
; #define PG8_BAR __builtin_amdgcn_s_barrier()
; #define PG8_SCHED __builtin_amdgcn_sched_barrier(0)
; template <class Epi>
; __device__ __forceinline__ void gemm_phase(LAS unsigned char* lds, const int tid, const Gemm g, const StaticOrder& S, const Epi& E) {
;     ...
;             PG8_WAIT_V(8); PG8_WAIT_L(0); PG8_BAR; PG8_MMA(1, 0, At, B0); PG8_MMA(1, 1, At, B1); PG8_BAR; PG8_SCHED;
;             PG8_LDB(B0, 1, 0); PG8_LDB(B1, 1, 1); PG8_SCHED; PG8_LDA(At, 1, 0); PG8_STAGE(PG8_SA(0, 1), a2 + hstepA, voffA);
;             PG8_WAIT_V(8); PG8_WAIT_L(0); PG8_BAR; PG8_MMA(0, 0, At, B0); PG8_MMA(0, 1, At, B1); PG8_BAR; PG8_SCHED;
	v_mfma_f32_16x16x32_bf16 v[62:65], v[98:101], v[190:193], v[62:65]
	v_mfma_f32_16x16x32_bf16 v[58:61], v[106:109], v[190:193], v[58:61]
	v_mfma_f32_16x16x32_bf16 v[54:57], v[98:101], v[198:201], v[54:57]
	v_mfma_f32_16x16x32_bf16 v[46:49], v[106:109], v[198:201], v[46:49]
	v_mfma_f32_16x16x32_bf16 v[30:33], v[98:101], v[214:217], v[30:33]
	v_mfma_f32_16x16x32_bf16 v[26:29], v[106:109], v[214:217], v[26:29]
	v_mfma_f32_16x16x32_bf16 v[22:25], v[98:101], v[222:225], v[22:25]
	v_mfma_f32_16x16x32_bf16 v[14:17], v[106:109], v[222:225], v[14:17]
	v_mfma_f32_16x16x32_bf16 v[62:65], v[102:105], v[194:197], v[62:65]
	v_mfma_f32_16x16x32_bf16 v[58:61], v[110:113], v[194:197], v[58:61]
	v_mfma_f32_16x16x32_bf16 v[54:57], v[102:105], v[210:213], v[54:57]
	v_mfma_f32_16x16x32_bf16 v[46:49], v[110:113], v[210:213], v[46:49]
	v_mfma_f32_16x16x32_bf16 v[30:33], v[102:105], v[218:221], v[30:33]
	v_mfma_f32_16x16x32_bf16 v[26:29], v[110:113], v[218:221], v[26:29]
	v_mfma_f32_16x16x32_bf16 v[22:25], v[102:105], v[226:229], v[22:25]
	v_mfma_f32_16x16x32_bf16 v[14:17], v[110:113], v[226:229], v[14:17]
	s_setprio 0
	s_setprio 1
	v_mfma_f32_16x16x32_bf16 v[50:53], v[174:177], v[190:193], v[50:53]
	v_mfma_f32_16x16x32_bf16 v[42:45], v[182:185], v[190:193], v[42:45]
	v_mfma_f32_16x16x32_bf16 v[38:41], v[174:177], v[198:201], v[38:41]
	v_mfma_f32_16x16x32_bf16 v[34:37], v[182:185], v[198:201], v[34:37]
	v_mfma_f32_16x16x32_bf16 v[18:21], v[174:177], v[214:217], v[18:21]
	v_mfma_f32_16x16x32_bf16 v[10:13], v[182:185], v[214:217], v[10:13]
	v_mfma_f32_16x16x32_bf16 v[6:9], v[174:177], v[222:225], v[6:9]
	v_mfma_f32_16x16x32_bf16 v[2:5], v[182:185], v[222:225], v[2:5]
	v_mfma_f32_16x16x32_bf16 v[50:53], v[178:181], v[194:197], v[50:53]
	v_mfma_f32_16x16x32_bf16 v[42:45], v[186:189], v[194:197], v[42:45]
	v_mfma_f32_16x16x32_bf16 v[38:41], v[178:181], v[210:213], v[38:41]
	v_mfma_f32_16x16x32_bf16 v[34:37], v[186:189], v[210:213], v[34:37]
	v_mfma_f32_16x16x32_bf16 v[18:21], v[178:181], v[218:221], v[18:21]
	v_mfma_f32_16x16x32_bf16 v[10:13], v[186:189], v[218:221], v[10:13]
	v_mfma_f32_16x16x32_bf16 v[6:9], v[178:181], v[226:229], v[6:9]
	v_mfma_f32_16x16x32_bf16 v[2:5], v[186:189], v[226:229], v[2:5]
	s_barrier
	s_setprio 0
	s_add_i32 s11, 0, 0x18000
	s_add_i32 s92, 0, 0x1c000
	v_add_u32_e32 v110, s11, v158
	v_add_u32_e32 v173, s92, v158
	ds_read_b128 v[98:101], v110
	ds_read_b128 v[102:105], v110 offset:1024
	ds_read_b128 v[106:109], v110 offset:2048
	ds_read_b128 v[110:113], v110 offset:3072
	ds_read_b128 v[174:177], v173
	ds_read_b128 v[178:181], v173 offset:1024
	ds_read_b128 v[182:185], v173 offset:2048
	ds_read_b128 v[186:189], v173 offset:3072
	s_add_u32 s88, s88, 0x40000
	s_addc_u32 s89, s89, 0
	s_mov_b32 m0, s70
	v_lshl_add_u64 v[230:231], s[88:89], 0, v[150:151]
	global_load_lds_dwordx4 v[230:231], off
	v_lshl_add_u64 v[230:231], s[88:89], 0, v[148:149]
	s_mov_b32 m0, s71
	s_nop 0
	global_load_lds_dwordx4 v[230:231], off
	ds_read_b128 v[190:193], v172 offset:32768
	ds_read_b128 v[194:197], v172 offset:33792
	ds_read_b128 v[198:201], v172 offset:34816
	ds_read_b128 v[210:213], v172 offset:35840
	ds_read_b128 v[214:217], v172 offset:36864
	ds_read_b128 v[218:221], v172 offset:37888
	ds_read_b128 v[222:225], v172 offset:38912
	ds_read_b128 v[226:229], v172 offset:39936
	s_waitcnt vmcnt(8)
	s_waitcnt lgkmcnt(0)
	s_setprio 1
	s_barrier
	v_mfma_f32_16x16x32_bf16 v[142:145], v[98:101], v[190:193], v[142:145]
	v_mfma_f32_16x16x32_bf16 v[138:141], v[106:109], v[190:193], v[138:141]
	v_mfma_f32_16x16x32_bf16 v[134:137], v[98:101], v[198:201], v[134:137]
	v_mfma_f32_16x16x32_bf16 v[130:133], v[106:109], v[198:201], v[130:133]
	v_mfma_f32_16x16x32_bf16 v[94:97], v[98:101], v[214:217], v[94:97]
	v_mfma_f32_16x16x32_bf16 v[90:93], v[106:109], v[214:217], v[90:93]
	v_mfma_f32_16x16x32_bf16 v[78:81], v[98:101], v[222:225], v[78:81]
	v_mfma_f32_16x16x32_bf16 v[74:77], v[106:109], v[222:225], v[74:77]
	v_mfma_f32_16x16x32_bf16 v[142:145], v[102:105], v[194:197], v[142:145]
	v_mfma_f32_16x16x32_bf16 v[138:141], v[110:113], v[194:197], v[138:141]
	v_mfma_f32_16x16x32_bf16 v[134:137], v[102:105], v[210:213], v[134:137]
	v_mfma_f32_16x16x32_bf16 v[130:133], v[110:113], v[210:213], v[130:133]
	v_mfma_f32_16x16x32_bf16 v[94:97], v[102:105], v[218:221], v[94:97]
	v_mfma_f32_16x16x32_bf16 v[90:93], v[110:113], v[218:221], v[90:93]
	v_mfma_f32_16x16x32_bf16 v[78:81], v[102:105], v[226:229], v[78:81]
	v_mfma_f32_16x16x32_bf16 v[74:77], v[110:113], v[226:229], v[74:77]
	s_setprio 0
	s_setprio 1
	v_mfma_f32_16x16x32_bf16 v[126:129], v[174:177], v[190:193], v[126:129]
	v_mfma_f32_16x16x32_bf16 v[122:125], v[182:185], v[190:193], v[122:125]
	v_mfma_f32_16x16x32_bf16 v[118:121], v[174:177], v[198:201], v[118:121]
	v_mfma_f32_16x16x32_bf16 v[114:117], v[182:185], v[198:201], v[114:117]
	v_mfma_f32_16x16x32_bf16 v[86:89], v[174:177], v[214:217], v[86:89]
	v_mfma_f32_16x16x32_bf16 v[82:85], v[182:185], v[214:217], v[82:85]
	v_mfma_f32_16x16x32_bf16 v[70:73], v[174:177], v[222:225], v[70:73]
	v_mfma_f32_16x16x32_bf16 v[66:69], v[182:185], v[222:225], v[66:69]
	v_mfma_f32_16x16x32_bf16 v[126:129], v[178:181], v[194:197], v[126:129]
	v_mfma_f32_16x16x32_bf16 v[122:125], v[186:189], v[194:197], v[122:125]
	v_mfma_f32_16x16x32_bf16 v[118:121], v[178:181], v[210:213], v[118:121]
	v_mfma_f32_16x16x32_bf16 v[114:117], v[186:189], v[210:213], v[114:117]
	v_mfma_f32_16x16x32_bf16 v[86:89], v[178:181], v[218:221], v[86:89]
	v_mfma_f32_16x16x32_bf16 v[82:85], v[186:189], v[218:221], v[82:85]
	v_mfma_f32_16x16x32_bf16 v[70:73], v[178:181], v[226:229], v[70:73]
	v_mfma_f32_16x16x32_bf16 v[66:69], v[186:189], v[226:229], v[66:69]
	s_barrier
; #define PG8_STAGE(bufoff, gbase, voff) do { _Pragma("unroll") for (int _i = 0; _i < 2; ++_i) \
;         __builtin_amdgcn_global_load_lds((const unsigned*)((const char*)(gbase) + (voff)[_i]), (LAS unsigned*)(lds + (bufoff) + ldsw + _i * 8192), 16, 0, 0); } while (0)
; #define PG8_LDA(dst, b, h) do { _Pragma("unroll") for (int m = 0; m < 4; ++m) _Pragma("unroll") for (int k = 0; k < 2; ++k) dst[m][k] = *(const LAS bf16x8*)(lds + PG8_SA(b, h) + aoff + m * 2048 + k * 1024); } while (0)
; #define PG8_MMA(ai, bj, At, Bt) do { __builtin_amdgcn_s_setprio(1); _Pragma("unroll") for (int m = 0; m < 4; ++m) _Pragma("unroll") for (int n = 0; n < 2; ++n) _Pragma("unroll") for (int k = 0; k < 2; ++k) \
;         acc[ai][bj][m][n] = __builtin_amdgcn_mfma_f32_16x16x32_bf16(Bt[n][k], At[m][k], acc[ai][bj][m][n], 0, 0, 0); __builtin_amdgcn_s_setprio(0); } while (0)
; #define PG8_WAIT_V(n) asm volatile("s_waitcnt vmcnt(" #n ")" ::: "memory")
; #define PG8_WAIT_L(n) asm volatile("s_waitcnt lgkmcnt(" #n ")" ::: "memory")
; #define PG8_BAR __builtin_amdgcn_s_barrier()
; #define PG8_SCHED __builtin_amdgcn_sched_barrier(0)
; template <class Epi>
; __device__ __forceinline__ void gemm_phase(LAS unsigned char* lds, const int tid, const Gemm g, const StaticOrder& S, const Epi& E) {
;     ...
;             PG8_WAIT_V(8); PG8_WAIT_L(0); PG8_BAR; PG8_MMA(0, 0, At, B0); PG8_MMA(0, 1, At, B1); PG8_BAR; PG8_SCHED;
;             PG8_LDA(At, 1, 1); PG8_STAGE(PG8_SB(1, 0), b3, voffB); PG8_STAGE(PG8_SB(1, 1), b3 + hstepB, voffB); PG8_STAGE(PG8_SA(1, 0), a3, voffA);
;             PG8_WAIT_V(8); PG8_WAIT_L(0); PG8_BAR; PG8_MMA(1, 0, At, B0); PG8_MMA(1, 1, At, B1); PG8_BAR; PG8_SCHED;
;         }
;         if (wr == 0) PG8_BAR;
	s_setprio 0
	s_add_i32 s11, s11, s28
	v_lshl_add_u64 v[162:163], v[162:163], 0, s[36:37]
	s_mov_b32 m0, s11
	s_nop 0
	global_load_lds_dwordx4 v[162:163], off
	s_add_i32 m0, s11, 0x2000
	s_add_u32 s30, s30, 0x40080
	v_lshl_add_u64 v[162:163], v[164:165], 0, s[36:37]
	s_addc_u32 s31, s31, 0
	s_add_i32 s11, s92, s28
	global_load_lds_dwordx4 v[162:163], off
	v_lshl_add_u64 v[162:163], s[30:31], 0, v[0:1]
	s_mov_b32 m0, s11
	s_nop 0
	global_load_lds_dwordx4 v[162:163], off
	v_lshl_add_u64 v[162:163], s[30:31], 0, v[146:147]
	s_add_i32 m0, s11, 0x2000
	s_nop 0
	global_load_lds_dwordx4 v[162:163], off
	v_lshl_add_u64 v[162:163], v[202:203], 0, s[36:37]
	s_mov_b32 m0, s72
	s_nop 0
	global_load_lds_dwordx4 v[162:163], off
	v_lshl_add_u64 v[162:163], v[206:207], 0, s[36:37]
	s_mov_b32 m0, s73
	s_nop 0
	global_load_lds_dwordx4 v[162:163], off
	ds_read_b128 v[190:193], v172 offset:49152
	ds_read_b128 v[194:197], v172 offset:50176
	ds_read_b128 v[198:201], v172 offset:51200
	ds_read_b128 v[210:213], v172 offset:52224
	ds_read_b128 v[214:217], v172 offset:53248
	ds_read_b128 v[218:221], v172 offset:54272
	ds_read_b128 v[222:225], v172 offset:55296
	ds_read_b128 v[226:229], v172 offset:56320
	s_waitcnt vmcnt(8)
	s_waitcnt lgkmcnt(0)
	s_setprio 1
	s_barrier
	v_mfma_f32_16x16x32_bf16 v[62:65], v[98:101], v[190:193], v[62:65]
	v_mfma_f32_16x16x32_bf16 v[58:61], v[106:109], v[190:193], v[58:61]
	v_mfma_f32_16x16x32_bf16 v[54:57], v[98:101], v[198:201], v[54:57]
	v_mfma_f32_16x16x32_bf16 v[46:49], v[106:109], v[198:201], v[46:49]
	v_mfma_f32_16x16x32_bf16 v[30:33], v[98:101], v[214:217], v[30:33]
	v_mfma_f32_16x16x32_bf16 v[26:29], v[106:109], v[214:217], v[26:29]
	v_mfma_f32_16x16x32_bf16 v[22:25], v[98:101], v[222:225], v[22:25]
	v_mfma_f32_16x16x32_bf16 v[14:17], v[106:109], v[222:225], v[14:17]
	v_mfma_f32_16x16x32_bf16 v[62:65], v[102:105], v[194:197], v[62:65]
	v_mfma_f32_16x16x32_bf16 v[58:61], v[110:113], v[194:197], v[58:61]
	v_mfma_f32_16x16x32_bf16 v[54:57], v[102:105], v[210:213], v[54:57]
	v_mfma_f32_16x16x32_bf16 v[46:49], v[110:113], v[210:213], v[46:49]
	v_mfma_f32_16x16x32_bf16 v[30:33], v[102:105], v[218:221], v[30:33]
	v_mfma_f32_16x16x32_bf16 v[26:29], v[110:113], v[218:221], v[26:29]
	v_mfma_f32_16x16x32_bf16 v[22:25], v[102:105], v[226:229], v[22:25]
	v_mfma_f32_16x16x32_bf16 v[14:17], v[110:113], v[226:229], v[14:17]
	s_setprio 0
	s_setprio 1
	v_mfma_f32_16x16x32_bf16 v[50:53], v[174:177], v[190:193], v[50:53]
	v_mfma_f32_16x16x32_bf16 v[42:45], v[182:185], v[190:193], v[42:45]
	v_mfma_f32_16x16x32_bf16 v[38:41], v[174:177], v[198:201], v[38:41]
	v_mfma_f32_16x16x32_bf16 v[34:37], v[182:185], v[198:201], v[34:37]
	v_mfma_f32_16x16x32_bf16 v[18:21], v[174:177], v[214:217], v[18:21]
	v_mfma_f32_16x16x32_bf16 v[10:13], v[182:185], v[214:217], v[10:13]
	v_mfma_f32_16x16x32_bf16 v[6:9], v[174:177], v[222:225], v[6:9]
	v_mfma_f32_16x16x32_bf16 v[2:5], v[182:185], v[222:225], v[2:5]
	v_mfma_f32_16x16x32_bf16 v[50:53], v[178:181], v[194:197], v[50:53]
	v_mfma_f32_16x16x32_bf16 v[42:45], v[186:189], v[194:197], v[42:45]
	v_mfma_f32_16x16x32_bf16 v[38:41], v[178:181], v[210:213], v[38:41]
	v_mfma_f32_16x16x32_bf16 v[34:37], v[186:189], v[210:213], v[34:37]
	v_mfma_f32_16x16x32_bf16 v[18:21], v[178:181], v[218:221], v[18:21]
	v_mfma_f32_16x16x32_bf16 v[10:13], v[186:189], v[218:221], v[10:13]
	v_mfma_f32_16x16x32_bf16 v[6:9], v[178:181], v[226:229], v[6:9]
	v_mfma_f32_16x16x32_bf16 v[2:5], v[186:189], v[226:229], v[2:5]
	s_barrier
	s_setprio 0
	s_add_i32 s17, s17, 2
	s_add_u32 s82, s82, 0x100
	s_addc_u32 s83, s83, 0
	s_add_u32 vcc_hi, vcc_hi, 0x100
	s_addc_u32 s27, s27, 0
	s_cmp_gt_u32 s17, 13
	s_cbranch_scc0 .LBB0_1912
	s_and_b64 vcc, exec, s[2:3]
	s_cbranch_vccz .LBB0_1915
	s_barrier

; #define PG8_STAGE(bufoff, gbase, voff) do { _Pragma("unroll") for (int _i = 0; _i < 2; ++_i) \
;         __builtin_amdgcn_global_load_lds((const unsigned*)((const char*)(gbase) + (voff)[_i]), (LAS unsigned*)(lds + (bufoff) + ldsw + _i * 8192), 16, 0, 0); } while (0)
; #define PG8_LDA(dst, b, h) do { _Pragma("unroll") for (int m = 0; m < 4; ++m) _Pragma("unroll") for (int k = 0; k < 2; ++k) dst[m][k] = *(const LAS bf16x8*)(lds + PG8_SA(b, h) + aoff + m * 2048 + k * 1024); } while (0)
; #define PG8_LDB(dst, b, h) do { _Pragma("unroll") for (int n = 0; n < 2; ++n) _Pragma("unroll") for (int k = 0; k < 2; ++k) dst[n][k] = *(const LAS bf16x8*)(lds + PG8_SB(b, h) + boff + n * 2048 + k * 1024); } while (0)
; #define PG8_MMA(ai, bj, At, Bt) do { __builtin_amdgcn_s_setprio(1); _Pragma("unroll") for (int m = 0; m < 4; ++m) _Pragma("unroll") for (int n = 0; n < 2; ++n) _Pragma("unroll") for (int k = 0; k < 2; ++k) \
;         acc[ai][bj][m][n] = __builtin_amdgcn_mfma_f32_16x16x32_bf16(Bt[n][k], At[m][k], acc[ai][bj][m][n], 0, 0, 0); __builtin_amdgcn_s_setprio(0); } while (0)
; #define PG8_WAIT_V(n) asm volatile("s_waitcnt vmcnt(" #n ")" ::: "memory")
; #define PG8_WAIT_L(n) asm volatile("s_waitcnt lgkmcnt(" #n ")" ::: "memory")
; #define PG8_BAR __builtin_amdgcn_s_barrier()
; #define PG8_SCHED __builtin_amdgcn_sched_barrier(0)
; template <class Epi>
; __device__ __forceinline__ void gemm_phase(LAS unsigned char* lds, const int tid, const Gemm g, const StaticOrder& S, const Epi& E) {
;     ...
;         for (int t = 0; t < nt; t += 2) {
;             const bool last = (t == nt - 2);
;             const char* a1 = cA + (size_t)(t + 1) * kstep;
;             const char* a2 = last ? nA : cA + (size_t)(t + 2) * kstep; const char* b2 = last ? nB : cB + (size_t)(t + 2) * kstep;
;             const char* a3 = a2 + kstep; const char* b3 = b2 + kstep;
;             PG8_LDB(B0, 0, 0); PG8_LDB(B1, 0, 1); PG8_SCHED; PG8_LDA(At, 0, 0); PG8_STAGE(PG8_SA(1, 1), a1 + hstepA, voffA);
;             PG8_WAIT_V(8); PG8_WAIT_L(0); PG8_BAR; PG8_MMA(0, 0, At, B0); PG8_MMA(0, 1, At, B1); PG8_BAR; PG8_SCHED;
;             PG8_LDA(At, 0, 1); PG8_STAGE(PG8_SB(0, 0), b2, voffB); PG8_STAGE(PG8_SB(0, 1), b2 + hstepB, voffB); PG8_STAGE(PG8_SA(0, 0), a2, voffA);
;             PG8_WAIT_V(8); PG8_WAIT_L(0); PG8_BAR; PG8_MMA(1, 0, At, B0); PG8_MMA(1, 1, At, B1); PG8_BAR; PG8_SCHED;
.LBB0_2193:
	s_add_u32 s70, s30, 0x100
	s_addc_u32 s71, s31, 0
	s_add_i32 s76, 0, 0x10000
	s_cmp_eq_u32 vcc_hi, 40
	s_cselect_b32 s75, s1, s71
	s_cselect_b32 s74, s0, s70
	s_cselect_b32 s73, s69, vcc_lo
	s_cselect_b32 s72, s68, s28
	s_add_i32 s2, 0, 0x14000
	v_add_u32_e32 v154, s76, v179
	v_add_u32_e32 v162, s2, v179
	ds_read_b128 v[130:133], v154
	ds_read_b128 v[134:137], v154 offset:1024
	ds_read_b128 v[138:141], v154 offset:2048
	ds_read_b128 v[154:157], v154 offset:3072
	ds_read_b128 v[158:161], v162
	ds_read_b128 v[170:173], v162 offset:1024
	ds_read_b128 v[174:177], v162 offset:2048
	ds_read_b128 v[184:187], v162 offset:3072
	v_lshl_add_u64 v[162:163], s[30:31], 0, v[150:151]
	s_add_i32 m0, s5, 0xc000
	s_nop 0
	global_load_lds_dwordx4 v[162:163], off
	v_lshl_add_u64 v[162:163], s[30:31], 0, v[152:153]
	s_add_i32 m0, s5, 0xe000
	s_nop 0
	global_load_lds_dwordx4 v[162:163], off
	ds_read_b128 v[188:191], v181
	ds_read_b128 v[192:195], v181 offset:1024
	ds_read_b128 v[196:199], v181 offset:2048
	ds_read_b128 v[200:203], v181 offset:3072
	ds_read_b128 v[212:215], v181 offset:4096
	ds_read_b128 v[216:219], v181 offset:5120
	ds_read_b128 v[220:223], v181 offset:6144
	ds_read_b128 v[224:227], v181 offset:7168
	s_waitcnt vmcnt(8)
	s_waitcnt lgkmcnt(0)
	s_setprio 1
	s_barrier
	v_mfma_f32_16x16x32_bf16 v[126:129], v[130:133], v[188:191], v[126:129]
	v_mfma_f32_16x16x32_bf16 v[122:125], v[138:141], v[188:191], v[122:125]
	v_mfma_f32_16x16x32_bf16 v[110:113], v[130:133], v[196:199], v[110:113]
	v_mfma_f32_16x16x32_bf16 v[106:109], v[138:141], v[196:199], v[106:109]
	v_mfma_f32_16x16x32_bf16 v[94:97], v[130:133], v[212:215], v[94:97]
	v_mfma_f32_16x16x32_bf16 v[90:93], v[138:141], v[212:215], v[90:93]
	v_mfma_f32_16x16x32_bf16 v[78:81], v[130:133], v[220:223], v[78:81]
	v_mfma_f32_16x16x32_bf16 v[74:77], v[138:141], v[220:223], v[74:77]
	v_mfma_f32_16x16x32_bf16 v[126:129], v[134:137], v[192:195], v[126:129]
	v_mfma_f32_16x16x32_bf16 v[122:125], v[154:157], v[192:195], v[122:125]
	v_mfma_f32_16x16x32_bf16 v[110:113], v[134:137], v[200:203], v[110:113]
	v_mfma_f32_16x16x32_bf16 v[106:109], v[154:157], v[200:203], v[106:109]
	v_mfma_f32_16x16x32_bf16 v[94:97], v[134:137], v[216:219], v[94:97]
	v_mfma_f32_16x16x32_bf16 v[90:93], v[154:157], v[216:219], v[90:93]
	v_mfma_f32_16x16x32_bf16 v[78:81], v[134:137], v[224:227], v[78:81]
	v_mfma_f32_16x16x32_bf16 v[74:77], v[154:157], v[224:227], v[74:77]
	s_setprio 0
	s_setprio 1
	v_mfma_f32_16x16x32_bf16 v[118:121], v[158:161], v[188:191], v[118:121]
	v_mfma_f32_16x16x32_bf16 v[114:117], v[174:177], v[188:191], v[114:117]
	v_mfma_f32_16x16x32_bf16 v[102:105], v[158:161], v[196:199], v[102:105]
	v_mfma_f32_16x16x32_bf16 v[98:101], v[174:177], v[196:199], v[98:101]
	v_mfma_f32_16x16x32_bf16 v[86:89], v[158:161], v[212:215], v[86:89]
	v_mfma_f32_16x16x32_bf16 v[82:85], v[174:177], v[212:215], v[82:85]
	v_mfma_f32_16x16x32_bf16 v[70:73], v[158:161], v[220:223], v[70:73]
	v_mfma_f32_16x16x32_bf16 v[66:69], v[174:177], v[220:223], v[66:69]
	v_mfma_f32_16x16x32_bf16 v[118:121], v[170:173], v[192:195], v[118:121]
	v_mfma_f32_16x16x32_bf16 v[114:117], v[184:187], v[192:195], v[114:117]
	v_mfma_f32_16x16x32_bf16 v[102:105], v[170:173], v[200:203], v[102:105]
	v_mfma_f32_16x16x32_bf16 v[98:101], v[184:187], v[200:203], v[98:101]
	v_mfma_f32_16x16x32_bf16 v[86:89], v[170:173], v[216:219], v[86:89]
	v_mfma_f32_16x16x32_bf16 v[82:85], v[184:187], v[216:219], v[82:85]
	v_mfma_f32_16x16x32_bf16 v[70:73], v[170:173], v[224:227], v[70:73]
	v_mfma_f32_16x16x32_bf16 v[66:69], v[184:187], v[224:227], v[66:69]
	s_barrier
	s_setprio 0
	s_add_i32 s3, s76, s4
	v_lshl_add_u64 v[162:163], s[72:73], 0, v[0:1]
	s_mov_b32 m0, s3
	s_nop 0
	global_load_lds_dwordx4 v[162:163], off
	s_add_i32 m0, s3, 0x2000
	s_add_u32 s30, s72, 0xb0000
	v_lshl_add_u64 v[164:165], s[72:73], 0, v[148:149]
	s_addc_u32 s31, s73, 0
	s_add_i32 s2, s2, s4
	global_load_lds_dwordx4 v[164:165], off
	v_lshl_add_u64 v[206:207], s[30:31], 0, v[0:1]
	s_mov_b32 m0, s2
	v_lshl_add_u64 v[228:229], s[74:75], 0, v[144:145]
	global_load_lds_dwordx4 v[206:207], off
	v_lshl_add_u64 v[206:207], s[30:31], 0, v[148:149]
	s_add_i32 m0, s2, 0x2000
	s_nop 0
	global_load_lds_dwordx4 v[206:207], off
	v_lshl_add_u64 v[206:207], s[74:75], 0, v[142:143]
	s_mov_b32 m0, s5
	s_nop 0
	global_load_lds_dwordx4 v[206:207], off
	s_mov_b32 m0, s6
	s_nop 0
	global_load_lds_dwordx4 v[228:229], off
	ds_read_b128 v[188:191], v181 offset:16384
	ds_read_b128 v[192:195], v181 offset:17408
	ds_read_b128 v[196:199], v181 offset:18432
	ds_read_b128 v[200:203], v181 offset:19456
	ds_read_b128 v[212:215], v181 offset:20480
	ds_read_b128 v[216:219], v181 offset:21504
	ds_read_b128 v[220:223], v181 offset:22528
	ds_read_b128 v[224:227], v181 offset:23552
	s_waitcnt vmcnt(8)
	s_waitcnt lgkmcnt(0)
	s_setprio 1
	s_barrier
; #define PG8_STAGE(bufoff, gbase, voff) do { _Pragma("unroll") for (int _i = 0; _i < 2; ++_i) \
;         __builtin_amdgcn_global_load_lds((const unsigned*)((const char*)(gbase) + (voff)[_i]), (LAS unsigned*)(lds + (bufoff) + ldsw + _i * 8192), 16, 0, 0); } while (0)
; #define PG8_LDA(dst, b, h) do { _Pragma("unroll") for (int m = 0; m < 4; ++m) _Pragma("unroll") for (int k = 0; k < 2; ++k) dst[m][k] = *(const LAS bf16x8*)(lds + PG8_SA(b, h) + aoff + m * 2048 + k * 1024); } while (0)
; #define PG8_LDB(dst, b, h) do { _Pragma("unroll") for (int n = 0; n < 2; ++n) _Pragma("unroll") for (int k = 0; k < 2; ++k) dst[n][k] = *(const LAS bf16x8*)(lds + PG8_SB(b, h) + boff + n * 2048 + k * 1024); } while (0)
; #define PG8_MMA(ai, bj, At, Bt) do { __builtin_amdgcn_s_setprio(1); _Pragma("unroll") for (int m = 0; m < 4; ++m) _Pragma("unroll") for (int n = 0; n < 2; ++n) _Pragma("unroll") for (int k = 0; k < 2; ++k) \
;         acc[ai][bj][m][n] = __builtin_amdgcn_mfma_f32_16x16x32_bf16(Bt[n][k], At[m][k], acc[ai][bj][m][n], 0, 0, 0); __builtin_amdgcn_s_setprio(0); } while (0)
; #define PG8_WAIT_V(n) asm volatile("s_waitcnt vmcnt(" #n ")" ::: "memory")
; #define PG8_WAIT_L(n) asm volatile("s_waitcnt lgkmcnt(" #n ")" ::: "memory")
; #define PG8_BAR __builtin_amdgcn_s_barrier()
; #define PG8_SCHED __builtin_amdgcn_sched_barrier(0)
; template <class Epi>
; __device__ __forceinline__ void gemm_phase(LAS unsigned char* lds, const int tid, const Gemm g, const StaticOrder& S, const Epi& E) {
;     ...
;             PG8_WAIT_V(8); PG8_WAIT_L(0); PG8_BAR; PG8_MMA(1, 0, At, B0); PG8_MMA(1, 1, At, B1); PG8_BAR; PG8_SCHED;
;             PG8_LDB(B0, 1, 0); PG8_LDB(B1, 1, 1); PG8_SCHED; PG8_LDA(At, 1, 0); PG8_STAGE(PG8_SA(0, 1), a2 + hstepA, voffA);
;             PG8_WAIT_V(8); PG8_WAIT_L(0); PG8_BAR; PG8_MMA(0, 0, At, B0); PG8_MMA(0, 1, At, B1); PG8_BAR; PG8_SCHED;
	v_mfma_f32_16x16x32_bf16 v[62:65], v[130:133], v[188:191], v[62:65]
	v_mfma_f32_16x16x32_bf16 v[58:61], v[138:141], v[188:191], v[58:61]
	v_mfma_f32_16x16x32_bf16 v[46:49], v[130:133], v[196:199], v[46:49]
	v_mfma_f32_16x16x32_bf16 v[42:45], v[138:141], v[196:199], v[42:45]
	v_mfma_f32_16x16x32_bf16 v[30:33], v[130:133], v[212:215], v[30:33]
	v_mfma_f32_16x16x32_bf16 v[26:29], v[138:141], v[212:215], v[26:29]
	v_mfma_f32_16x16x32_bf16 v[14:17], v[130:133], v[220:223], v[14:17]
	v_mfma_f32_16x16x32_bf16 v[10:13], v[138:141], v[220:223], v[10:13]
	v_mfma_f32_16x16x32_bf16 v[62:65], v[134:137], v[192:195], v[62:65]
	v_mfma_f32_16x16x32_bf16 v[58:61], v[154:157], v[192:195], v[58:61]
	v_mfma_f32_16x16x32_bf16 v[46:49], v[134:137], v[200:203], v[46:49]
	v_mfma_f32_16x16x32_bf16 v[42:45], v[154:157], v[200:203], v[42:45]
	v_mfma_f32_16x16x32_bf16 v[30:33], v[134:137], v[216:219], v[30:33]
	v_mfma_f32_16x16x32_bf16 v[26:29], v[154:157], v[216:219], v[26:29]
	v_mfma_f32_16x16x32_bf16 v[14:17], v[134:137], v[224:227], v[14:17]
	v_mfma_f32_16x16x32_bf16 v[10:13], v[154:157], v[224:227], v[10:13]
	s_setprio 0
	s_setprio 1
	v_mfma_f32_16x16x32_bf16 v[54:57], v[158:161], v[188:191], v[54:57]
	v_mfma_f32_16x16x32_bf16 v[50:53], v[174:177], v[188:191], v[50:53]
	v_mfma_f32_16x16x32_bf16 v[38:41], v[158:161], v[196:199], v[38:41]
	v_mfma_f32_16x16x32_bf16 v[34:37], v[174:177], v[196:199], v[34:37]
	v_mfma_f32_16x16x32_bf16 v[22:25], v[158:161], v[212:215], v[22:25]
	v_mfma_f32_16x16x32_bf16 v[18:21], v[174:177], v[212:215], v[18:21]
	v_mfma_f32_16x16x32_bf16 v[6:9], v[158:161], v[220:223], v[6:9]
	v_mfma_f32_16x16x32_bf16 v[2:5], v[174:177], v[220:223], v[2:5]
	v_mfma_f32_16x16x32_bf16 v[54:57], v[170:173], v[192:195], v[54:57]
	v_mfma_f32_16x16x32_bf16 v[50:53], v[184:187], v[192:195], v[50:53]
	v_mfma_f32_16x16x32_bf16 v[38:41], v[170:173], v[200:203], v[38:41]
	v_mfma_f32_16x16x32_bf16 v[34:37], v[184:187], v[200:203], v[34:37]
	v_mfma_f32_16x16x32_bf16 v[22:25], v[170:173], v[216:219], v[22:25]
	v_mfma_f32_16x16x32_bf16 v[18:21], v[184:187], v[216:219], v[18:21]
	v_mfma_f32_16x16x32_bf16 v[6:9], v[170:173], v[224:227], v[6:9]
	v_mfma_f32_16x16x32_bf16 v[2:5], v[184:187], v[224:227], v[2:5]
	s_barrier
	s_setprio 0
	s_add_i32 s2, 0, 0x18000
	s_add_i32 s3, 0, 0x1c000
	v_add_u32_e32 v154, s2, v179
	v_add_u32_e32 v183, s3, v179
	ds_read_b128 v[130:133], v154
	ds_read_b128 v[134:137], v154 offset:1024
	ds_read_b128 v[138:141], v154 offset:2048
	ds_read_b128 v[154:157], v154 offset:3072
	ds_read_b128 v[158:161], v183
	ds_read_b128 v[170:173], v183 offset:1024
	ds_read_b128 v[174:177], v183 offset:2048
	ds_read_b128 v[184:187], v183 offset:3072
	s_add_u32 s30, s74, 0x160000
	s_addc_u32 s31, s75, 0
	s_mov_b32 m0, s7
	v_lshl_add_u64 v[230:231], s[30:31], 0, v[142:143]
	global_load_lds_dwordx4 v[230:231], off
	v_lshl_add_u64 v[230:231], s[30:31], 0, v[144:145]
	s_mov_b32 m0, s77
	s_nop 0
	global_load_lds_dwordx4 v[230:231], off
	ds_read_b128 v[188:191], v181 offset:32768
	ds_read_b128 v[192:195], v181 offset:33792
	ds_read_b128 v[196:199], v181 offset:34816
	ds_read_b128 v[200:203], v181 offset:35840
	ds_read_b128 v[212:215], v181 offset:36864
	ds_read_b128 v[216:219], v181 offset:37888
	ds_read_b128 v[220:223], v181 offset:38912
	ds_read_b128 v[224:227], v181 offset:39936
	s_waitcnt vmcnt(8)
	s_waitcnt lgkmcnt(0)
	s_setprio 1
	s_barrier
	v_mfma_f32_16x16x32_bf16 v[126:129], v[130:133], v[188:191], v[126:129]
	v_mfma_f32_16x16x32_bf16 v[122:125], v[138:141], v[188:191], v[122:125]
	v_mfma_f32_16x16x32_bf16 v[110:113], v[130:133], v[196:199], v[110:113]
	v_mfma_f32_16x16x32_bf16 v[106:109], v[138:141], v[196:199], v[106:109]
	v_mfma_f32_16x16x32_bf16 v[94:97], v[130:133], v[212:215], v[94:97]
	v_mfma_f32_16x16x32_bf16 v[90:93], v[138:141], v[212:215], v[90:93]
	v_mfma_f32_16x16x32_bf16 v[78:81], v[130:133], v[220:223], v[78:81]
	v_mfma_f32_16x16x32_bf16 v[74:77], v[138:141], v[220:223], v[74:77]
	v_mfma_f32_16x16x32_bf16 v[126:129], v[134:137], v[192:195], v[126:129]
	v_mfma_f32_16x16x32_bf16 v[122:125], v[154:157], v[192:195], v[122:125]
	v_mfma_f32_16x16x32_bf16 v[110:113], v[134:137], v[200:203], v[110:113]
	v_mfma_f32_16x16x32_bf16 v[106:109], v[154:157], v[200:203], v[106:109]
	v_mfma_f32_16x16x32_bf16 v[94:97], v[134:137], v[216:219], v[94:97]
	v_mfma_f32_16x16x32_bf16 v[90:93], v[154:157], v[216:219], v[90:93]
	v_mfma_f32_16x16x32_bf16 v[78:81], v[134:137], v[224:227], v[78:81]
	v_mfma_f32_16x16x32_bf16 v[74:77], v[154:157], v[224:227], v[74:77]
	s_setprio 0
	s_setprio 1
	v_mfma_f32_16x16x32_bf16 v[118:121], v[158:161], v[188:191], v[118:121]
	v_mfma_f32_16x16x32_bf16 v[114:117], v[174:177], v[188:191], v[114:117]
	v_mfma_f32_16x16x32_bf16 v[102:105], v[158:161], v[196:199], v[102:105]
	v_mfma_f32_16x16x32_bf16 v[98:101], v[174:177], v[196:199], v[98:101]
	v_mfma_f32_16x16x32_bf16 v[86:89], v[158:161], v[212:215], v[86:89]
	v_mfma_f32_16x16x32_bf16 v[82:85], v[174:177], v[212:215], v[82:85]
	v_mfma_f32_16x16x32_bf16 v[70:73], v[158:161], v[220:223], v[70:73]
	v_mfma_f32_16x16x32_bf16 v[66:69], v[174:177], v[220:223], v[66:69]
	v_mfma_f32_16x16x32_bf16 v[118:121], v[170:173], v[192:195], v[118:121]
	v_mfma_f32_16x16x32_bf16 v[114:117], v[184:187], v[192:195], v[114:117]
	v_mfma_f32_16x16x32_bf16 v[102:105], v[170:173], v[200:203], v[102:105]
	v_mfma_f32_16x16x32_bf16 v[98:101], v[184:187], v[200:203], v[98:101]
	v_mfma_f32_16x16x32_bf16 v[86:89], v[170:173], v[216:219], v[86:89]
	v_mfma_f32_16x16x32_bf16 v[82:85], v[184:187], v[216:219], v[82:85]
	v_mfma_f32_16x16x32_bf16 v[70:73], v[170:173], v[224:227], v[70:73]
	v_mfma_f32_16x16x32_bf16 v[66:69], v[184:187], v[224:227], v[66:69]
	s_barrier
; #define PG8_STAGE(bufoff, gbase, voff) do { _Pragma("unroll") for (int _i = 0; _i < 2; ++_i) \
;         __builtin_amdgcn_global_load_lds((const unsigned*)((const char*)(gbase) + (voff)[_i]), (LAS unsigned*)(lds + (bufoff) + ldsw + _i * 8192), 16, 0, 0); } while (0)
; #define PG8_LDA(dst, b, h) do { _Pragma("unroll") for (int m = 0; m < 4; ++m) _Pragma("unroll") for (int k = 0; k < 2; ++k) dst[m][k] = *(const LAS bf16x8*)(lds + PG8_SA(b, h) + aoff + m * 2048 + k * 1024); } while (0)
; #define PG8_MMA(ai, bj, At, Bt) do { __builtin_amdgcn_s_setprio(1); _Pragma("unroll") for (int m = 0; m < 4; ++m) _Pragma("unroll") for (int n = 0; n < 2; ++n) _Pragma("unroll") for (int k = 0; k < 2; ++k) \
;         acc[ai][bj][m][n] = __builtin_amdgcn_mfma_f32_16x16x32_bf16(Bt[n][k], At[m][k], acc[ai][bj][m][n], 0, 0, 0); __builtin_amdgcn_s_setprio(0); } while (0)
; #define PG8_WAIT_V(n) asm volatile("s_waitcnt vmcnt(" #n ")" ::: "memory")
; #define PG8_WAIT_L(n) asm volatile("s_waitcnt lgkmcnt(" #n ")" ::: "memory")
; #define PG8_BAR __builtin_amdgcn_s_barrier()
; #define PG8_SCHED __builtin_amdgcn_sched_barrier(0)
; template <class Epi>
; __device__ __forceinline__ void gemm_phase(LAS unsigned char* lds, const int tid, const Gemm g, const StaticOrder& S, const Epi& E) {
;     ...
;             PG8_LDA(At, 1, 1); PG8_STAGE(PG8_SB(1, 0), b3, voffB); PG8_STAGE(PG8_SB(1, 1), b3 + hstepB, voffB); PG8_STAGE(PG8_SA(1, 0), a3, voffA);
;             PG8_WAIT_V(8); PG8_WAIT_L(0); PG8_BAR; PG8_MMA(1, 0, At, B0); PG8_MMA(1, 1, At, B1); PG8_BAR; PG8_SCHED;
;         }
;         if (wr == 0) PG8_BAR;
	s_setprio 0
	s_add_i32 s2, s2, s4
	v_lshl_add_u64 v[162:163], v[162:163], 0, s[36:37]
	s_mov_b32 m0, s2
	s_nop 0
	global_load_lds_dwordx4 v[162:163], off
	s_add_i32 m0, s2, 0x2000
	s_add_u32 s30, s72, 0xb0080
	v_lshl_add_u64 v[162:163], v[164:165], 0, s[36:37]
	s_addc_u32 s31, s73, 0
	s_add_i32 s2, s3, s4
	global_load_lds_dwordx4 v[162:163], off
	v_lshl_add_u64 v[162:163], s[30:31], 0, v[0:1]
	s_mov_b32 m0, s2
	s_nop 0
	global_load_lds_dwordx4 v[162:163], off
	v_lshl_add_u64 v[162:163], s[30:31], 0, v[148:149]
	s_add_i32 m0, s2, 0x2000
	s_nop 0
	global_load_lds_dwordx4 v[162:163], off
	v_lshl_add_u64 v[162:163], v[206:207], 0, s[36:37]
	s_mov_b32 m0, s83
	s_nop 0
	global_load_lds_dwordx4 v[162:163], off
	v_lshl_add_u64 v[162:163], v[228:229], 0, s[36:37]
	s_mov_b32 m0, s88
	s_nop 0
	global_load_lds_dwordx4 v[162:163], off
	ds_read_b128 v[188:191], v181 offset:49152
	ds_read_b128 v[192:195], v181 offset:50176
	ds_read_b128 v[196:199], v181 offset:51200
	ds_read_b128 v[200:203], v181 offset:52224
	ds_read_b128 v[212:215], v181 offset:53248
	ds_read_b128 v[216:219], v181 offset:54272
	ds_read_b128 v[220:223], v181 offset:55296
	ds_read_b128 v[224:227], v181 offset:56320
	s_waitcnt vmcnt(8)
	s_waitcnt lgkmcnt(0)
	s_setprio 1
	s_barrier
	v_mfma_f32_16x16x32_bf16 v[62:65], v[130:133], v[188:191], v[62:65]
	v_mfma_f32_16x16x32_bf16 v[58:61], v[138:141], v[188:191], v[58:61]
	v_mfma_f32_16x16x32_bf16 v[46:49], v[130:133], v[196:199], v[46:49]
	v_mfma_f32_16x16x32_bf16 v[42:45], v[138:141], v[196:199], v[42:45]
	v_mfma_f32_16x16x32_bf16 v[30:33], v[130:133], v[212:215], v[30:33]
	v_mfma_f32_16x16x32_bf16 v[26:29], v[138:141], v[212:215], v[26:29]
	v_mfma_f32_16x16x32_bf16 v[14:17], v[130:133], v[220:223], v[14:17]
	v_mfma_f32_16x16x32_bf16 v[10:13], v[138:141], v[220:223], v[10:13]
	v_mfma_f32_16x16x32_bf16 v[62:65], v[134:137], v[192:195], v[62:65]
	v_mfma_f32_16x16x32_bf16 v[58:61], v[154:157], v[192:195], v[58:61]
	v_mfma_f32_16x16x32_bf16 v[46:49], v[134:137], v[200:203], v[46:49]
	v_mfma_f32_16x16x32_bf16 v[42:45], v[154:157], v[200:203], v[42:45]
	v_mfma_f32_16x16x32_bf16 v[30:33], v[134:137], v[216:219], v[30:33]
	v_mfma_f32_16x16x32_bf16 v[26:29], v[154:157], v[216:219], v[26:29]
	v_mfma_f32_16x16x32_bf16 v[14:17], v[134:137], v[224:227], v[14:17]
	v_mfma_f32_16x16x32_bf16 v[10:13], v[154:157], v[224:227], v[10:13]
	s_setprio 0
	s_setprio 1
	v_mfma_f32_16x16x32_bf16 v[54:57], v[158:161], v[188:191], v[54:57]
	v_mfma_f32_16x16x32_bf16 v[50:53], v[174:177], v[188:191], v[50:53]
	v_mfma_f32_16x16x32_bf16 v[38:41], v[158:161], v[196:199], v[38:41]
	v_mfma_f32_16x16x32_bf16 v[34:37], v[174:177], v[196:199], v[34:37]
	v_mfma_f32_16x16x32_bf16 v[22:25], v[158:161], v[212:215], v[22:25]
	v_mfma_f32_16x16x32_bf16 v[18:21], v[174:177], v[212:215], v[18:21]
	v_mfma_f32_16x16x32_bf16 v[6:9], v[158:161], v[220:223], v[6:9]
	v_mfma_f32_16x16x32_bf16 v[2:5], v[174:177], v[220:223], v[2:5]
	v_mfma_f32_16x16x32_bf16 v[54:57], v[170:173], v[192:195], v[54:57]
	v_mfma_f32_16x16x32_bf16 v[50:53], v[184:187], v[192:195], v[50:53]
	v_mfma_f32_16x16x32_bf16 v[38:41], v[170:173], v[200:203], v[38:41]
	v_mfma_f32_16x16x32_bf16 v[34:37], v[184:187], v[200:203], v[34:37]
	v_mfma_f32_16x16x32_bf16 v[22:25], v[170:173], v[216:219], v[22:25]
	v_mfma_f32_16x16x32_bf16 v[18:21], v[184:187], v[216:219], v[18:21]
	v_mfma_f32_16x16x32_bf16 v[6:9], v[170:173], v[224:227], v[6:9]
	v_mfma_f32_16x16x32_bf16 v[2:5], v[184:187], v[224:227], v[2:5]
	s_barrier
	s_setprio 0
	s_add_i32 vcc_hi, vcc_hi, 2
	s_add_u32 s28, s28, 0x100
	s_addc_u32 vcc_lo, vcc_lo, 0
	s_cmp_gt_u32 vcc_hi, 41
	s_mov_b64 s[30:31], s[70:71]
	s_cbranch_scc0 .LBB0_2193
	s_and_b64 vcc, exec, s[26:27]
	s_cbranch_vccz .LBB0_2196
	s_barrier

; #define PG8_STAGE(bufoff, gbase, voff) do { _Pragma("unroll") for (int _i = 0; _i < 2; ++_i) \
;         __builtin_amdgcn_global_load_lds((const unsigned*)((const char*)(gbase) + (voff)[_i]), (LAS unsigned*)(lds + (bufoff) + ldsw + _i * 8192), 16, 0, 0); } while (0)
; #define PG8_LDA(dst, b, h) do { _Pragma("unroll") for (int m = 0; m < 4; ++m) _Pragma("unroll") for (int k = 0; k < 2; ++k) dst[m][k] = *(const LAS bf16x8*)(lds + PG8_SA(b, h) + aoff + m * 2048 + k * 1024); } while (0)
; #define PG8_LDB(dst, b, h) do { _Pragma("unroll") for (int n = 0; n < 2; ++n) _Pragma("unroll") for (int k = 0; k < 2; ++k) dst[n][k] = *(const LAS bf16x8*)(lds + PG8_SB(b, h) + boff + n * 2048 + k * 1024); } while (0)
; #define PG8_MMA(ai, bj, At, Bt) do { __builtin_amdgcn_s_setprio(1); _Pragma("unroll") for (int m = 0; m < 4; ++m) _Pragma("unroll") for (int n = 0; n < 2; ++n) _Pragma("unroll") for (int k = 0; k < 2; ++k) \
;         acc[ai][bj][m][n] = __builtin_amdgcn_mfma_f32_16x16x32_bf16(Bt[n][k], At[m][k], acc[ai][bj][m][n], 0, 0, 0); __builtin_amdgcn_s_setprio(0); } while (0)
; #define PG8_WAIT_V(n) asm volatile("s_waitcnt vmcnt(" #n ")" ::: "memory")
; #define PG8_WAIT_L(n) asm volatile("s_waitcnt lgkmcnt(" #n ")" ::: "memory")
; #define PG8_BAR __builtin_amdgcn_s_barrier()
; #define PG8_SCHED __builtin_amdgcn_sched_barrier(0)
; template <class Epi>
; __device__ __forceinline__ void gemm_phase(LAS unsigned char* lds, const int tid, const Gemm g, const StaticOrder& S, const Epi& E) {
;     ...
;             const bool last = (t == nt - 2);
;             const char* a1 = cA + (size_t)(t + 1) * kstep;
;             const char* a2 = last ? nA : cA + (size_t)(t + 2) * kstep; const char* b2 = last ? nB : cB + (size_t)(t + 2) * kstep;
;             const char* a3 = a2 + kstep; const char* b3 = b2 + kstep;
;             PG8_LDB(B0, 0, 0); PG8_LDB(B1, 0, 1); PG8_SCHED; PG8_LDA(At, 0, 0); PG8_STAGE(PG8_SA(1, 1), a1 + hstepA, voffA);
;             PG8_WAIT_V(8); PG8_WAIT_L(0); PG8_BAR; PG8_MMA(0, 0, At, B0); PG8_MMA(0, 1, At, B1); PG8_BAR; PG8_SCHED;
;             PG8_LDA(At, 0, 1); PG8_STAGE(PG8_SB(0, 0), b2, voffB); PG8_STAGE(PG8_SB(0, 1), b2 + hstepB, voffB); PG8_STAGE(PG8_SA(0, 0), a2, voffA);
;             PG8_WAIT_V(8); PG8_WAIT_L(0); PG8_BAR; PG8_MMA(1, 0, At, B0); PG8_MMA(1, 1, At, B1); PG8_BAR; PG8_SCHED;
.LBB0_2303:
	s_add_u32 s68, s66, 0x100
	s_addc_u32 s69, s67, 0
	s_add_i32 s76, 0, 0x10000
	s_cmp_eq_u32 s93, 40
	s_cselect_b32 s73, s1, s69
	s_cselect_b32 s72, s0, s68
	s_cselect_b32 s71, s31, s28
	s_cselect_b32 s70, s30, s11
	s_add_i32 vcc_lo, 0, 0x14000
	v_add_u32_e32 v70, s76, v212
	v_add_u32_e32 v162, vcc_lo, v212
	ds_read_b128 v[42:45], v70
	ds_read_b128 v[46:49], v70 offset:1024
	ds_read_b128 v[66:69], v70 offset:2048
	ds_read_b128 v[70:73], v70 offset:3072
	ds_read_b128 v[158:161], v162
	ds_read_b128 v[170:173], v162 offset:1024
	ds_read_b128 v[174:177], v162 offset:2048
	ds_read_b128 v[178:181], v162 offset:3072
	v_lshl_add_u64 v[162:163], s[66:67], 0, v[154:155]
	s_add_i32 m0, s5, 0xc000
	s_nop 0
	global_load_lds_dwordx4 v[162:163], off
	v_lshl_add_u64 v[162:163], s[66:67], 0, v[156:157]
	s_add_i32 m0, s5, 0xe000
	s_nop 0
	global_load_lds_dwordx4 v[162:163], off
	ds_read_b128 v[182:185], v214
	ds_read_b128 v[186:189], v214 offset:1024
	ds_read_b128 v[190:193], v214 offset:2048
	ds_read_b128 v[194:197], v214 offset:3072
	ds_read_b128 v[198:201], v214 offset:4096
	ds_read_b128 v[216:219], v214 offset:5120
	ds_read_b128 v[220:223], v214 offset:6144
	ds_read_b128 v[224:227], v214 offset:7168
	s_waitcnt vmcnt(8)
	s_waitcnt lgkmcnt(0)
	s_setprio 1
	s_barrier
	v_mfma_f32_16x16x32_bf16 v[142:145], v[42:45], v[182:185], v[142:145]
	v_mfma_f32_16x16x32_bf16 v[138:141], v[66:69], v[182:185], v[138:141]
	v_mfma_f32_16x16x32_bf16 v[126:129], v[42:45], v[190:193], v[126:129]
	v_mfma_f32_16x16x32_bf16 v[122:125], v[66:69], v[190:193], v[122:125]
	v_mfma_f32_16x16x32_bf16 v[110:113], v[42:45], v[198:201], v[110:113]
	v_mfma_f32_16x16x32_bf16 v[106:109], v[66:69], v[198:201], v[106:109]
	v_mfma_f32_16x16x32_bf16 v[94:97], v[42:45], v[220:223], v[94:97]
	v_mfma_f32_16x16x32_bf16 v[90:93], v[66:69], v[220:223], v[90:93]
	v_mfma_f32_16x16x32_bf16 v[142:145], v[46:49], v[186:189], v[142:145]
	v_mfma_f32_16x16x32_bf16 v[138:141], v[70:73], v[186:189], v[138:141]
	v_mfma_f32_16x16x32_bf16 v[126:129], v[46:49], v[194:197], v[126:129]
	v_mfma_f32_16x16x32_bf16 v[122:125], v[70:73], v[194:197], v[122:125]
	v_mfma_f32_16x16x32_bf16 v[110:113], v[46:49], v[216:219], v[110:113]
	v_mfma_f32_16x16x32_bf16 v[106:109], v[70:73], v[216:219], v[106:109]
	v_mfma_f32_16x16x32_bf16 v[94:97], v[46:49], v[224:227], v[94:97]
	v_mfma_f32_16x16x32_bf16 v[90:93], v[70:73], v[224:227], v[90:93]
	s_setprio 0
	s_setprio 1
	v_mfma_f32_16x16x32_bf16 v[134:137], v[158:161], v[182:185], v[134:137]
	v_mfma_f32_16x16x32_bf16 v[130:133], v[174:177], v[182:185], v[130:133]
	v_mfma_f32_16x16x32_bf16 v[118:121], v[158:161], v[190:193], v[118:121]
	v_mfma_f32_16x16x32_bf16 v[114:117], v[174:177], v[190:193], v[114:117]
	v_mfma_f32_16x16x32_bf16 v[102:105], v[158:161], v[198:201], v[102:105]
	v_mfma_f32_16x16x32_bf16 v[98:101], v[174:177], v[198:201], v[98:101]
	v_mfma_f32_16x16x32_bf16 v[86:89], v[158:161], v[220:223], v[86:89]
	v_mfma_f32_16x16x32_bf16 v[82:85], v[174:177], v[220:223], v[82:85]
	v_mfma_f32_16x16x32_bf16 v[134:137], v[170:173], v[186:189], v[134:137]
	v_mfma_f32_16x16x32_bf16 v[130:133], v[178:181], v[186:189], v[130:133]
	v_mfma_f32_16x16x32_bf16 v[118:121], v[170:173], v[194:197], v[118:121]
	v_mfma_f32_16x16x32_bf16 v[114:117], v[178:181], v[194:197], v[114:117]
	v_mfma_f32_16x16x32_bf16 v[102:105], v[170:173], v[216:219], v[102:105]
	v_mfma_f32_16x16x32_bf16 v[98:101], v[178:181], v[216:219], v[98:101]
	v_mfma_f32_16x16x32_bf16 v[86:89], v[170:173], v[224:227], v[86:89]
	v_mfma_f32_16x16x32_bf16 v[82:85], v[178:181], v[224:227], v[82:85]
	s_barrier
	s_setprio 0
	s_add_i32 s66, s76, s4
	v_lshl_add_u64 v[162:163], s[70:71], 0, v[0:1]
	s_mov_b32 m0, s66
	s_nop 0
	global_load_lds_dwordx4 v[162:163], off
	s_add_i32 m0, s66, 0x2000
	s_add_u32 s66, s70, 0xb0000
	v_lshl_add_u64 v[164:165], s[70:71], 0, v[152:153]
	s_addc_u32 s67, s71, 0
	s_add_i32 s76, vcc_lo, s4
	global_load_lds_dwordx4 v[164:165], off
	v_lshl_add_u64 v[202:203], s[66:67], 0, v[0:1]
	s_mov_b32 m0, s76
	v_lshl_add_u64 v[206:207], s[72:73], 0, v[150:151]
	global_load_lds_dwordx4 v[202:203], off
	v_lshl_add_u64 v[202:203], s[66:67], 0, v[152:153]
	s_add_i32 m0, s76, 0x2000
	s_nop 0
	global_load_lds_dwordx4 v[202:203], off
	v_lshl_add_u64 v[202:203], s[72:73], 0, v[148:149]
	s_mov_b32 m0, s5
	s_nop 0
	global_load_lds_dwordx4 v[202:203], off
	s_mov_b32 m0, s6
	s_nop 0
	global_load_lds_dwordx4 v[206:207], off
	ds_read_b128 v[182:185], v214 offset:16384
	ds_read_b128 v[186:189], v214 offset:17408
	ds_read_b128 v[190:193], v214 offset:18432
	ds_read_b128 v[194:197], v214 offset:19456
	ds_read_b128 v[198:201], v214 offset:20480
	ds_read_b128 v[216:219], v214 offset:21504
	ds_read_b128 v[220:223], v214 offset:22528
	ds_read_b128 v[224:227], v214 offset:23552
	s_waitcnt vmcnt(8)
	s_waitcnt lgkmcnt(0)
	s_setprio 1
	s_barrier
; #define PG8_STAGE(bufoff, gbase, voff) do { _Pragma("unroll") for (int _i = 0; _i < 2; ++_i) \
;         __builtin_amdgcn_global_load_lds((const unsigned*)((const char*)(gbase) + (voff)[_i]), (LAS unsigned*)(lds + (bufoff) + ldsw + _i * 8192), 16, 0, 0); } while (0)
; #define PG8_LDA(dst, b, h) do { _Pragma("unroll") for (int m = 0; m < 4; ++m) _Pragma("unroll") for (int k = 0; k < 2; ++k) dst[m][k] = *(const LAS bf16x8*)(lds + PG8_SA(b, h) + aoff + m * 2048 + k * 1024); } while (0)
; #define PG8_LDB(dst, b, h) do { _Pragma("unroll") for (int n = 0; n < 2; ++n) _Pragma("unroll") for (int k = 0; k < 2; ++k) dst[n][k] = *(const LAS bf16x8*)(lds + PG8_SB(b, h) + boff + n * 2048 + k * 1024); } while (0)
; #define PG8_MMA(ai, bj, At, Bt) do { __builtin_amdgcn_s_setprio(1); _Pragma("unroll") for (int m = 0; m < 4; ++m) _Pragma("unroll") for (int n = 0; n < 2; ++n) _Pragma("unroll") for (int k = 0; k < 2; ++k) \
;         acc[ai][bj][m][n] = __builtin_amdgcn_mfma_f32_16x16x32_bf16(Bt[n][k], At[m][k], acc[ai][bj][m][n], 0, 0, 0); __builtin_amdgcn_s_setprio(0); } while (0)
; #define PG8_WAIT_V(n) asm volatile("s_waitcnt vmcnt(" #n ")" ::: "memory")
; #define PG8_WAIT_L(n) asm volatile("s_waitcnt lgkmcnt(" #n ")" ::: "memory")
; #define PG8_BAR __builtin_amdgcn_s_barrier()
; #define PG8_SCHED __builtin_amdgcn_sched_barrier(0)
; template <class Epi>
; __device__ __forceinline__ void gemm_phase(LAS unsigned char* lds, const int tid, const Gemm g, const StaticOrder& S, const Epi& E) {
;     ...
;             PG8_WAIT_V(8); PG8_WAIT_L(0); PG8_BAR; PG8_MMA(1, 0, At, B0); PG8_MMA(1, 1, At, B1); PG8_BAR; PG8_SCHED;
;             PG8_LDB(B0, 1, 0); PG8_LDB(B1, 1, 1); PG8_SCHED; PG8_LDA(At, 1, 0); PG8_STAGE(PG8_SA(0, 1), a2 + hstepA, voffA);
;             PG8_WAIT_V(8); PG8_WAIT_L(0); PG8_BAR; PG8_MMA(0, 0, At, B0); PG8_MMA(0, 1, At, B1); PG8_BAR; PG8_SCHED;
	v_mfma_f32_16x16x32_bf16 v[78:81], v[42:45], v[182:185], v[78:81]
	v_mfma_f32_16x16x32_bf16 v[74:77], v[66:69], v[182:185], v[74:77]
	v_mfma_f32_16x16x32_bf16 v[54:57], v[42:45], v[190:193], v[54:57]
	v_mfma_f32_16x16x32_bf16 v[50:53], v[66:69], v[190:193], v[50:53]
	v_mfma_f32_16x16x32_bf16 v[30:33], v[42:45], v[198:201], v[30:33]
	v_mfma_f32_16x16x32_bf16 v[26:29], v[66:69], v[198:201], v[26:29]
	v_mfma_f32_16x16x32_bf16 v[14:17], v[42:45], v[220:223], v[14:17]
	v_mfma_f32_16x16x32_bf16 v[10:13], v[66:69], v[220:223], v[10:13]
	v_mfma_f32_16x16x32_bf16 v[78:81], v[46:49], v[186:189], v[78:81]
	v_mfma_f32_16x16x32_bf16 v[74:77], v[70:73], v[186:189], v[74:77]
	v_mfma_f32_16x16x32_bf16 v[54:57], v[46:49], v[194:197], v[54:57]
	v_mfma_f32_16x16x32_bf16 v[50:53], v[70:73], v[194:197], v[50:53]
	v_mfma_f32_16x16x32_bf16 v[30:33], v[46:49], v[216:219], v[30:33]
	v_mfma_f32_16x16x32_bf16 v[26:29], v[70:73], v[216:219], v[26:29]
	v_mfma_f32_16x16x32_bf16 v[14:17], v[46:49], v[224:227], v[14:17]
	v_mfma_f32_16x16x32_bf16 v[10:13], v[70:73], v[224:227], v[10:13]
	s_setprio 0
	s_setprio 1
	v_mfma_f32_16x16x32_bf16 v[38:41], v[158:161], v[190:193], v[38:41]
	v_mfma_f32_16x16x32_bf16 v[34:37], v[174:177], v[190:193], v[34:37]
	v_mfma_f32_16x16x32_bf16 v[22:25], v[158:161], v[198:201], v[22:25]
	v_mfma_f32_16x16x32_bf16 v[18:21], v[174:177], v[198:201], v[18:21]
	v_mfma_f32_16x16x32_bf16 v[6:9], v[158:161], v[220:223], v[6:9]
	v_mfma_f32_16x16x32_bf16 v[2:5], v[174:177], v[220:223], v[2:5]
	v_mfma_f32_16x16x32_bf16 v[42:45], v[158:161], v[182:185], v[62:65]
	v_mfma_f32_16x16x32_bf16 v[46:49], v[174:177], v[182:185], v[58:61]
	v_mfma_f32_16x16x32_bf16 v[38:41], v[170:173], v[194:197], v[38:41]
	v_mfma_f32_16x16x32_bf16 v[34:37], v[178:181], v[194:197], v[34:37]
	v_mfma_f32_16x16x32_bf16 v[22:25], v[170:173], v[216:219], v[22:25]
	v_mfma_f32_16x16x32_bf16 v[18:21], v[178:181], v[216:219], v[18:21]
	v_mfma_f32_16x16x32_bf16 v[6:9], v[170:173], v[224:227], v[6:9]
	v_mfma_f32_16x16x32_bf16 v[2:5], v[178:181], v[224:227], v[2:5]
	v_mfma_f32_16x16x32_bf16 v[42:45], v[170:173], v[186:189], v[42:45]
	v_mfma_f32_16x16x32_bf16 v[46:49], v[178:181], v[186:189], v[46:49]
	s_barrier
	s_setprio 0
	s_add_i32 s76, 0, 0x18000
	s_add_i32 vcc_lo, 0, 0x1c000
	v_add_u32_e32 v70, s76, v212
	v_add_u32_e32 v178, vcc_lo, v212
	ds_read_b128 v[58:61], v70
	ds_read_b128 v[62:65], v70 offset:1024
	ds_read_b128 v[66:69], v70 offset:2048
	ds_read_b128 v[70:73], v70 offset:3072
	ds_read_b128 v[158:161], v178
	ds_read_b128 v[170:173], v178 offset:1024
	ds_read_b128 v[174:177], v178 offset:2048
	ds_read_b128 v[178:181], v178 offset:3072
	s_add_u32 s66, s72, 0x160000
	s_addc_u32 s67, s73, 0
	s_mov_b32 m0, s7
	v_lshl_add_u64 v[228:229], s[66:67], 0, v[148:149]
	global_load_lds_dwordx4 v[228:229], off
	v_lshl_add_u64 v[228:229], s[66:67], 0, v[150:151]
	s_mov_b32 m0, s74
	s_nop 0
	global_load_lds_dwordx4 v[228:229], off
	ds_read_b128 v[182:185], v214 offset:32768
	ds_read_b128 v[186:189], v214 offset:33792
	ds_read_b128 v[190:193], v214 offset:34816
	ds_read_b128 v[194:197], v214 offset:35840
	ds_read_b128 v[198:201], v214 offset:36864
	ds_read_b128 v[216:219], v214 offset:37888
	ds_read_b128 v[220:223], v214 offset:38912
	ds_read_b128 v[224:227], v214 offset:39936
	s_waitcnt vmcnt(8)
	s_waitcnt lgkmcnt(0)
	s_setprio 1
	s_barrier
	v_mfma_f32_16x16x32_bf16 v[142:145], v[58:61], v[182:185], v[142:145]
	v_mfma_f32_16x16x32_bf16 v[138:141], v[66:69], v[182:185], v[138:141]
	v_mfma_f32_16x16x32_bf16 v[126:129], v[58:61], v[190:193], v[126:129]
	v_mfma_f32_16x16x32_bf16 v[122:125], v[66:69], v[190:193], v[122:125]
	v_mfma_f32_16x16x32_bf16 v[110:113], v[58:61], v[198:201], v[110:113]
	v_mfma_f32_16x16x32_bf16 v[106:109], v[66:69], v[198:201], v[106:109]
	v_mfma_f32_16x16x32_bf16 v[94:97], v[58:61], v[220:223], v[94:97]
	v_mfma_f32_16x16x32_bf16 v[90:93], v[66:69], v[220:223], v[90:93]
	v_mfma_f32_16x16x32_bf16 v[142:145], v[62:65], v[186:189], v[142:145]
	v_mfma_f32_16x16x32_bf16 v[138:141], v[70:73], v[186:189], v[138:141]
	v_mfma_f32_16x16x32_bf16 v[126:129], v[62:65], v[194:197], v[126:129]
	v_mfma_f32_16x16x32_bf16 v[122:125], v[70:73], v[194:197], v[122:125]
	v_mfma_f32_16x16x32_bf16 v[110:113], v[62:65], v[216:219], v[110:113]
	v_mfma_f32_16x16x32_bf16 v[106:109], v[70:73], v[216:219], v[106:109]
	v_mfma_f32_16x16x32_bf16 v[94:97], v[62:65], v[224:227], v[94:97]
	v_mfma_f32_16x16x32_bf16 v[90:93], v[70:73], v[224:227], v[90:93]
	s_setprio 0
	s_setprio 1
	v_mfma_f32_16x16x32_bf16 v[134:137], v[158:161], v[182:185], v[134:137]
	v_mfma_f32_16x16x32_bf16 v[130:133], v[174:177], v[182:185], v[130:133]
	v_mfma_f32_16x16x32_bf16 v[118:121], v[158:161], v[190:193], v[118:121]
	v_mfma_f32_16x16x32_bf16 v[114:117], v[174:177], v[190:193], v[114:117]
	v_mfma_f32_16x16x32_bf16 v[102:105], v[158:161], v[198:201], v[102:105]
	v_mfma_f32_16x16x32_bf16 v[98:101], v[174:177], v[198:201], v[98:101]
	v_mfma_f32_16x16x32_bf16 v[86:89], v[158:161], v[220:223], v[86:89]
	v_mfma_f32_16x16x32_bf16 v[82:85], v[174:177], v[220:223], v[82:85]
	v_mfma_f32_16x16x32_bf16 v[134:137], v[170:173], v[186:189], v[134:137]
	v_mfma_f32_16x16x32_bf16 v[130:133], v[178:181], v[186:189], v[130:133]
	v_mfma_f32_16x16x32_bf16 v[118:121], v[170:173], v[194:197], v[118:121]
	v_mfma_f32_16x16x32_bf16 v[114:117], v[178:181], v[194:197], v[114:117]
	v_mfma_f32_16x16x32_bf16 v[102:105], v[170:173], v[216:219], v[102:105]
	v_mfma_f32_16x16x32_bf16 v[98:101], v[178:181], v[216:219], v[98:101]
	v_mfma_f32_16x16x32_bf16 v[86:89], v[170:173], v[224:227], v[86:89]
	v_mfma_f32_16x16x32_bf16 v[82:85], v[178:181], v[224:227], v[82:85]
	s_barrier
; #define PG8_STAGE(bufoff, gbase, voff) do { _Pragma("unroll") for (int _i = 0; _i < 2; ++_i) \
;         __builtin_amdgcn_global_load_lds((const unsigned*)((const char*)(gbase) + (voff)[_i]), (LAS unsigned*)(lds + (bufoff) + ldsw + _i * 8192), 16, 0, 0); } while (0)
; #define PG8_LDA(dst, b, h) do { _Pragma("unroll") for (int m = 0; m < 4; ++m) _Pragma("unroll") for (int k = 0; k < 2; ++k) dst[m][k] = *(const LAS bf16x8*)(lds + PG8_SA(b, h) + aoff + m * 2048 + k * 1024); } while (0)
; #define PG8_MMA(ai, bj, At, Bt) do { __builtin_amdgcn_s_setprio(1); _Pragma("unroll") for (int m = 0; m < 4; ++m) _Pragma("unroll") for (int n = 0; n < 2; ++n) _Pragma("unroll") for (int k = 0; k < 2; ++k) \
;         acc[ai][bj][m][n] = __builtin_amdgcn_mfma_f32_16x16x32_bf16(Bt[n][k], At[m][k], acc[ai][bj][m][n], 0, 0, 0); __builtin_amdgcn_s_setprio(0); } while (0)
; #define PG8_WAIT_V(n) asm volatile("s_waitcnt vmcnt(" #n ")" ::: "memory")
; #define PG8_WAIT_L(n) asm volatile("s_waitcnt lgkmcnt(" #n ")" ::: "memory")
; #define PG8_BAR __builtin_amdgcn_s_barrier()
; #define PG8_SCHED __builtin_amdgcn_sched_barrier(0)
; template <class Epi>
; __device__ __forceinline__ void gemm_phase(LAS unsigned char* lds, const int tid, const Gemm g, const StaticOrder& S, const Epi& E) {
;     ...
;             PG8_LDA(At, 1, 1); PG8_STAGE(PG8_SB(1, 0), b3, voffB); PG8_STAGE(PG8_SB(1, 1), b3 + hstepB, voffB); PG8_STAGE(PG8_SA(1, 0), a3, voffA);
;             PG8_WAIT_V(8); PG8_WAIT_L(0); PG8_BAR; PG8_MMA(1, 0, At, B0); PG8_MMA(1, 1, At, B1); PG8_BAR; PG8_SCHED;
;         }
;         if (wr == 0) PG8_BAR;
	s_setprio 0
	s_add_i32 s66, s76, s4
	v_lshl_add_u64 v[162:163], v[162:163], 0, s[36:37]
	s_mov_b32 m0, s66
	s_nop 0
	global_load_lds_dwordx4 v[162:163], off
	s_add_i32 m0, s66, 0x2000
	s_add_u32 s66, s70, 0xb0080
	v_lshl_add_u64 v[162:163], v[164:165], 0, s[36:37]
	s_addc_u32 s67, s71, 0
	s_add_i32 s70, vcc_lo, s4
	global_load_lds_dwordx4 v[162:163], off
	v_lshl_add_u64 v[162:163], s[66:67], 0, v[0:1]
	s_mov_b32 m0, s70
	s_nop 0
	global_load_lds_dwordx4 v[162:163], off
	v_lshl_add_u64 v[162:163], s[66:67], 0, v[152:153]
	s_add_i32 m0, s70, 0x2000
	s_nop 0
	global_load_lds_dwordx4 v[162:163], off
	v_lshl_add_u64 v[162:163], v[202:203], 0, s[36:37]
	s_mov_b32 m0, s77
	s_nop 0
	global_load_lds_dwordx4 v[162:163], off
	v_lshl_add_u64 v[162:163], v[206:207], 0, s[36:37]
	s_mov_b32 m0, s79
	s_nop 0
	global_load_lds_dwordx4 v[162:163], off
	ds_read_b128 v[182:185], v214 offset:49152
	ds_read_b128 v[186:189], v214 offset:50176
	ds_read_b128 v[190:193], v214 offset:51200
	ds_read_b128 v[194:197], v214 offset:52224
	ds_read_b128 v[198:201], v214 offset:53248
	ds_read_b128 v[216:219], v214 offset:54272
	ds_read_b128 v[220:223], v214 offset:55296
	ds_read_b128 v[224:227], v214 offset:56320
	s_waitcnt vmcnt(8)
	s_waitcnt lgkmcnt(0)
	s_setprio 1
	s_barrier
	v_mfma_f32_16x16x32_bf16 v[78:81], v[58:61], v[182:185], v[78:81]
	v_mfma_f32_16x16x32_bf16 v[74:77], v[66:69], v[182:185], v[74:77]
	v_mfma_f32_16x16x32_bf16 v[54:57], v[58:61], v[190:193], v[54:57]
	v_mfma_f32_16x16x32_bf16 v[50:53], v[66:69], v[190:193], v[50:53]
	v_mfma_f32_16x16x32_bf16 v[30:33], v[58:61], v[198:201], v[30:33]
	v_mfma_f32_16x16x32_bf16 v[26:29], v[66:69], v[198:201], v[26:29]
	v_mfma_f32_16x16x32_bf16 v[14:17], v[58:61], v[220:223], v[14:17]
	v_mfma_f32_16x16x32_bf16 v[10:13], v[66:69], v[220:223], v[10:13]
	v_mfma_f32_16x16x32_bf16 v[78:81], v[62:65], v[186:189], v[78:81]
	v_mfma_f32_16x16x32_bf16 v[74:77], v[70:73], v[186:189], v[74:77]
	v_mfma_f32_16x16x32_bf16 v[54:57], v[62:65], v[194:197], v[54:57]
	v_mfma_f32_16x16x32_bf16 v[50:53], v[70:73], v[194:197], v[50:53]
	v_mfma_f32_16x16x32_bf16 v[30:33], v[62:65], v[216:219], v[30:33]
	v_mfma_f32_16x16x32_bf16 v[26:29], v[70:73], v[216:219], v[26:29]
	v_mfma_f32_16x16x32_bf16 v[14:17], v[62:65], v[224:227], v[14:17]
	v_mfma_f32_16x16x32_bf16 v[10:13], v[70:73], v[224:227], v[10:13]
	s_setprio 0
	s_setprio 1
	v_mfma_f32_16x16x32_bf16 v[42:45], v[158:161], v[182:185], v[42:45]
	v_mfma_f32_16x16x32_bf16 v[62:65], v[170:173], v[186:189], v[42:45]
	v_mfma_f32_16x16x32_bf16 v[42:45], v[174:177], v[182:185], v[46:49]
	v_mfma_f32_16x16x32_bf16 v[38:41], v[158:161], v[190:193], v[38:41]
	v_mfma_f32_16x16x32_bf16 v[34:37], v[174:177], v[190:193], v[34:37]
	v_mfma_f32_16x16x32_bf16 v[22:25], v[158:161], v[198:201], v[22:25]
	v_mfma_f32_16x16x32_bf16 v[18:21], v[174:177], v[198:201], v[18:21]
	v_mfma_f32_16x16x32_bf16 v[6:9], v[158:161], v[220:223], v[6:9]
	v_mfma_f32_16x16x32_bf16 v[2:5], v[174:177], v[220:223], v[2:5]
	v_mfma_f32_16x16x32_bf16 v[58:61], v[178:181], v[186:189], v[42:45]
	v_mfma_f32_16x16x32_bf16 v[38:41], v[170:173], v[194:197], v[38:41]
	v_mfma_f32_16x16x32_bf16 v[34:37], v[178:181], v[194:197], v[34:37]
	v_mfma_f32_16x16x32_bf16 v[22:25], v[170:173], v[216:219], v[22:25]
	v_mfma_f32_16x16x32_bf16 v[18:21], v[178:181], v[216:219], v[18:21]
	v_mfma_f32_16x16x32_bf16 v[6:9], v[170:173], v[224:227], v[6:9]
	v_mfma_f32_16x16x32_bf16 v[2:5], v[178:181], v[224:227], v[2:5]
	s_barrier
	s_setprio 0
	s_add_i32 s93, s93, 2
	s_add_u32 s11, s11, 0x100
	s_addc_u32 s28, s28, 0
	s_cmp_gt_u32 s93, 41
	s_mov_b64 s[66:67], s[68:69]
	s_cbranch_scc0 .LBB0_2303
	s_and_b64 vcc, exec, s[26:27]
	s_cbranch_vccz .LBB0_2306
	s_barrier

; #define PG8_STAGE(bufoff, gbase, voff) do { _Pragma("unroll") for (int _i = 0; _i < 2; ++_i) \
;         __builtin_amdgcn_global_load_lds((const unsigned*)((const char*)(gbase) + (voff)[_i]), (LAS unsigned*)(lds + (bufoff) + ldsw + _i * 8192), 16, 0, 0); } while (0)
; #define PG8_LDA(dst, b, h) do { _Pragma("unroll") for (int m = 0; m < 4; ++m) _Pragma("unroll") for (int k = 0; k < 2; ++k) dst[m][k] = *(const LAS bf16x8*)(lds + PG8_SA(b, h) + aoff + m * 2048 + k * 1024); } while (0)
; #define PG8_LDB(dst, b, h) do { _Pragma("unroll") for (int n = 0; n < 2; ++n) _Pragma("unroll") for (int k = 0; k < 2; ++k) dst[n][k] = *(const LAS bf16x8*)(lds + PG8_SB(b, h) + boff + n * 2048 + k * 1024); } while (0)
; #define PG8_MMA(ai, bj, At, Bt) do { __builtin_amdgcn_s_setprio(1); _Pragma("unroll") for (int m = 0; m < 4; ++m) _Pragma("unroll") for (int n = 0; n < 2; ++n) _Pragma("unroll") for (int k = 0; k < 2; ++k) \
;         acc[ai][bj][m][n] = __builtin_amdgcn_mfma_f32_16x16x32_bf16(Bt[n][k], At[m][k], acc[ai][bj][m][n], 0, 0, 0); __builtin_amdgcn_s_setprio(0); } while (0)
; #define PG8_WAIT_V(n) asm volatile("s_waitcnt vmcnt(" #n ")" ::: "memory")
; #define PG8_WAIT_L(n) asm volatile("s_waitcnt lgkmcnt(" #n ")" ::: "memory")
; #define PG8_BAR __builtin_amdgcn_s_barrier()
; #define PG8_SCHED __builtin_amdgcn_sched_barrier(0)
; template <class Epi>
; __device__ __forceinline__ void gemm_phase(LAS unsigned char* lds, const int tid, const Gemm g, const StaticOrder& S, const Epi& E) {
;     ...
;             const bool last = (t == nt - 2);
;             const char* a1 = cA + (size_t)(t + 1) * kstep;
;             const char* a2 = last ? nA : cA + (size_t)(t + 2) * kstep; const char* b2 = last ? nB : cB + (size_t)(t + 2) * kstep;
;             const char* a3 = a2 + kstep; const char* b3 = b2 + kstep;
;             PG8_LDB(B0, 0, 0); PG8_LDB(B1, 0, 1); PG8_SCHED; PG8_LDA(At, 0, 0); PG8_STAGE(PG8_SA(1, 1), a1 + hstepA, voffA);
;             PG8_WAIT_V(8); PG8_WAIT_L(0); PG8_BAR; PG8_MMA(0, 0, At, B0); PG8_MMA(0, 1, At, B1); PG8_BAR; PG8_SCHED;
;             PG8_LDA(At, 0, 1); PG8_STAGE(PG8_SB(0, 0), b2, voffB); PG8_STAGE(PG8_SB(0, 1), b2 + hstepB, voffB); PG8_STAGE(PG8_SA(0, 0), a2, voffA);
;             PG8_WAIT_V(8); PG8_WAIT_L(0); PG8_BAR; PG8_MMA(1, 0, At, B0); PG8_MMA(1, 1, At, B1); PG8_BAR; PG8_SCHED;
.LBB0_2353:
	s_add_u32 s70, s68, 0x100
	s_addc_u32 s71, s69, 0
	s_add_i32 s76, 0, 0x10000
	s_cmp_eq_u32 vcc_hi, 40
	s_cselect_b32 s75, s1, s71
	s_cselect_b32 s74, s0, s70
	s_cselect_b32 s73, s31, vcc_lo
	s_cselect_b32 s72, s30, s11
	s_add_i32 s2, 0, 0x14000
	v_add_u32_e32 v154, s76, v199
	v_add_u32_e32 v162, s2, v199
	ds_read_b128 v[130:133], v154
	ds_read_b128 v[134:137], v154 offset:1024
	ds_read_b128 v[138:141], v154 offset:2048
	ds_read_b128 v[154:157], v154 offset:3072
	ds_read_b128 v[158:161], v162
	ds_read_b128 v[170:173], v162 offset:1024
	ds_read_b128 v[174:177], v162 offset:2048
	ds_read_b128 v[212:215], v162 offset:3072
	v_lshl_add_u64 v[162:163], s[68:69], 0, v[150:151]
	s_add_i32 m0, s83, 0xc000
	s_nop 0
	global_load_lds_dwordx4 v[162:163], off
	v_lshl_add_u64 v[162:163], s[68:69], 0, v[152:153]
	s_add_i32 m0, s83, 0xe000
	s_nop 0
	global_load_lds_dwordx4 v[162:163], off
	ds_read_b128 v[216:219], v201
	ds_read_b128 v[220:223], v201 offset:1024
	ds_read_b128 v[224:227], v201 offset:2048
	ds_read_b128 v[228:231], v201 offset:3072
	ds_read_b128 v[232:235], v201 offset:4096
	ds_read_b128 v[236:239], v201 offset:5120
	ds_read_b128 v[240:243], v201 offset:6144
	ds_read_b128 v[244:247], v201 offset:7168
	s_waitcnt vmcnt(8)
	s_waitcnt lgkmcnt(0)
	s_setprio 1
	s_barrier
	v_mfma_f32_16x16x32_bf16 v[126:129], v[130:133], v[216:219], v[126:129]
	v_mfma_f32_16x16x32_bf16 v[122:125], v[138:141], v[216:219], v[122:125]
	v_mfma_f32_16x16x32_bf16 v[110:113], v[130:133], v[224:227], v[110:113]
	v_mfma_f32_16x16x32_bf16 v[106:109], v[138:141], v[224:227], v[106:109]
	v_mfma_f32_16x16x32_bf16 v[94:97], v[130:133], v[232:235], v[94:97]
	v_mfma_f32_16x16x32_bf16 v[90:93], v[138:141], v[232:235], v[90:93]
	v_mfma_f32_16x16x32_bf16 v[78:81], v[130:133], v[240:243], v[78:81]
	v_mfma_f32_16x16x32_bf16 v[74:77], v[138:141], v[240:243], v[74:77]
	v_mfma_f32_16x16x32_bf16 v[126:129], v[134:137], v[220:223], v[126:129]
	v_mfma_f32_16x16x32_bf16 v[122:125], v[154:157], v[220:223], v[122:125]
	v_mfma_f32_16x16x32_bf16 v[110:113], v[134:137], v[228:231], v[110:113]
	v_mfma_f32_16x16x32_bf16 v[106:109], v[154:157], v[228:231], v[106:109]
	v_mfma_f32_16x16x32_bf16 v[94:97], v[134:137], v[236:239], v[94:97]
	v_mfma_f32_16x16x32_bf16 v[90:93], v[154:157], v[236:239], v[90:93]
	v_mfma_f32_16x16x32_bf16 v[78:81], v[134:137], v[244:247], v[78:81]
	v_mfma_f32_16x16x32_bf16 v[74:77], v[154:157], v[244:247], v[74:77]
	s_setprio 0
	s_setprio 1
	v_mfma_f32_16x16x32_bf16 v[118:121], v[158:161], v[216:219], v[118:121]
	v_mfma_f32_16x16x32_bf16 v[114:117], v[174:177], v[216:219], v[114:117]
	v_mfma_f32_16x16x32_bf16 v[102:105], v[158:161], v[224:227], v[102:105]
	v_mfma_f32_16x16x32_bf16 v[98:101], v[174:177], v[224:227], v[98:101]
	v_mfma_f32_16x16x32_bf16 v[86:89], v[158:161], v[232:235], v[86:89]
	v_mfma_f32_16x16x32_bf16 v[82:85], v[174:177], v[232:235], v[82:85]
	v_mfma_f32_16x16x32_bf16 v[70:73], v[158:161], v[240:243], v[70:73]
	v_mfma_f32_16x16x32_bf16 v[66:69], v[174:177], v[240:243], v[66:69]
	v_mfma_f32_16x16x32_bf16 v[118:121], v[170:173], v[220:223], v[118:121]
	v_mfma_f32_16x16x32_bf16 v[114:117], v[212:215], v[220:223], v[114:117]
	v_mfma_f32_16x16x32_bf16 v[102:105], v[170:173], v[228:231], v[102:105]
	v_mfma_f32_16x16x32_bf16 v[98:101], v[212:215], v[228:231], v[98:101]
	v_mfma_f32_16x16x32_bf16 v[86:89], v[170:173], v[236:239], v[86:89]
	v_mfma_f32_16x16x32_bf16 v[82:85], v[212:215], v[236:239], v[82:85]
	v_mfma_f32_16x16x32_bf16 v[70:73], v[170:173], v[244:247], v[70:73]
	v_mfma_f32_16x16x32_bf16 v[66:69], v[212:215], v[244:247], v[66:69]
	s_barrier
	s_setprio 0
	s_add_i32 s3, s76, s82
	v_lshl_add_u64 v[162:163], s[72:73], 0, v[0:1]
	s_mov_b32 m0, s3
	s_nop 0
	global_load_lds_dwordx4 v[162:163], off
	s_add_i32 m0, s3, 0x2000
	s_add_u32 s68, s72, 0xb0000
	v_lshl_add_u64 v[164:165], s[72:73], 0, v[142:143]
	s_addc_u32 s69, s73, 0
	s_add_i32 s2, s2, s82
	global_load_lds_dwordx4 v[164:165], off
	v_lshl_add_u64 v[178:179], s[68:69], 0, v[0:1]
	s_mov_b32 m0, s2
	v_lshl_add_u64 v[206:207], s[74:75], 0, v[148:149]
	global_load_lds_dwordx4 v[178:179], off
	v_lshl_add_u64 v[178:179], s[68:69], 0, v[142:143]
	s_add_i32 m0, s2, 0x2000
	s_nop 0
	global_load_lds_dwordx4 v[178:179], off
	v_lshl_add_u64 v[178:179], s[74:75], 0, v[144:145]
	s_mov_b32 m0, s83
	s_nop 0
	global_load_lds_dwordx4 v[178:179], off
	s_mov_b32 m0, s88
	s_nop 0
	global_load_lds_dwordx4 v[206:207], off
	ds_read_b128 v[216:219], v201 offset:16384
	ds_read_b128 v[220:223], v201 offset:17408
	ds_read_b128 v[224:227], v201 offset:18432
	ds_read_b128 v[228:231], v201 offset:19456
	ds_read_b128 v[232:235], v201 offset:20480
	ds_read_b128 v[236:239], v201 offset:21504
	ds_read_b128 v[240:243], v201 offset:22528
	ds_read_b128 v[244:247], v201 offset:23552
	s_waitcnt vmcnt(8)
	s_waitcnt lgkmcnt(0)
	s_setprio 1
	s_barrier
; #define PG8_STAGE(bufoff, gbase, voff) do { _Pragma("unroll") for (int _i = 0; _i < 2; ++_i) \
;         __builtin_amdgcn_global_load_lds((const unsigned*)((const char*)(gbase) + (voff)[_i]), (LAS unsigned*)(lds + (bufoff) + ldsw + _i * 8192), 16, 0, 0); } while (0)
; #define PG8_LDA(dst, b, h) do { _Pragma("unroll") for (int m = 0; m < 4; ++m) _Pragma("unroll") for (int k = 0; k < 2; ++k) dst[m][k] = *(const LAS bf16x8*)(lds + PG8_SA(b, h) + aoff + m * 2048 + k * 1024); } while (0)
; #define PG8_LDB(dst, b, h) do { _Pragma("unroll") for (int n = 0; n < 2; ++n) _Pragma("unroll") for (int k = 0; k < 2; ++k) dst[n][k] = *(const LAS bf16x8*)(lds + PG8_SB(b, h) + boff + n * 2048 + k * 1024); } while (0)
; #define PG8_MMA(ai, bj, At, Bt) do { __builtin_amdgcn_s_setprio(1); _Pragma("unroll") for (int m = 0; m < 4; ++m) _Pragma("unroll") for (int n = 0; n < 2; ++n) _Pragma("unroll") for (int k = 0; k < 2; ++k) \
;         acc[ai][bj][m][n] = __builtin_amdgcn_mfma_f32_16x16x32_bf16(Bt[n][k], At[m][k], acc[ai][bj][m][n], 0, 0, 0); __builtin_amdgcn_s_setprio(0); } while (0)
; #define PG8_WAIT_V(n) asm volatile("s_waitcnt vmcnt(" #n ")" ::: "memory")
; #define PG8_WAIT_L(n) asm volatile("s_waitcnt lgkmcnt(" #n ")" ::: "memory")
; #define PG8_BAR __builtin_amdgcn_s_barrier()
; #define PG8_SCHED __builtin_amdgcn_sched_barrier(0)
; template <class Epi>
; __device__ __forceinline__ void gemm_phase(LAS unsigned char* lds, const int tid, const Gemm g, const StaticOrder& S, const Epi& E) {
;     ...
;             PG8_WAIT_V(8); PG8_WAIT_L(0); PG8_BAR; PG8_MMA(1, 0, At, B0); PG8_MMA(1, 1, At, B1); PG8_BAR; PG8_SCHED;
;             PG8_LDB(B0, 1, 0); PG8_LDB(B1, 1, 1); PG8_SCHED; PG8_LDA(At, 1, 0); PG8_STAGE(PG8_SA(0, 1), a2 + hstepA, voffA);
;             PG8_WAIT_V(8); PG8_WAIT_L(0); PG8_BAR; PG8_MMA(0, 0, At, B0); PG8_MMA(0, 1, At, B1); PG8_BAR; PG8_SCHED;
	v_mfma_f32_16x16x32_bf16 v[62:65], v[130:133], v[216:219], v[62:65]
	v_mfma_f32_16x16x32_bf16 v[58:61], v[138:141], v[216:219], v[58:61]
	v_mfma_f32_16x16x32_bf16 v[46:49], v[130:133], v[224:227], v[46:49]
	v_mfma_f32_16x16x32_bf16 v[42:45], v[138:141], v[224:227], v[42:45]
	v_mfma_f32_16x16x32_bf16 v[30:33], v[130:133], v[232:235], v[30:33]
	v_mfma_f32_16x16x32_bf16 v[26:29], v[138:141], v[232:235], v[26:29]
	v_mfma_f32_16x16x32_bf16 v[14:17], v[130:133], v[240:243], v[14:17]
	v_mfma_f32_16x16x32_bf16 v[10:13], v[138:141], v[240:243], v[10:13]
	v_mfma_f32_16x16x32_bf16 v[62:65], v[134:137], v[220:223], v[62:65]
	v_mfma_f32_16x16x32_bf16 v[58:61], v[154:157], v[220:223], v[58:61]
	v_mfma_f32_16x16x32_bf16 v[46:49], v[134:137], v[228:231], v[46:49]
	v_mfma_f32_16x16x32_bf16 v[42:45], v[154:157], v[228:231], v[42:45]
	v_mfma_f32_16x16x32_bf16 v[30:33], v[134:137], v[236:239], v[30:33]
	v_mfma_f32_16x16x32_bf16 v[26:29], v[154:157], v[236:239], v[26:29]
	v_mfma_f32_16x16x32_bf16 v[14:17], v[134:137], v[244:247], v[14:17]
	v_mfma_f32_16x16x32_bf16 v[10:13], v[154:157], v[244:247], v[10:13]
	s_setprio 0
	s_setprio 1
	v_mfma_f32_16x16x32_bf16 v[54:57], v[158:161], v[216:219], v[54:57]
	v_mfma_f32_16x16x32_bf16 v[50:53], v[174:177], v[216:219], v[50:53]
	v_mfma_f32_16x16x32_bf16 v[38:41], v[158:161], v[224:227], v[38:41]
	v_mfma_f32_16x16x32_bf16 v[34:37], v[174:177], v[224:227], v[34:37]
	v_mfma_f32_16x16x32_bf16 v[22:25], v[158:161], v[232:235], v[22:25]
	v_mfma_f32_16x16x32_bf16 v[18:21], v[174:177], v[232:235], v[18:21]
	v_mfma_f32_16x16x32_bf16 v[6:9], v[158:161], v[240:243], v[6:9]
	v_mfma_f32_16x16x32_bf16 v[2:5], v[174:177], v[240:243], v[2:5]
	v_mfma_f32_16x16x32_bf16 v[54:57], v[170:173], v[220:223], v[54:57]
	v_mfma_f32_16x16x32_bf16 v[50:53], v[212:215], v[220:223], v[50:53]
	v_mfma_f32_16x16x32_bf16 v[38:41], v[170:173], v[228:231], v[38:41]
	v_mfma_f32_16x16x32_bf16 v[34:37], v[212:215], v[228:231], v[34:37]
	v_mfma_f32_16x16x32_bf16 v[22:25], v[170:173], v[236:239], v[22:25]
	v_mfma_f32_16x16x32_bf16 v[18:21], v[212:215], v[236:239], v[18:21]
	v_mfma_f32_16x16x32_bf16 v[6:9], v[170:173], v[244:247], v[6:9]
	v_mfma_f32_16x16x32_bf16 v[2:5], v[212:215], v[244:247], v[2:5]
	s_barrier
	s_setprio 0
	s_add_i32 s2, 0, 0x18000
	s_add_i32 s3, 0, 0x1c000
	v_add_u32_e32 v154, s2, v199
	v_add_u32_e32 v192, s3, v199
	ds_read_b128 v[130:133], v154
	ds_read_b128 v[134:137], v154 offset:1024
	ds_read_b128 v[138:141], v154 offset:2048
	ds_read_b128 v[154:157], v154 offset:3072
	ds_read_b128 v[158:161], v192
	ds_read_b128 v[170:173], v192 offset:1024
	ds_read_b128 v[174:177], v192 offset:2048
	ds_read_b128 v[212:215], v192 offset:3072
	s_add_u32 s68, s74, 0x160000
	s_addc_u32 s69, s75, 0
	s_mov_b32 m0, s89
	v_lshl_add_u64 v[192:193], s[68:69], 0, v[144:145]
	global_load_lds_dwordx4 v[192:193], off
	v_lshl_add_u64 v[192:193], s[68:69], 0, v[148:149]
	s_mov_b32 m0, s92
	s_nop 0
	global_load_lds_dwordx4 v[192:193], off
	ds_read_b128 v[216:219], v201 offset:32768
	ds_read_b128 v[220:223], v201 offset:33792
	ds_read_b128 v[224:227], v201 offset:34816
	ds_read_b128 v[228:231], v201 offset:35840
	ds_read_b128 v[232:235], v201 offset:36864
	ds_read_b128 v[236:239], v201 offset:37888
	ds_read_b128 v[240:243], v201 offset:38912
	ds_read_b128 v[244:247], v201 offset:39936
	s_waitcnt vmcnt(8)
	s_waitcnt lgkmcnt(0)
	s_setprio 1
	s_barrier
	v_mfma_f32_16x16x32_bf16 v[126:129], v[130:133], v[216:219], v[126:129]
	v_mfma_f32_16x16x32_bf16 v[122:125], v[138:141], v[216:219], v[122:125]
	v_mfma_f32_16x16x32_bf16 v[110:113], v[130:133], v[224:227], v[110:113]
	v_mfma_f32_16x16x32_bf16 v[106:109], v[138:141], v[224:227], v[106:109]
	v_mfma_f32_16x16x32_bf16 v[94:97], v[130:133], v[232:235], v[94:97]
	v_mfma_f32_16x16x32_bf16 v[90:93], v[138:141], v[232:235], v[90:93]
	v_mfma_f32_16x16x32_bf16 v[78:81], v[130:133], v[240:243], v[78:81]
	v_mfma_f32_16x16x32_bf16 v[74:77], v[138:141], v[240:243], v[74:77]
	v_mfma_f32_16x16x32_bf16 v[126:129], v[134:137], v[220:223], v[126:129]
	v_mfma_f32_16x16x32_bf16 v[122:125], v[154:157], v[220:223], v[122:125]
	v_mfma_f32_16x16x32_bf16 v[110:113], v[134:137], v[228:231], v[110:113]
	v_mfma_f32_16x16x32_bf16 v[106:109], v[154:157], v[228:231], v[106:109]
	v_mfma_f32_16x16x32_bf16 v[94:97], v[134:137], v[236:239], v[94:97]
	v_mfma_f32_16x16x32_bf16 v[90:93], v[154:157], v[236:239], v[90:93]
	v_mfma_f32_16x16x32_bf16 v[78:81], v[134:137], v[244:247], v[78:81]
	v_mfma_f32_16x16x32_bf16 v[74:77], v[154:157], v[244:247], v[74:77]
	s_setprio 0
	s_setprio 1
	v_mfma_f32_16x16x32_bf16 v[118:121], v[158:161], v[216:219], v[118:121]
	v_mfma_f32_16x16x32_bf16 v[114:117], v[174:177], v[216:219], v[114:117]
	v_mfma_f32_16x16x32_bf16 v[102:105], v[158:161], v[224:227], v[102:105]
	v_mfma_f32_16x16x32_bf16 v[98:101], v[174:177], v[224:227], v[98:101]
	v_mfma_f32_16x16x32_bf16 v[86:89], v[158:161], v[232:235], v[86:89]
	v_mfma_f32_16x16x32_bf16 v[82:85], v[174:177], v[232:235], v[82:85]
	v_mfma_f32_16x16x32_bf16 v[70:73], v[158:161], v[240:243], v[70:73]
	v_mfma_f32_16x16x32_bf16 v[66:69], v[174:177], v[240:243], v[66:69]
	v_mfma_f32_16x16x32_bf16 v[118:121], v[170:173], v[220:223], v[118:121]
	v_mfma_f32_16x16x32_bf16 v[114:117], v[212:215], v[220:223], v[114:117]
	v_mfma_f32_16x16x32_bf16 v[102:105], v[170:173], v[228:231], v[102:105]
	v_mfma_f32_16x16x32_bf16 v[98:101], v[212:215], v[228:231], v[98:101]
	v_mfma_f32_16x16x32_bf16 v[86:89], v[170:173], v[236:239], v[86:89]
	v_mfma_f32_16x16x32_bf16 v[82:85], v[212:215], v[236:239], v[82:85]
	v_mfma_f32_16x16x32_bf16 v[70:73], v[170:173], v[244:247], v[70:73]
	v_mfma_f32_16x16x32_bf16 v[66:69], v[212:215], v[244:247], v[66:69]
	s_barrier
; #define PG8_STAGE(bufoff, gbase, voff) do { _Pragma("unroll") for (int _i = 0; _i < 2; ++_i) \
;         __builtin_amdgcn_global_load_lds((const unsigned*)((const char*)(gbase) + (voff)[_i]), (LAS unsigned*)(lds + (bufoff) + ldsw + _i * 8192), 16, 0, 0); } while (0)
; #define PG8_LDA(dst, b, h) do { _Pragma("unroll") for (int m = 0; m < 4; ++m) _Pragma("unroll") for (int k = 0; k < 2; ++k) dst[m][k] = *(const LAS bf16x8*)(lds + PG8_SA(b, h) + aoff + m * 2048 + k * 1024); } while (0)
; #define PG8_MMA(ai, bj, At, Bt) do { __builtin_amdgcn_s_setprio(1); _Pragma("unroll") for (int m = 0; m < 4; ++m) _Pragma("unroll") for (int n = 0; n < 2; ++n) _Pragma("unroll") for (int k = 0; k < 2; ++k) \
;         acc[ai][bj][m][n] = __builtin_amdgcn_mfma_f32_16x16x32_bf16(Bt[n][k], At[m][k], acc[ai][bj][m][n], 0, 0, 0); __builtin_amdgcn_s_setprio(0); } while (0)
; #define PG8_WAIT_V(n) asm volatile("s_waitcnt vmcnt(" #n ")" ::: "memory")
; #define PG8_WAIT_L(n) asm volatile("s_waitcnt lgkmcnt(" #n ")" ::: "memory")
; #define PG8_BAR __builtin_amdgcn_s_barrier()
; #define PG8_SCHED __builtin_amdgcn_sched_barrier(0)
; template <class Epi>
; __device__ __forceinline__ void gemm_phase(LAS unsigned char* lds, const int tid, const Gemm g, const StaticOrder& S, const Epi& E) {
;     ...
;             PG8_LDA(At, 1, 1); PG8_STAGE(PG8_SB(1, 0), b3, voffB); PG8_STAGE(PG8_SB(1, 1), b3 + hstepB, voffB); PG8_STAGE(PG8_SA(1, 0), a3, voffA);
;             PG8_WAIT_V(8); PG8_WAIT_L(0); PG8_BAR; PG8_MMA(1, 0, At, B0); PG8_MMA(1, 1, At, B1); PG8_BAR; PG8_SCHED;
;         }
;         if (wr == 0) PG8_BAR;
	s_setprio 0
	s_add_i32 s2, s2, s82
	v_lshl_add_u64 v[162:163], v[162:163], 0, s[36:37]
	s_mov_b32 m0, s2
	s_nop 0
	global_load_lds_dwordx4 v[162:163], off
	s_add_i32 m0, s2, 0x2000
	s_add_u32 s68, s72, 0xb0080
	v_lshl_add_u64 v[162:163], v[164:165], 0, s[36:37]
	s_addc_u32 s69, s73, 0
	s_add_i32 s2, s3, s82
	global_load_lds_dwordx4 v[162:163], off
	v_lshl_add_u64 v[162:163], s[68:69], 0, v[0:1]
	s_mov_b32 m0, s2
	s_nop 0
	global_load_lds_dwordx4 v[162:163], off
	v_lshl_add_u64 v[162:163], s[68:69], 0, v[142:143]
	s_add_i32 m0, s2, 0x2000
	s_nop 0
	global_load_lds_dwordx4 v[162:163], off
	v_lshl_add_u64 v[162:163], v[178:179], 0, s[36:37]
	s_mov_b32 m0, s4
	s_nop 0
	global_load_lds_dwordx4 v[162:163], off
	v_lshl_add_u64 v[162:163], v[206:207], 0, s[36:37]
	s_mov_b32 m0, s5
	s_nop 0
	global_load_lds_dwordx4 v[162:163], off
	ds_read_b128 v[216:219], v201 offset:49152
	ds_read_b128 v[220:223], v201 offset:50176
	ds_read_b128 v[224:227], v201 offset:51200
	ds_read_b128 v[228:231], v201 offset:52224
	ds_read_b128 v[232:235], v201 offset:53248
	ds_read_b128 v[236:239], v201 offset:54272
	ds_read_b128 v[240:243], v201 offset:55296
	ds_read_b128 v[244:247], v201 offset:56320
	s_waitcnt vmcnt(8)
	s_waitcnt lgkmcnt(0)
	s_setprio 1
	s_barrier
	v_mfma_f32_16x16x32_bf16 v[62:65], v[130:133], v[216:219], v[62:65]
	v_mfma_f32_16x16x32_bf16 v[58:61], v[138:141], v[216:219], v[58:61]
	v_mfma_f32_16x16x32_bf16 v[46:49], v[130:133], v[224:227], v[46:49]
	v_mfma_f32_16x16x32_bf16 v[42:45], v[138:141], v[224:227], v[42:45]
	v_mfma_f32_16x16x32_bf16 v[30:33], v[130:133], v[232:235], v[30:33]
	v_mfma_f32_16x16x32_bf16 v[26:29], v[138:141], v[232:235], v[26:29]
	v_mfma_f32_16x16x32_bf16 v[14:17], v[130:133], v[240:243], v[14:17]
	v_mfma_f32_16x16x32_bf16 v[10:13], v[138:141], v[240:243], v[10:13]
	v_mfma_f32_16x16x32_bf16 v[62:65], v[134:137], v[220:223], v[62:65]
	v_mfma_f32_16x16x32_bf16 v[58:61], v[154:157], v[220:223], v[58:61]
	v_mfma_f32_16x16x32_bf16 v[46:49], v[134:137], v[228:231], v[46:49]
	v_mfma_f32_16x16x32_bf16 v[42:45], v[154:157], v[228:231], v[42:45]
	v_mfma_f32_16x16x32_bf16 v[30:33], v[134:137], v[236:239], v[30:33]
	v_mfma_f32_16x16x32_bf16 v[26:29], v[154:157], v[236:239], v[26:29]
	v_mfma_f32_16x16x32_bf16 v[14:17], v[134:137], v[244:247], v[14:17]
	v_mfma_f32_16x16x32_bf16 v[10:13], v[154:157], v[244:247], v[10:13]
	s_setprio 0
	s_setprio 1
	v_mfma_f32_16x16x32_bf16 v[54:57], v[158:161], v[216:219], v[54:57]
	v_mfma_f32_16x16x32_bf16 v[50:53], v[174:177], v[216:219], v[50:53]
	v_mfma_f32_16x16x32_bf16 v[38:41], v[158:161], v[224:227], v[38:41]
	v_mfma_f32_16x16x32_bf16 v[34:37], v[174:177], v[224:227], v[34:37]
	v_mfma_f32_16x16x32_bf16 v[22:25], v[158:161], v[232:235], v[22:25]
	v_mfma_f32_16x16x32_bf16 v[18:21], v[174:177], v[232:235], v[18:21]
	v_mfma_f32_16x16x32_bf16 v[6:9], v[158:161], v[240:243], v[6:9]
	v_mfma_f32_16x16x32_bf16 v[2:5], v[174:177], v[240:243], v[2:5]
	v_mfma_f32_16x16x32_bf16 v[54:57], v[170:173], v[220:223], v[54:57]
	v_mfma_f32_16x16x32_bf16 v[50:53], v[212:215], v[220:223], v[50:53]
	v_mfma_f32_16x16x32_bf16 v[38:41], v[170:173], v[228:231], v[38:41]
	v_mfma_f32_16x16x32_bf16 v[34:37], v[212:215], v[228:231], v[34:37]
	v_mfma_f32_16x16x32_bf16 v[22:25], v[170:173], v[236:239], v[22:25]
	v_mfma_f32_16x16x32_bf16 v[18:21], v[212:215], v[236:239], v[18:21]
	v_mfma_f32_16x16x32_bf16 v[6:9], v[170:173], v[244:247], v[6:9]
	v_mfma_f32_16x16x32_bf16 v[2:5], v[212:215], v[244:247], v[2:5]
	s_barrier
	s_setprio 0
	s_add_i32 vcc_hi, vcc_hi, 2
	s_add_u32 s11, s11, 0x100
	s_addc_u32 vcc_lo, vcc_lo, 0
	s_cmp_gt_u32 vcc_hi, 41
	s_mov_b64 s[68:69], s[70:71]
	s_cbranch_scc0 .LBB0_2353
	s_and_b64 vcc, exec, s[26:27]
	s_cbranch_vccz .LBB0_2356
	s_barrier
